# v4: v3 + W_out round-2 tiles split into half tiles over all 256 workgroups (hand-written EpiOut, merged ssq stores)
# speedup vs baseline: 1.0413x; 1.0060x over previous
.LBB0_955:
	s_add_i32 s84, s84, 1
	s_mul_i32 s4, s84, s78
	s_mul_hi_u32 s5, s84, s79
	s_add_i32 s5, s5, s4
	s_mul_i32 s4, s84, s79
	s_add_u32 s8, s4, s2
	s_addc_u32 s9, s5, s80
	s_cmp_eq_u32 s84, 1
	s_cbranch_scc0 .Lwo_half_enum_skip
	s_cmp_eq_u32 s79, 0x100
	s_cbranch_scc0 .Lwo_half_enum_skip
	s_lshr_b32 s8, s2, 1
	s_add_u32 s8, s8, 0x100
	s_mov_b32 s9, 0
.Lwo_half_enum_skip:
	v_mov_b64_e32 v[4:5], 0x180
	v_cmp_gt_i64_e32 vcc, s[8:9], v[212:213]
	v_cmp_lt_i64_e64 s[4:5], s[8:9], v[4:5]
	s_cbranch_vccnz .LBB0_957
	s_mul_hi_i32 s7, s8, 0x2aaaaaab
	s_lshr_b32 s9, s7, 31
	s_ashr_i32 s7, s7, 6
	s_add_i32 s54, s7, s9
	s_mul_i32 s7, s54, 0xfffffe80
	s_add_i32 s7, s7, s8
	s_ashr_i32 s8, s7, 31
	s_lshr_b32 s8, s8, 29
	s_add_i32 s8, s7, s8
	s_ashr_i32 s9, s8, 3
	s_and_b32 s8, s8, -8
	s_sub_i32 s7, s7, s8
	s_cmp_lt_i32 s7, 0
	s_cselect_b32 s8, 49, 48
	s_mul_i32 s7, s8, s7
	s_add_i32 s7, s7, s9
	s_ashr_i32 s8, s7, 31
	s_lshr_b32 s8, s8, 27
	s_add_i32 s8, s7, s8
	s_ashr_i32 s9, s8, 5
	s_lshl_b32 s9, s9, 3
	s_sub_i32 s10, 0x60, s9
	s_min_i32 s10, s10, 8
	s_abs_i32 s11, s10
	v_cvt_f32_u32_e32 v4, s11
	s_sub_i32 s33, 0, s11
	s_andn2_b32 s8, s8, 31
	s_sub_i32 s7, s7, s8
	v_rcp_iflag_f32_e32 v4, v4
	s_abs_i32 s8, s7
	s_xor_b32 s24, s7, s10
	s_ashr_i32 s24, s24, 31
	v_mul_f32_e32 v4, 0x4f7ffffe, v4
	v_cvt_u32_f32_e32 v4, v4
	s_nop 0
	v_readfirstlane_b32 s46, v4
	s_mul_i32 s33, s33, s46
	s_mul_hi_u32 s33, s46, s33
	s_add_i32 s46, s46, s33
	s_mul_hi_u32 s33, s8, s46
	s_mul_i32 s46, s33, s11
	s_sub_i32 s8, s8, s46
	s_add_i32 s47, s33, 1
	s_sub_i32 s46, s8, s11
	s_cmp_ge_u32 s8, s11
	s_cselect_b32 s33, s47, s33
	s_cselect_b32 s8, s46, s8
	s_add_i32 s46, s33, 1
	s_cmp_ge_u32 s8, s11
	s_cselect_b32 s8, s46, s33
	s_xor_b32 s8, s8, s24
	s_sub_i32 s62, s8, s24
	s_mul_i32 s8, s62, s10
	s_sub_i32 s7, s7, s8
	s_add_i32 s64, s7, s9
.LBB0_957:
	s_ashr_i32 s65, s64, 31
	s_lshl_b64 s[8:9], s[64:65], 19
	s_cmp_eq_u32 s84, 1
	s_cbranch_scc0 .Lwo_half_a_skip
	s_cmp_eq_u32 s79, 0x100
	s_cbranch_scc0 .Lwo_half_a_skip
	s_and_b32 s10, s2, 1
	s_lshl_b32 s10, s10, 18
	s_or_b32 s8, s8, s10
.Lwo_half_a_skip:
	s_ashr_i32 s55, s54, 31
	s_ashr_i32 s63, s62, 31
	v_lshl_add_u64 v[4:5], v[186:187], 0, s[8:9]
	s_lshl_b64 s[8:9], s[54:55], 11
	s_lshl_b64 s[10:11], s[62:63], 19
	v_lshl_add_u64 v[214:215], v[4:5], 0, s[8:9]
	v_lshl_add_u64 v[4:5], v[188:189], 0, s[10:11]
	v_lshl_add_u64 v[216:217], v[4:5], 0, s[8:9]
	v_cndmask_b32_e64 v42, v0, v216, s[4:5]
	v_lshl_add_u64 v[46:47], v[0:1], 0, s[34:35]
	v_mov_b32_e32 v0, 0
	v_cndmask_b32_e64 v41, v3, v215, s[4:5]
	v_cndmask_b32_e64 v40, v2, v214, s[4:5]
	v_cndmask_b32_e64 v43, v1, v217, s[4:5]
	v_lshl_add_u64 v[44:45], v[2:3], 0, s[28:29]
	s_mov_b32 s7, -2
	v_mov_b32_e32 v1, v0
	v_mov_b32_e32 v2, v0
	v_mov_b32_e32 v3, v0
	v_mov_b32_e32 v4, v0
	v_mov_b32_e32 v5, v0
	v_mov_b32_e32 v6, v0
	v_mov_b32_e32 v7, v0
	v_mov_b32_e32 v16, v0
	v_mov_b32_e32 v17, v0
	v_mov_b32_e32 v18, v0
	v_mov_b32_e32 v19, v0
	v_mov_b32_e32 v20, v0
	v_mov_b32_e32 v21, v0
	v_mov_b32_e32 v22, v0
	v_mov_b32_e32 v23, v0
	v_mov_b32_e32 v32, v0
	v_mov_b32_e32 v33, v0
	v_mov_b32_e32 v34, v0
	v_mov_b32_e32 v35, v0
	v_mov_b32_e32 v36, v0
	v_mov_b32_e32 v37, v0
	v_mov_b32_e32 v38, v0
	v_mov_b32_e32 v39, v0
	v_mov_b32_e32 v64, v0
	v_mov_b32_e32 v65, v0
	v_mov_b32_e32 v66, v0
	v_mov_b32_e32 v67, v0
	v_mov_b32_e32 v68, v0
	v_mov_b32_e32 v69, v0
	v_mov_b32_e32 v70, v0
	v_mov_b32_e32 v71, v0
	v_mov_b32_e32 v8, v0
	v_mov_b32_e32 v9, v0
	v_mov_b32_e32 v10, v0
	v_mov_b32_e32 v11, v0
	v_mov_b32_e32 v12, v0
	v_mov_b32_e32 v13, v0
	v_mov_b32_e32 v14, v0
	v_mov_b32_e32 v15, v0
	v_mov_b32_e32 v24, v0
	v_mov_b32_e32 v25, v0
	v_mov_b32_e32 v26, v0
	v_mov_b32_e32 v27, v0
	v_mov_b32_e32 v28, v0
	v_mov_b32_e32 v29, v0
	v_mov_b32_e32 v30, v0
	v_mov_b32_e32 v31, v0
	v_mov_b32_e32 v48, v0
	v_mov_b32_e32 v49, v0
	v_mov_b32_e32 v50, v0
	v_mov_b32_e32 v51, v0
	v_mov_b32_e32 v52, v0
	v_mov_b32_e32 v53, v0
	v_mov_b32_e32 v54, v0
	v_mov_b32_e32 v55, v0
	v_mov_b32_e32 v72, v0
	v_mov_b32_e32 v73, v0
	v_mov_b32_e32 v74, v0
	v_mov_b32_e32 v75, v0
	v_mov_b32_e32 v76, v0
	v_mov_b32_e32 v77, v0
	v_mov_b32_e32 v78, v0
	v_mov_b32_e32 v79, v0
	v_mov_b32_e32 v80, v0
	v_mov_b32_e32 v81, v0
	v_mov_b32_e32 v82, v0
	v_mov_b32_e32 v83, v0
	v_mov_b32_e32 v84, v0
	v_mov_b32_e32 v85, v0
	v_mov_b32_e32 v86, v0
	v_mov_b32_e32 v87, v0
	v_mov_b32_e32 v96, v0
	v_mov_b32_e32 v97, v0
	v_mov_b32_e32 v98, v0
	v_mov_b32_e32 v99, v0
	v_mov_b32_e32 v100, v0
	v_mov_b32_e32 v101, v0
	v_mov_b32_e32 v102, v0
	v_mov_b32_e32 v103, v0
	v_mov_b32_e32 v112, v0
	v_mov_b32_e32 v113, v0
	v_mov_b32_e32 v114, v0
	v_mov_b32_e32 v115, v0
	v_mov_b32_e32 v116, v0
	v_mov_b32_e32 v117, v0
	v_mov_b32_e32 v118, v0
	v_mov_b32_e32 v119, v0
	v_mov_b32_e32 v128, v0
	v_mov_b32_e32 v129, v0
	v_mov_b32_e32 v130, v0
	v_mov_b32_e32 v131, v0
	v_mov_b32_e32 v132, v0
	v_mov_b32_e32 v133, v0
	v_mov_b32_e32 v134, v0
	v_mov_b32_e32 v135, v0
	v_mov_b32_e32 v88, v0
	v_mov_b32_e32 v89, v0
	v_mov_b32_e32 v90, v0
	v_mov_b32_e32 v91, v0
	v_mov_b32_e32 v92, v0
	v_mov_b32_e32 v93, v0
	v_mov_b32_e32 v94, v0
	v_mov_b32_e32 v95, v0
	v_mov_b32_e32 v104, v0
	v_mov_b32_e32 v105, v0
	v_mov_b32_e32 v106, v0
	v_mov_b32_e32 v107, v0
	v_mov_b32_e32 v108, v0
	v_mov_b32_e32 v109, v0
	v_mov_b32_e32 v110, v0
	v_mov_b32_e32 v111, v0
	v_mov_b32_e32 v120, v0
	v_mov_b32_e32 v121, v0
	v_mov_b32_e32 v122, v0
	v_mov_b32_e32 v123, v0
	v_mov_b32_e32 v124, v0
	v_mov_b32_e32 v125, v0
	v_mov_b32_e32 v126, v0
	v_mov_b32_e32 v127, v0
	v_mov_b32_e32 v136, v0
	v_mov_b32_e32 v137, v0
	v_mov_b32_e32 v138, v0
	v_mov_b32_e32 v139, v0
	v_mov_b32_e32 v140, v0
	v_mov_b32_e32 v141, v0
	v_mov_b32_e32 v142, v0
	v_mov_b32_e32 v143, v0
.LBB0_958:
	v_add_u32_e32 v164, s82, v237
	ds_read_b128 v[56:59], v239
	ds_read_b128 v[60:63], v239 offset:1024
	ds_read_b128 v[144:147], v239 offset:2048
	ds_read_b128 v[148:151], v239 offset:3072
	ds_read_b128 v[152:155], v164
	ds_read_b128 v[156:159], v164 offset:1024
	ds_read_b128 v[160:163], v164 offset:2048
	ds_read_b128 v[164:167], v164 offset:3072
	s_cmp_eq_u32 s7, 12
	v_lshl_add_u64 v[168:169], v[44:45], 0, s[36:37]
	s_cselect_b64 vcc, -1, 0
	v_cndmask_b32_e32 v241, v169, v41, vcc
	v_cndmask_b32_e32 v240, v168, v40, vcc
	v_cndmask_b32_e32 v243, v47, v43, vcc
	v_cndmask_b32_e32 v242, v46, v42, vcc
	v_lshl_add_u64 v[244:245], v[44:45], 0, v[208:209]
	s_add_i32 m0, s69, 0xc000
	ds_read_b128 v[168:171], v238
	ds_read_b128 v[172:175], v238 offset:1024
	ds_read_b128 v[176:179], v238 offset:2048
	ds_read_b128 v[180:183], v238 offset:3072
	ds_read_b128 v[218:221], v238 offset:4096
	ds_read_b128 v[222:225], v238 offset:5120
	ds_read_b128 v[226:229], v238 offset:6144
	ds_read_b128 v[230:233], v238 offset:7168
	global_load_lds_dwordx4 v[244:245], off
	v_lshl_add_u64 v[244:245], v[44:45], 0, v[210:211]
	s_add_i32 m0, s69, 0xe000
	s_nop 0
	global_load_lds_dwordx4 v[244:245], off
	s_waitcnt vmcnt(8)
	s_waitcnt lgkmcnt(0)
	s_barrier
	s_setprio 1
	s_waitcnt lgkmcnt(0)
	v_mfma_f32_16x16x32_bf16 v[140:143], v[56:59], v[168:171], v[140:143]
	v_mfma_f32_16x16x32_bf16 v[136:139], v[144:147], v[168:171], v[136:139]
	v_mfma_f32_16x16x32_bf16 v[124:127], v[56:59], v[176:179], v[124:127]
	v_mfma_f32_16x16x32_bf16 v[120:123], v[144:147], v[176:179], v[120:123]
	v_mfma_f32_16x16x32_bf16 v[108:111], v[56:59], v[218:221], v[108:111]
	v_mfma_f32_16x16x32_bf16 v[104:107], v[144:147], v[218:221], v[104:107]
	v_mfma_f32_16x16x32_bf16 v[92:95], v[56:59], v[226:229], v[92:95]
	v_mfma_f32_16x16x32_bf16 v[88:91], v[144:147], v[226:229], v[88:91]
	v_mfma_f32_16x16x32_bf16 v[140:143], v[60:63], v[172:175], v[140:143]
	v_mfma_f32_16x16x32_bf16 v[136:139], v[148:151], v[172:175], v[136:139]
	v_mfma_f32_16x16x32_bf16 v[124:127], v[60:63], v[180:183], v[124:127]
	v_mfma_f32_16x16x32_bf16 v[120:123], v[148:151], v[180:183], v[120:123]
	v_mfma_f32_16x16x32_bf16 v[108:111], v[60:63], v[222:225], v[108:111]
	v_mfma_f32_16x16x32_bf16 v[104:107], v[148:151], v[222:225], v[104:107]
	v_mfma_f32_16x16x32_bf16 v[92:95], v[60:63], v[230:233], v[92:95]
	v_mfma_f32_16x16x32_bf16 v[88:91], v[148:151], v[230:233], v[88:91]
	s_setprio 0
	s_setprio 1
	v_mfma_f32_16x16x32_bf16 v[132:135], v[152:155], v[168:171], v[132:135]
	v_mfma_f32_16x16x32_bf16 v[128:131], v[160:163], v[168:171], v[128:131]
	v_mfma_f32_16x16x32_bf16 v[116:119], v[152:155], v[176:179], v[116:119]
	v_mfma_f32_16x16x32_bf16 v[112:115], v[160:163], v[176:179], v[112:115]
	v_mfma_f32_16x16x32_bf16 v[100:103], v[152:155], v[218:221], v[100:103]
	v_mfma_f32_16x16x32_bf16 v[96:99], v[160:163], v[218:221], v[96:99]
	v_mfma_f32_16x16x32_bf16 v[84:87], v[152:155], v[226:229], v[84:87]
	v_mfma_f32_16x16x32_bf16 v[80:83], v[160:163], v[226:229], v[80:83]
	v_mfma_f32_16x16x32_bf16 v[132:135], v[156:159], v[172:175], v[132:135]
	v_mfma_f32_16x16x32_bf16 v[128:131], v[164:167], v[172:175], v[128:131]
	v_mfma_f32_16x16x32_bf16 v[116:119], v[156:159], v[180:183], v[116:119]
	v_mfma_f32_16x16x32_bf16 v[112:115], v[164:167], v[180:183], v[112:115]
	v_mfma_f32_16x16x32_bf16 v[100:103], v[156:159], v[222:225], v[100:103]
	v_mfma_f32_16x16x32_bf16 v[96:99], v[164:167], v[222:225], v[96:99]
	v_mfma_f32_16x16x32_bf16 v[84:87], v[156:159], v[230:233], v[84:87]
	v_mfma_f32_16x16x32_bf16 v[80:83], v[164:167], v[230:233], v[80:83]
	s_setprio 0
	s_barrier
	s_add_i32 s8, s81, s68
	v_lshl_add_u64 v[244:245], v[242:243], 0, v[192:193]
	s_mov_b32 m0, s8
	ds_read_b128 v[168:171], v238 offset:16384
	ds_read_b128 v[172:175], v238 offset:17408
	ds_read_b128 v[176:179], v238 offset:18432
	ds_read_b128 v[180:183], v238 offset:19456
	ds_read_b128 v[218:221], v238 offset:20480
	ds_read_b128 v[222:225], v238 offset:21504
	ds_read_b128 v[226:229], v238 offset:22528
	ds_read_b128 v[230:233], v238 offset:23552
	global_load_lds_dwordx4 v[244:245], off
	v_lshl_add_u64 v[246:247], v[242:243], 0, v[196:197]
	s_add_i32 m0, s8, 0x2000
	v_lshl_add_u64 v[248:249], v[242:243], 0, s[16:17]
	s_add_i32 s8, s82, s68
	global_load_lds_dwordx4 v[246:247], off
	v_lshl_add_u64 v[250:251], v[248:249], 0, v[192:193]
	s_mov_b32 m0, s8
	v_lshl_add_u64 v[248:249], v[248:249], 0, v[196:197]
	global_load_lds_dwordx4 v[250:251], off
	s_add_i32 m0, s8, 0x2000
	v_lshl_add_u64 v[250:251], v[240:241], 0, v[194:195]
	global_load_lds_dwordx4 v[248:249], off
	v_lshl_add_u64 v[248:249], v[240:241], 0, v[190:191]
	s_mov_b32 m0, s69
	s_nop 0
	global_load_lds_dwordx4 v[248:249], off
	s_mov_b32 m0, s70
	s_nop 0
	global_load_lds_dwordx4 v[250:251], off
	s_waitcnt vmcnt(8)
	s_waitcnt lgkmcnt(0)
	s_barrier
	s_setprio 1
	s_waitcnt lgkmcnt(0)
	s_cmp_eq_u32 s84, 2
	s_cbranch_scc1 .Lwo_half_skip_a
	v_mfma_f32_16x16x32_bf16 v[76:79], v[56:59], v[168:171], v[76:79]
	v_mfma_f32_16x16x32_bf16 v[72:75], v[144:147], v[168:171], v[72:75]
	v_mfma_f32_16x16x32_bf16 v[52:55], v[56:59], v[176:179], v[52:55]
	v_mfma_f32_16x16x32_bf16 v[48:51], v[144:147], v[176:179], v[48:51]
	v_mfma_f32_16x16x32_bf16 v[28:31], v[56:59], v[218:221], v[28:31]
	v_mfma_f32_16x16x32_bf16 v[24:27], v[144:147], v[218:221], v[24:27]
	v_mfma_f32_16x16x32_bf16 v[12:15], v[56:59], v[226:229], v[12:15]
	v_mfma_f32_16x16x32_bf16 v[8:11], v[144:147], v[226:229], v[8:11]
	v_mfma_f32_16x16x32_bf16 v[76:79], v[60:63], v[172:175], v[76:79]
	v_mfma_f32_16x16x32_bf16 v[72:75], v[148:151], v[172:175], v[72:75]
	v_mfma_f32_16x16x32_bf16 v[52:55], v[60:63], v[180:183], v[52:55]
	v_mfma_f32_16x16x32_bf16 v[48:51], v[148:151], v[180:183], v[48:51]
	v_mfma_f32_16x16x32_bf16 v[28:31], v[60:63], v[222:225], v[28:31]
	v_mfma_f32_16x16x32_bf16 v[24:27], v[148:151], v[222:225], v[24:27]
	v_mfma_f32_16x16x32_bf16 v[12:15], v[60:63], v[230:233], v[12:15]
	v_mfma_f32_16x16x32_bf16 v[8:11], v[148:151], v[230:233], v[8:11]
	s_setprio 0
	s_setprio 1
	v_mfma_f32_16x16x32_bf16 v[36:39], v[152:155], v[176:179], v[36:39]
	v_mfma_f32_16x16x32_bf16 v[32:35], v[160:163], v[176:179], v[32:35]
	v_mfma_f32_16x16x32_bf16 v[20:23], v[152:155], v[218:221], v[20:23]
	v_mfma_f32_16x16x32_bf16 v[16:19], v[160:163], v[218:221], v[16:19]
	v_mfma_f32_16x16x32_bf16 v[4:7], v[152:155], v[226:229], v[4:7]
	v_mfma_f32_16x16x32_bf16 v[0:3], v[160:163], v[226:229], v[0:3]
	v_mfma_f32_16x16x32_bf16 v[56:59], v[152:155], v[168:171], v[68:71]
	v_mfma_f32_16x16x32_bf16 v[60:63], v[160:163], v[168:171], v[64:67]
	v_mfma_f32_16x16x32_bf16 v[36:39], v[156:159], v[180:183], v[36:39]
	v_mfma_f32_16x16x32_bf16 v[32:35], v[164:167], v[180:183], v[32:35]
	v_mfma_f32_16x16x32_bf16 v[20:23], v[156:159], v[222:225], v[20:23]
	v_mfma_f32_16x16x32_bf16 v[16:19], v[164:167], v[222:225], v[16:19]
	v_mfma_f32_16x16x32_bf16 v[4:7], v[156:159], v[230:233], v[4:7]
	v_mfma_f32_16x16x32_bf16 v[0:3], v[164:167], v[230:233], v[0:3]
	v_mfma_f32_16x16x32_bf16 v[56:59], v[156:159], v[172:175], v[56:59]
	v_mfma_f32_16x16x32_bf16 v[60:63], v[164:167], v[172:175], v[60:63]
.Lwo_half_skip_a:
	s_setprio 0
	s_barrier
	s_add_i32 s8, 0, 0x18000
	s_add_i32 s9, 0, 0x1c000
	v_add_u32_e32 v148, s8, v237
	v_add_u32_e32 v164, s9, v237
	ds_read_b128 v[64:67], v148
	ds_read_b128 v[68:71], v148 offset:1024
	ds_read_b128 v[144:147], v148 offset:2048
	ds_read_b128 v[148:151], v148 offset:3072
	ds_read_b128 v[152:155], v164
	ds_read_b128 v[156:159], v164 offset:1024
	ds_read_b128 v[160:163], v164 offset:2048
	ds_read_b128 v[164:167], v164 offset:3072
	v_lshl_add_u64 v[240:241], v[240:241], 0, s[16:17]
	s_mov_b32 m0, s71
	v_lshl_add_u64 v[252:253], v[240:241], 0, v[190:191]
	ds_read_b128 v[168:171], v238 offset:32768
	ds_read_b128 v[172:175], v238 offset:33792
	ds_read_b128 v[176:179], v238 offset:34816
	ds_read_b128 v[180:183], v238 offset:35840
	ds_read_b128 v[218:221], v238 offset:36864
	ds_read_b128 v[222:225], v238 offset:37888
	ds_read_b128 v[226:229], v238 offset:38912
	ds_read_b128 v[230:233], v238 offset:39936
	global_load_lds_dwordx4 v[252:253], off
	v_lshl_add_u64 v[240:241], v[240:241], 0, v[194:195]
	s_mov_b32 m0, s72
	s_nop 0
	global_load_lds_dwordx4 v[240:241], off
	s_waitcnt vmcnt(8)
	s_waitcnt lgkmcnt(0)
	s_barrier
	s_setprio 1
	s_waitcnt lgkmcnt(0)
	v_mfma_f32_16x16x32_bf16 v[140:143], v[64:67], v[168:171], v[140:143]
	v_mfma_f32_16x16x32_bf16 v[136:139], v[144:147], v[168:171], v[136:139]
	v_mfma_f32_16x16x32_bf16 v[124:127], v[64:67], v[176:179], v[124:127]
	v_mfma_f32_16x16x32_bf16 v[120:123], v[144:147], v[176:179], v[120:123]
	v_mfma_f32_16x16x32_bf16 v[108:111], v[64:67], v[218:221], v[108:111]
	v_mfma_f32_16x16x32_bf16 v[104:107], v[144:147], v[218:221], v[104:107]
	v_mfma_f32_16x16x32_bf16 v[92:95], v[64:67], v[226:229], v[92:95]
	v_mfma_f32_16x16x32_bf16 v[88:91], v[144:147], v[226:229], v[88:91]
	v_mfma_f32_16x16x32_bf16 v[140:143], v[68:71], v[172:175], v[140:143]
	v_mfma_f32_16x16x32_bf16 v[136:139], v[148:151], v[172:175], v[136:139]
	v_mfma_f32_16x16x32_bf16 v[124:127], v[68:71], v[180:183], v[124:127]
	v_mfma_f32_16x16x32_bf16 v[120:123], v[148:151], v[180:183], v[120:123]
	v_mfma_f32_16x16x32_bf16 v[108:111], v[68:71], v[222:225], v[108:111]
	v_mfma_f32_16x16x32_bf16 v[104:107], v[148:151], v[222:225], v[104:107]
	v_mfma_f32_16x16x32_bf16 v[92:95], v[68:71], v[230:233], v[92:95]
	v_mfma_f32_16x16x32_bf16 v[88:91], v[148:151], v[230:233], v[88:91]
	s_setprio 0
	s_setprio 1
	v_mfma_f32_16x16x32_bf16 v[132:135], v[152:155], v[168:171], v[132:135]
	v_mfma_f32_16x16x32_bf16 v[128:131], v[160:163], v[168:171], v[128:131]
	v_mfma_f32_16x16x32_bf16 v[116:119], v[152:155], v[176:179], v[116:119]
	v_mfma_f32_16x16x32_bf16 v[112:115], v[160:163], v[176:179], v[112:115]
	v_mfma_f32_16x16x32_bf16 v[100:103], v[152:155], v[218:221], v[100:103]
	v_mfma_f32_16x16x32_bf16 v[96:99], v[160:163], v[218:221], v[96:99]
	v_mfma_f32_16x16x32_bf16 v[84:87], v[152:155], v[226:229], v[84:87]
	v_mfma_f32_16x16x32_bf16 v[80:83], v[160:163], v[226:229], v[80:83]
	v_mfma_f32_16x16x32_bf16 v[132:135], v[156:159], v[172:175], v[132:135]
	v_mfma_f32_16x16x32_bf16 v[128:131], v[164:167], v[172:175], v[128:131]
	v_mfma_f32_16x16x32_bf16 v[116:119], v[156:159], v[180:183], v[116:119]
	v_mfma_f32_16x16x32_bf16 v[112:115], v[164:167], v[180:183], v[112:115]
	v_mfma_f32_16x16x32_bf16 v[100:103], v[156:159], v[222:225], v[100:103]
	v_mfma_f32_16x16x32_bf16 v[96:99], v[164:167], v[222:225], v[96:99]
	v_mfma_f32_16x16x32_bf16 v[84:87], v[156:159], v[230:233], v[84:87]
	v_mfma_f32_16x16x32_bf16 v[80:83], v[164:167], v[230:233], v[80:83]
	s_setprio 0
	s_barrier
	s_add_i32 s8, s8, s68
	v_lshl_add_u64 v[240:241], v[244:245], 0, s[26:27]
	s_mov_b32 m0, s8
	ds_read_b128 v[168:171], v238 offset:49152
	ds_read_b128 v[172:175], v238 offset:50176
	ds_read_b128 v[176:179], v238 offset:51200
	ds_read_b128 v[180:183], v238 offset:52224
	ds_read_b128 v[218:221], v238 offset:53248
	ds_read_b128 v[222:225], v238 offset:54272
	ds_read_b128 v[226:229], v238 offset:55296
	ds_read_b128 v[230:233], v238 offset:56320
	global_load_lds_dwordx4 v[240:241], off
	v_lshl_add_u64 v[240:241], v[246:247], 0, s[26:27]
	s_add_i32 m0, s8, 0x2000
	s_add_i32 s8, s9, s68
	global_load_lds_dwordx4 v[240:241], off
	v_lshl_add_u64 v[240:241], v[242:243], 0, s[28:29]
	v_lshl_add_u64 v[242:243], v[240:241], 0, v[192:193]
	s_mov_b32 m0, s8
	v_lshl_add_u64 v[240:241], v[240:241], 0, v[196:197]
	global_load_lds_dwordx4 v[242:243], off
	s_add_i32 m0, s8, 0x2000
	s_nop 0
	global_load_lds_dwordx4 v[240:241], off
	v_lshl_add_u64 v[240:241], v[248:249], 0, s[26:27]
	s_mov_b32 m0, s73
	s_nop 0
	global_load_lds_dwordx4 v[240:241], off
	v_lshl_add_u64 v[240:241], v[250:251], 0, s[26:27]
	s_mov_b32 m0, s74
	s_nop 0
	global_load_lds_dwordx4 v[240:241], off
	s_waitcnt vmcnt(8)
	s_waitcnt lgkmcnt(0)
	s_barrier
	s_setprio 1
	s_waitcnt lgkmcnt(0)
	s_cmp_eq_u32 s84, 2
	s_cbranch_scc1 .Lwo_half_skip_b
	v_mfma_f32_16x16x32_bf16 v[76:79], v[64:67], v[168:171], v[76:79]
	v_mfma_f32_16x16x32_bf16 v[72:75], v[144:147], v[168:171], v[72:75]
	v_mfma_f32_16x16x32_bf16 v[52:55], v[64:67], v[176:179], v[52:55]
	v_mfma_f32_16x16x32_bf16 v[48:51], v[144:147], v[176:179], v[48:51]
	v_mfma_f32_16x16x32_bf16 v[28:31], v[64:67], v[218:221], v[28:31]
	v_mfma_f32_16x16x32_bf16 v[24:27], v[144:147], v[218:221], v[24:27]
	v_mfma_f32_16x16x32_bf16 v[12:15], v[64:67], v[226:229], v[12:15]
	v_mfma_f32_16x16x32_bf16 v[8:11], v[144:147], v[226:229], v[8:11]
	v_mfma_f32_16x16x32_bf16 v[76:79], v[68:71], v[172:175], v[76:79]
	v_mfma_f32_16x16x32_bf16 v[72:75], v[148:151], v[172:175], v[72:75]
	v_mfma_f32_16x16x32_bf16 v[52:55], v[68:71], v[180:183], v[52:55]
	v_mfma_f32_16x16x32_bf16 v[48:51], v[148:151], v[180:183], v[48:51]
	v_mfma_f32_16x16x32_bf16 v[28:31], v[68:71], v[222:225], v[28:31]
	v_mfma_f32_16x16x32_bf16 v[24:27], v[148:151], v[222:225], v[24:27]
	v_mfma_f32_16x16x32_bf16 v[12:15], v[68:71], v[230:233], v[12:15]
	v_mfma_f32_16x16x32_bf16 v[8:11], v[148:151], v[230:233], v[8:11]
	s_setprio 0
	s_setprio 1
	v_mfma_f32_16x16x32_bf16 v[56:59], v[152:155], v[168:171], v[56:59]
	v_mfma_f32_16x16x32_bf16 v[68:71], v[156:159], v[172:175], v[56:59]
	v_mfma_f32_16x16x32_bf16 v[56:59], v[160:163], v[168:171], v[60:63]
	v_mfma_f32_16x16x32_bf16 v[36:39], v[152:155], v[176:179], v[36:39]
	v_mfma_f32_16x16x32_bf16 v[32:35], v[160:163], v[176:179], v[32:35]
	v_mfma_f32_16x16x32_bf16 v[20:23], v[152:155], v[218:221], v[20:23]
	v_mfma_f32_16x16x32_bf16 v[16:19], v[160:163], v[218:221], v[16:19]
	v_mfma_f32_16x16x32_bf16 v[4:7], v[152:155], v[226:229], v[4:7]
	v_mfma_f32_16x16x32_bf16 v[0:3], v[160:163], v[226:229], v[0:3]
	v_mfma_f32_16x16x32_bf16 v[64:67], v[164:167], v[172:175], v[56:59]
	v_mfma_f32_16x16x32_bf16 v[36:39], v[156:159], v[180:183], v[36:39]
	v_mfma_f32_16x16x32_bf16 v[32:35], v[164:167], v[180:183], v[32:35]
	v_mfma_f32_16x16x32_bf16 v[20:23], v[156:159], v[222:225], v[20:23]
	v_mfma_f32_16x16x32_bf16 v[16:19], v[164:167], v[222:225], v[16:19]
	v_mfma_f32_16x16x32_bf16 v[4:7], v[156:159], v[230:233], v[4:7]
	v_mfma_f32_16x16x32_bf16 v[0:3], v[164:167], v[230:233], v[0:3]
.Lwo_half_skip_b:
	s_setprio 0
	s_barrier
	s_add_i32 s7, s7, 2
	v_lshl_add_u64 v[44:45], v[44:45], 0, s[34:35]
	s_cmp_gt_u32 s7, 13
	v_lshl_add_u64 v[46:47], v[46:47], 0, s[34:35]
	s_cbranch_scc0 .LBB0_958
	s_and_b64 vcc, exec, s[30:31]
	s_cbranch_vccz .LBB0_961
	s_barrier
.LBB0_961:
	v_lshlrev_b32_e32 v218, 5, v236
	s_lshl_b32 s7, s66, 10
	s_lshl_b32 s8, s77, 2
	s_add_i32 s7, s7, s8
	v_lshlrev_b32_e32 v219, 12, v235
	v_add_u32_e32 v218, s7, v218
	v_lshlrev_b32_e32 v222, 6, v235
	v_lshl_add_u32 v222, v236, 10, v222
	v_add_u32_e32 v219, v219, v218
	s_lshl_b32 s24, s6, 8
	s_add_i32 s24, s24, s76
	s_cmp_eq_u32 s84, 2
	s_cbranch_scc0 .Lepo_full_rows
	s_and_b32 s8, s2, 1
	s_lshl_b32 s8, s8, 7
	s_add_i32 s24, s24, s8
.Lepo_full_rows:
	s_lshl_b32 s10, s24, 12
	s_add_u32 s10, s20, s10
	s_addc_u32 s11, s21, 0
	s_lshl_b32 s98, s24, 11
	s_add_i32 s98, s98, 0x2800000
	s_add_u32 s98, s58, s98
	s_addc_u32 s99, s59, 0
	v_lshrrev_b32_e32 v220, 1, v219
	s_cmp_eq_u32 s84, 2
	s_cbranch_scc1 .Lepo_half
	s_cmp_lt_i32 s6, 32
	s_cbranch_scc1 .Lepo_ctx
	s_cmp_lt_i32 s66, 2
	s_cbranch_scc1 .Lepo_per
.Lepo_pec:
	s_lshl_b32 s8, s66, 4
	s_lshl_b32 s9, s75, 2
	s_add_i32 s8, s8, s9
	s_lshl_b32 s9, s24, 6
	s_add_i32 s8, s8, s9
	s_add_i32 s8, s8, 0xea9a000
	s_add_u32 s66, s58, s8
	s_addc_u32 s67, s59, 0
	s_sub_i32 s8, s6, 32
	s_ashr_i32 s8, s8, 3
	s_add_i32 s8, s8, 1
	s_mul_i32 s8, s8, 0x6000
	s_add_i32 s8, s8, 0xe802000
	s_add_u32 s8, s58, s8
	s_addc_u32 s9, s59, 0
	global_load_dwordx4 v[60:63], v218, s[8:9] offset:0
	global_load_dwordx4 v[56:59], v218, s[8:9] offset:16
	global_load_dwordx4 v[44:47], v218, s[8:9] offset:512
	global_load_dwordx4 v[40:43], v218, s[8:9] offset:528
	s_add_u32 s8, s8, 0x2000
	s_addc_u32 s9, s9, 0
	global_load_dwordx4 v[144:147], v218, s[8:9] offset:0
	global_load_dwordx4 v[148:151], v218, s[8:9] offset:16
	global_load_dwordx4 v[152:155], v218, s[8:9] offset:512
	global_load_dwordx4 v[156:159], v218, s[8:9] offset:528
	global_load_dwordx4 v[160:163], v218, s[18:19] offset:0
	global_load_dwordx4 v[164:167], v218, s[18:19] offset:16
	global_load_dwordx4 v[168:171], v218, s[18:19] offset:512
	global_load_dwordx4 v[172:175], v218, s[18:19] offset:528
	s_sub_i32 s8, s24, 0x2000
	s_lshl_b32 s8, s8, 12
	s_add_u32 s8, s14, s8
	s_addc_u32 s9, s15, 0
	s_add_u32 s100, s58, 0xe8fa000
	s_addc_u32 s101, s59, 0
	v_lshlrev_b32_e32 v221, 11, v235
	v_add_u32_e32 v221, v221, v218
	v_add_u32_e32 v221, 0xfffff800, v221
	global_load_dwordx4 v[176:179], v219, s[8:9] offset:0
	global_load_dwordx4 v[180:183], v219, s[8:9] offset:16
	global_load_dwordx4 v[224:227], v221, s[100:101] offset:0
	global_load_dwordx4 v[228:231], v221, s[100:101] offset:16
	s_waitcnt vmcnt(4)
	v_pk_add_f32 v[144:145], v[144:145], 1.0 op_sel_hi:[1,0]
	v_pk_add_f32 v[146:147], v[146:147], 1.0 op_sel_hi:[1,0]
	v_pk_add_f32 v[148:149], v[148:149], 1.0 op_sel_hi:[1,0]
	v_pk_add_f32 v[150:151], v[150:151], 1.0 op_sel_hi:[1,0]
	v_pk_add_f32 v[152:153], v[152:153], 1.0 op_sel_hi:[1,0]
	v_pk_add_f32 v[154:155], v[154:155], 1.0 op_sel_hi:[1,0]
	v_pk_add_f32 v[156:157], v[156:157], 1.0 op_sel_hi:[1,0]
	v_pk_add_f32 v[158:159], v[158:159], 1.0 op_sel_hi:[1,0]
	v_pk_mul_f32 v[144:145], v[160:161], v[144:145]
	v_pk_mul_f32 v[146:147], v[162:163], v[146:147]
	v_pk_mul_f32 v[148:149], v[164:165], v[148:149]
	v_pk_mul_f32 v[150:151], v[166:167], v[150:151]
	v_pk_mul_f32 v[152:153], v[168:169], v[152:153]
	v_pk_mul_f32 v[154:155], v[170:171], v[154:155]
	v_pk_mul_f32 v[156:157], v[172:173], v[156:157]
	v_pk_mul_f32 v[158:159], v[174:175], v[158:159]
	global_load_dwordx4 v[242:245], v219, s[8:9] offset:512
	global_load_dwordx4 v[246:249], v219, s[8:9] offset:528
	global_load_dwordx4 v[160:163], v221, s[100:101] offset:512
	global_load_dwordx4 v[164:167], v221, s[100:101] offset:528
	s_waitcnt vmcnt(4)
	v_pk_add_f32 v[176:177], v[176:177], v[224:225]
	v_pk_add_f32 v[178:179], v[178:179], v[226:227]
	v_pk_add_f32 v[180:181], v[180:181], v[228:229]
	v_pk_add_f32 v[182:183], v[182:183], v[230:231]
	v_pk_fma_f32 v[140:141], v[140:141], v[60:61], v[176:177]
	v_pk_fma_f32 v[142:143], v[142:143], v[62:63], v[178:179]
	v_pk_fma_f32 v[136:137], v[136:137], v[56:57], v[180:181]
	v_pk_fma_f32 v[138:139], v[138:139], v[58:59], v[182:183]
	global_store_dwordx4 v219, v[140:143], s[10:11] offset:0
	global_store_dwordx4 v219, v[136:139], s[10:11] offset:16
	v_mul_f32_e32 v198, v140, v140
	v_fmac_f32_e32 v198, v141, v141
	v_fmac_f32_e32 v198, v142, v142
	v_fmac_f32_e32 v198, v143, v143
	v_fmac_f32_e32 v198, v136, v136
	v_fmac_f32_e32 v198, v137, v137
	v_fmac_f32_e32 v198, v138, v138
	v_fmac_f32_e32 v198, v139, v139
	v_pk_mul_f32 v[176:177], v[144:145], v[140:141]
	v_pk_mul_f32 v[178:179], v[146:147], v[142:143]
	v_pk_mul_f32 v[180:181], v[148:149], v[136:137]
	v_pk_mul_f32 v[182:183], v[150:151], v[138:139]
	v_cvt_pk_bf16_f32 v176, v176, v177
	v_cvt_pk_bf16_f32 v177, v178, v179
	v_cvt_pk_bf16_f32 v178, v180, v181
	v_cvt_pk_bf16_f32 v179, v182, v183
	global_store_dwordx4 v220, v[176:179], s[98:99] offset:0
	s_add_u32 s8, s8, 0x10000
	s_addc_u32 s9, s9, 0
	s_add_u32 s100, s100, 0x8000
	s_addc_u32 s101, s101, 0
	global_load_dwordx4 v[168:171], v219, s[8:9] offset:0
	global_load_dwordx4 v[172:175], v219, s[8:9] offset:16
	global_load_dwordx4 v[180:183], v221, s[100:101] offset:0
	global_load_dwordx4 v[224:227], v221, s[100:101] offset:16
	global_load_dwordx4 v[228:231], v219, s[8:9] offset:512
	global_load_dwordx4 v[140:143], v219, s[8:9] offset:528
	global_load_dwordx4 v[136:139], v221, s[100:101] offset:512
	global_load_dwordx4 v[176:179], v221, s[100:101] offset:528
	s_waitcnt vmcnt(11)
	v_pk_add_f32 v[242:243], v[242:243], v[160:161]
	v_pk_add_f32 v[244:245], v[244:245], v[162:163]
	v_pk_add_f32 v[246:247], v[246:247], v[164:165]
	v_pk_add_f32 v[248:249], v[248:249], v[166:167]
	v_pk_fma_f32 v[132:133], v[132:133], v[44:45], v[242:243]
	v_pk_fma_f32 v[134:135], v[134:135], v[46:47], v[244:245]
	v_pk_fma_f32 v[128:129], v[128:129], v[40:41], v[246:247]
	v_pk_fma_f32 v[130:131], v[130:131], v[42:43], v[248:249]
	global_store_dwordx4 v219, v[132:135], s[10:11] offset:512
	global_store_dwordx4 v219, v[128:131], s[10:11] offset:528
	v_fmac_f32_e32 v198, v132, v132
	v_fmac_f32_e32 v198, v133, v133
	v_fmac_f32_e32 v198, v134, v134
	v_fmac_f32_e32 v198, v135, v135
	v_fmac_f32_e32 v198, v128, v128
	v_fmac_f32_e32 v198, v129, v129
	v_fmac_f32_e32 v198, v130, v130
	v_fmac_f32_e32 v198, v131, v131
	v_pk_mul_f32 v[242:243], v[152:153], v[132:133]
	v_pk_mul_f32 v[244:245], v[154:155], v[134:135]
	v_pk_mul_f32 v[246:247], v[156:157], v[128:129]
	v_pk_mul_f32 v[248:249], v[158:159], v[130:131]
	v_cvt_pk_bf16_f32 v242, v242, v243
	v_cvt_pk_bf16_f32 v243, v244, v245
	v_cvt_pk_bf16_f32 v244, v246, v247
	v_cvt_pk_bf16_f32 v245, v248, v249
	global_store_dwordx4 v220, v[242:245], s[98:99] offset:256
	v_mov_b32_e32 v240, v198
	s_nop 1
	v_permlane16_swap_b32_e32 v198, v240
	v_add_f32_e32 v240, v198, v240
	v_mov_b32_e32 v241, v240
	s_nop 1
	v_permlane32_swap_b32_e32 v240, v241
	v_add_f32_e32 v240, v240, v241
	v_mov_b32_e32 v233, v240
	s_add_u32 s8, s8, 0x10000
	s_addc_u32 s9, s9, 0
	s_add_u32 s100, s100, 0x8000
	s_addc_u32 s101, s101, 0
	global_load_dwordx4 v[246:249], v219, s[8:9] offset:0
	global_load_dwordx4 v[160:163], v219, s[8:9] offset:16
	global_load_dwordx4 v[164:167], v221, s[100:101] offset:0
	global_load_dwordx4 v[132:135], v221, s[100:101] offset:16
	s_waitcnt vmcnt(11)
	s_add_u32 s10, s10, 0x10000
	s_addc_u32 s11, s11, 0
	s_add_u32 s98, s98, 0x8000
	s_addc_u32 s99, s99, 0
	s_add_u32 s66, s66, 0x400
	s_addc_u32 s67, s67, 0
	v_pk_add_f32 v[168:169], v[168:169], v[180:181]
	v_pk_add_f32 v[170:171], v[170:171], v[182:183]
	v_pk_add_f32 v[172:173], v[172:173], v[224:225]
	v_pk_add_f32 v[174:175], v[174:175], v[226:227]
	v_pk_fma_f32 v[124:125], v[124:125], v[60:61], v[168:169]
	v_pk_fma_f32 v[126:127], v[126:127], v[62:63], v[170:171]
	v_pk_fma_f32 v[120:121], v[120:121], v[56:57], v[172:173]
	v_pk_fma_f32 v[122:123], v[122:123], v[58:59], v[174:175]
	global_store_dwordx4 v219, v[124:127], s[10:11] offset:0
	global_store_dwordx4 v219, v[120:123], s[10:11] offset:16
	v_mul_f32_e32 v198, v124, v124
	v_fmac_f32_e32 v198, v125, v125
	v_fmac_f32_e32 v198, v126, v126
	v_fmac_f32_e32 v198, v127, v127
	v_fmac_f32_e32 v198, v120, v120
	v_fmac_f32_e32 v198, v121, v121
	v_fmac_f32_e32 v198, v122, v122
	v_fmac_f32_e32 v198, v123, v123
	v_pk_mul_f32 v[168:169], v[144:145], v[124:125]
	v_pk_mul_f32 v[170:171], v[146:147], v[126:127]
	v_pk_mul_f32 v[172:173], v[148:149], v[120:121]
	v_pk_mul_f32 v[174:175], v[150:151], v[122:123]
	v_cvt_pk_bf16_f32 v168, v168, v169
	v_cvt_pk_bf16_f32 v169, v170, v171
	v_cvt_pk_bf16_f32 v170, v172, v173
	v_cvt_pk_bf16_f32 v171, v174, v175
	global_store_dwordx4 v220, v[168:171], s[98:99] offset:0
	global_load_dwordx4 v[128:131], v219, s[8:9] offset:512
	global_load_dwordx4 v[242:245], v219, s[8:9] offset:528
	global_load_dwordx4 v[172:175], v221, s[100:101] offset:512
	global_load_dwordx4 v[180:183], v221, s[100:101] offset:528
	s_add_u32 s8, s8, 0x10000
	s_addc_u32 s9, s9, 0
	s_add_u32 s100, s100, 0x8000
	s_addc_u32 s101, s101, 0
	global_load_dwordx4 v[224:227], v219, s[8:9] offset:0
	global_load_dwordx4 v[124:127], v219, s[8:9] offset:16
	global_load_dwordx4 v[120:123], v221, s[100:101] offset:0
	global_load_dwordx4 v[168:171], v221, s[100:101] offset:16
	s_waitcnt vmcnt(18)
	v_pk_add_f32 v[228:229], v[228:229], v[136:137]
	v_pk_add_f32 v[230:231], v[230:231], v[138:139]
	v_pk_add_f32 v[140:141], v[140:141], v[176:177]
	v_pk_add_f32 v[142:143], v[142:143], v[178:179]
	v_pk_fma_f32 v[116:117], v[116:117], v[44:45], v[228:229]
	v_pk_fma_f32 v[118:119], v[118:119], v[46:47], v[230:231]
	v_pk_fma_f32 v[112:113], v[112:113], v[40:41], v[140:141]
	v_pk_fma_f32 v[114:115], v[114:115], v[42:43], v[142:143]
	global_store_dwordx4 v219, v[116:119], s[10:11] offset:512
	global_store_dwordx4 v219, v[112:115], s[10:11] offset:528
	v_fmac_f32_e32 v198, v116, v116
	v_fmac_f32_e32 v198, v117, v117
	v_fmac_f32_e32 v198, v118, v118
	v_fmac_f32_e32 v198, v119, v119
	v_fmac_f32_e32 v198, v112, v112
	v_fmac_f32_e32 v198, v113, v113
	v_fmac_f32_e32 v198, v114, v114
	v_fmac_f32_e32 v198, v115, v115
	v_pk_mul_f32 v[228:229], v[152:153], v[116:117]
	v_pk_mul_f32 v[230:231], v[154:155], v[118:119]
	v_pk_mul_f32 v[140:141], v[156:157], v[112:113]
	v_pk_mul_f32 v[142:143], v[158:159], v[114:115]
	v_cvt_pk_bf16_f32 v228, v228, v229
	v_cvt_pk_bf16_f32 v229, v230, v231
	v_cvt_pk_bf16_f32 v230, v140, v141
	v_cvt_pk_bf16_f32 v231, v142, v143
	global_store_dwordx4 v220, v[228:231], s[98:99] offset:256
	v_mov_b32_e32 v240, v198
	s_nop 1
	v_permlane16_swap_b32_e32 v198, v240
	v_add_f32_e32 v240, v198, v240
	v_mov_b32_e32 v241, v240
	s_nop 1
	v_permlane32_swap_b32_e32 v240, v241
	v_add_f32_e32 v240, v240, v241
	v_cmp_eq_u32_e64 s[6:7], 1, v236
	s_nop 1
	v_cndmask_b32_e64 v233, v233, v240, s[6:7]
	global_load_dwordx4 v[140:143], v219, s[8:9] offset:512
	global_load_dwordx4 v[136:139], v219, s[8:9] offset:528
	global_load_dwordx4 v[176:179], v221, s[100:101] offset:512
	global_load_dwordx4 v[116:119], v221, s[100:101] offset:528
	s_waitcnt vmcnt(18)
	s_add_u32 s10, s10, 0x10000
	s_addc_u32 s11, s11, 0
	s_add_u32 s98, s98, 0x8000
	s_addc_u32 s99, s99, 0
	s_add_u32 s66, s66, 0x400
	s_addc_u32 s67, s67, 0
	v_pk_add_f32 v[246:247], v[246:247], v[164:165]
	v_pk_add_f32 v[248:249], v[248:249], v[166:167]
	v_pk_add_f32 v[160:161], v[160:161], v[132:133]
	v_pk_add_f32 v[162:163], v[162:163], v[134:135]
	v_pk_fma_f32 v[108:109], v[108:109], v[60:61], v[246:247]
	v_pk_fma_f32 v[110:111], v[110:111], v[62:63], v[248:249]
	v_pk_fma_f32 v[104:105], v[104:105], v[56:57], v[160:161]
	v_pk_fma_f32 v[106:107], v[106:107], v[58:59], v[162:163]
	global_store_dwordx4 v219, v[108:111], s[10:11] offset:0
	global_store_dwordx4 v219, v[104:107], s[10:11] offset:16
	v_mul_f32_e32 v198, v108, v108
	v_fmac_f32_e32 v198, v109, v109
	v_fmac_f32_e32 v198, v110, v110
	v_fmac_f32_e32 v198, v111, v111
	v_fmac_f32_e32 v198, v104, v104
	v_fmac_f32_e32 v198, v105, v105
	v_fmac_f32_e32 v198, v106, v106
	v_fmac_f32_e32 v198, v107, v107
	v_pk_mul_f32 v[246:247], v[144:145], v[108:109]
	v_pk_mul_f32 v[248:249], v[146:147], v[110:111]
	v_pk_mul_f32 v[160:161], v[148:149], v[104:105]
	v_pk_mul_f32 v[162:163], v[150:151], v[106:107]
	v_cvt_pk_bf16_f32 v246, v246, v247
	v_cvt_pk_bf16_f32 v247, v248, v249
	v_cvt_pk_bf16_f32 v248, v160, v161
	v_cvt_pk_bf16_f32 v249, v162, v163
	global_store_dwordx4 v220, v[246:249], s[98:99] offset:0
	s_add_u32 s8, s8, 0x50000
	s_addc_u32 s9, s9, 0
	s_sub_u32 s100, s100, 0x18000
	s_subb_u32 s101, s101, 0
	global_load_dwordx4 v[112:115], v219, s[8:9] offset:0
	global_load_dwordx4 v[228:231], v219, s[8:9] offset:16
	global_load_dwordx4 v[160:163], v221, s[100:101] offset:0
	global_load_dwordx4 v[164:167], v221, s[100:101] offset:16
	global_load_dwordx4 v[132:135], v219, s[8:9] offset:512
	global_load_dwordx4 v[108:111], v219, s[8:9] offset:528
	global_load_dwordx4 v[104:107], v221, s[100:101] offset:512
	global_load_dwordx4 v[246:249], v221, s[100:101] offset:528
	s_waitcnt vmcnt(22)
	v_pk_add_f32 v[128:129], v[128:129], v[172:173]
	v_pk_add_f32 v[130:131], v[130:131], v[174:175]
	v_pk_add_f32 v[242:243], v[242:243], v[180:181]
	v_pk_add_f32 v[244:245], v[244:245], v[182:183]
	v_pk_fma_f32 v[100:101], v[100:101], v[44:45], v[128:129]
	v_pk_fma_f32 v[102:103], v[102:103], v[46:47], v[130:131]
	v_pk_fma_f32 v[96:97], v[96:97], v[40:41], v[242:243]
	v_pk_fma_f32 v[98:99], v[98:99], v[42:43], v[244:245]
	global_store_dwordx4 v219, v[100:103], s[10:11] offset:512
	global_store_dwordx4 v219, v[96:99], s[10:11] offset:528
	v_fmac_f32_e32 v198, v100, v100
	v_fmac_f32_e32 v198, v101, v101
	v_fmac_f32_e32 v198, v102, v102
	v_fmac_f32_e32 v198, v103, v103
	v_fmac_f32_e32 v198, v96, v96
	v_fmac_f32_e32 v198, v97, v97
	v_fmac_f32_e32 v198, v98, v98
	v_fmac_f32_e32 v198, v99, v99
	v_pk_mul_f32 v[128:129], v[152:153], v[100:101]
	v_pk_mul_f32 v[130:131], v[154:155], v[102:103]
	v_pk_mul_f32 v[242:243], v[156:157], v[96:97]
	v_pk_mul_f32 v[244:245], v[158:159], v[98:99]
	v_cvt_pk_bf16_f32 v128, v128, v129
	v_cvt_pk_bf16_f32 v129, v130, v131
	v_cvt_pk_bf16_f32 v130, v242, v243
	v_cvt_pk_bf16_f32 v131, v244, v245
	global_store_dwordx4 v220, v[128:131], s[98:99] offset:256
	v_mov_b32_e32 v240, v198
	s_nop 1
	v_permlane16_swap_b32_e32 v198, v240
	v_add_f32_e32 v240, v198, v240
	v_mov_b32_e32 v241, v240
	s_nop 1
	v_permlane32_swap_b32_e32 v240, v241
	v_add_f32_e32 v240, v240, v241
	v_cmp_eq_u32_e64 s[6:7], 2, v236
	s_nop 1
	v_cndmask_b32_e64 v233, v233, v240, s[6:7]
	s_add_u32 s8, s8, 0x10000
	s_addc_u32 s9, s9, 0
	s_add_u32 s100, s100, 0x8000
	s_addc_u32 s101, s101, 0
	global_load_dwordx4 v[242:245], v219, s[8:9] offset:0
	global_load_dwordx4 v[172:175], v219, s[8:9] offset:16
	global_load_dwordx4 v[180:183], v221, s[100:101] offset:0
	global_load_dwordx4 v[100:103], v221, s[100:101] offset:16
	s_waitcnt vmcnt(25)
	s_add_u32 s10, s10, 0x10000
	s_addc_u32 s11, s11, 0
	s_add_u32 s98, s98, 0x8000
	s_addc_u32 s99, s99, 0
	s_add_u32 s66, s66, 0x400
	s_addc_u32 s67, s67, 0
	v_pk_add_f32 v[224:225], v[224:225], v[120:121]
	v_pk_add_f32 v[226:227], v[226:227], v[122:123]
	v_pk_add_f32 v[124:125], v[124:125], v[168:169]
	v_pk_add_f32 v[126:127], v[126:127], v[170:171]
	v_pk_fma_f32 v[92:93], v[92:93], v[60:61], v[224:225]
	v_pk_fma_f32 v[94:95], v[94:95], v[62:63], v[226:227]
	v_pk_fma_f32 v[88:89], v[88:89], v[56:57], v[124:125]
	v_pk_fma_f32 v[90:91], v[90:91], v[58:59], v[126:127]
	global_store_dwordx4 v219, v[92:95], s[10:11] offset:0
	global_store_dwordx4 v219, v[88:91], s[10:11] offset:16
	v_mul_f32_e32 v198, v92, v92
	v_fmac_f32_e32 v198, v93, v93
	v_fmac_f32_e32 v198, v94, v94
	v_fmac_f32_e32 v198, v95, v95
	v_fmac_f32_e32 v198, v88, v88
	v_fmac_f32_e32 v198, v89, v89
	v_fmac_f32_e32 v198, v90, v90
	v_fmac_f32_e32 v198, v91, v91
	v_pk_mul_f32 v[224:225], v[144:145], v[92:93]
	v_pk_mul_f32 v[226:227], v[146:147], v[94:95]
	v_pk_mul_f32 v[124:125], v[148:149], v[88:89]
	v_pk_mul_f32 v[126:127], v[150:151], v[90:91]
	v_cvt_pk_bf16_f32 v224, v224, v225
	v_cvt_pk_bf16_f32 v225, v226, v227
	v_cvt_pk_bf16_f32 v226, v124, v125
	v_cvt_pk_bf16_f32 v227, v126, v127
	global_store_dwordx4 v220, v[224:227], s[98:99] offset:0
	global_load_dwordx4 v[96:99], v219, s[8:9] offset:512
	global_load_dwordx4 v[128:131], v219, s[8:9] offset:528
	global_load_dwordx4 v[124:127], v221, s[100:101] offset:512
	global_load_dwordx4 v[120:123], v221, s[100:101] offset:528
	s_add_u32 s8, s8, 0x10000
	s_addc_u32 s9, s9, 0
	s_add_u32 s100, s100, 0x8000
	s_addc_u32 s101, s101, 0
	global_load_dwordx4 v[168:171], v219, s[8:9] offset:0
	global_load_dwordx4 v[92:95], v219, s[8:9] offset:16
	global_load_dwordx4 v[88:91], v221, s[100:101] offset:0
	global_load_dwordx4 v[224:227], v221, s[100:101] offset:16
	s_waitcnt vmcnt(29)
	v_pk_add_f32 v[140:141], v[140:141], v[176:177]
	v_pk_add_f32 v[142:143], v[142:143], v[178:179]
	v_pk_add_f32 v[136:137], v[136:137], v[116:117]
	v_pk_add_f32 v[138:139], v[138:139], v[118:119]
	v_pk_fma_f32 v[84:85], v[84:85], v[44:45], v[140:141]
	v_pk_fma_f32 v[86:87], v[86:87], v[46:47], v[142:143]
	v_pk_fma_f32 v[80:81], v[80:81], v[40:41], v[136:137]
	v_pk_fma_f32 v[82:83], v[82:83], v[42:43], v[138:139]
	global_store_dwordx4 v219, v[84:87], s[10:11] offset:512
	global_store_dwordx4 v219, v[80:83], s[10:11] offset:528
	v_fmac_f32_e32 v198, v84, v84
	v_fmac_f32_e32 v198, v85, v85
	v_fmac_f32_e32 v198, v86, v86
	v_fmac_f32_e32 v198, v87, v87
	v_fmac_f32_e32 v198, v80, v80
	v_fmac_f32_e32 v198, v81, v81
	v_fmac_f32_e32 v198, v82, v82
	v_fmac_f32_e32 v198, v83, v83
	v_pk_mul_f32 v[140:141], v[152:153], v[84:85]
	v_pk_mul_f32 v[142:143], v[154:155], v[86:87]
	v_pk_mul_f32 v[136:137], v[156:157], v[80:81]
	v_pk_mul_f32 v[138:139], v[158:159], v[82:83]
	v_cvt_pk_bf16_f32 v140, v140, v141
	v_cvt_pk_bf16_f32 v141, v142, v143
	v_cvt_pk_bf16_f32 v142, v136, v137
	v_cvt_pk_bf16_f32 v143, v138, v139
	global_store_dwordx4 v220, v[140:143], s[98:99] offset:256
	v_mov_b32_e32 v240, v198
	s_nop 1
	v_permlane16_swap_b32_e32 v198, v240
	v_add_f32_e32 v240, v198, v240
	v_mov_b32_e32 v241, v240
	s_nop 1
	v_permlane32_swap_b32_e32 v240, v241
	v_add_f32_e32 v240, v240, v241
	v_cmp_eq_u32_e64 s[6:7], 3, v236
	s_nop 1
	v_cndmask_b32_e64 v233, v233, v240, s[6:7]
	global_store_dword v222, v233, s[66:67] offset:-3072
	global_load_dwordx4 v[136:139], v219, s[8:9] offset:512
	global_load_dwordx4 v[176:179], v219, s[8:9] offset:528
	global_load_dwordx4 v[116:119], v221, s[100:101] offset:512
	global_load_dwordx4 v[84:87], v221, s[100:101] offset:528
	s_waitcnt vmcnt(30)
	s_add_u32 s10, s10, 0x50000
	s_addc_u32 s11, s11, 0
	s_add_u32 s98, s98, 0x28000
	s_addc_u32 s99, s99, 0
	s_add_u32 s66, s66, 0x1400
	s_addc_u32 s67, s67, 0
	v_pk_add_f32 v[112:113], v[112:113], v[160:161]
	v_pk_add_f32 v[114:115], v[114:115], v[162:163]
	v_pk_add_f32 v[228:229], v[228:229], v[164:165]
	v_pk_add_f32 v[230:231], v[230:231], v[166:167]
	v_pk_fma_f32 v[76:77], v[76:77], v[60:61], v[112:113]
	v_pk_fma_f32 v[78:79], v[78:79], v[62:63], v[114:115]
	v_pk_fma_f32 v[72:73], v[72:73], v[56:57], v[228:229]
	v_pk_fma_f32 v[74:75], v[74:75], v[58:59], v[230:231]
	global_store_dwordx4 v219, v[76:79], s[10:11] offset:0
	global_store_dwordx4 v219, v[72:75], s[10:11] offset:16
	v_mul_f32_e32 v198, v76, v76
	v_fmac_f32_e32 v198, v77, v77
	v_fmac_f32_e32 v198, v78, v78
	v_fmac_f32_e32 v198, v79, v79
	v_fmac_f32_e32 v198, v72, v72
	v_fmac_f32_e32 v198, v73, v73
	v_fmac_f32_e32 v198, v74, v74
	v_fmac_f32_e32 v198, v75, v75
	v_pk_mul_f32 v[112:113], v[144:145], v[76:77]
	v_pk_mul_f32 v[114:115], v[146:147], v[78:79]
	v_pk_mul_f32 v[228:229], v[148:149], v[72:73]
	v_pk_mul_f32 v[230:231], v[150:151], v[74:75]
	v_cvt_pk_bf16_f32 v112, v112, v113
	v_cvt_pk_bf16_f32 v113, v114, v115
	v_cvt_pk_bf16_f32 v114, v228, v229
	v_cvt_pk_bf16_f32 v115, v230, v231
	global_store_dwordx4 v220, v[112:115], s[98:99] offset:0
	s_add_u32 s8, s8, 0x10000
	s_addc_u32 s9, s9, 0
	s_add_u32 s100, s100, 0x8000
	s_addc_u32 s101, s101, 0
	global_load_dwordx4 v[80:83], v219, s[8:9] offset:0
	global_load_dwordx4 v[140:143], v219, s[8:9] offset:16
	global_load_dwordx4 v[228:231], v221, s[100:101] offset:0
	global_load_dwordx4 v[160:163], v221, s[100:101] offset:16
	global_load_dwordx4 v[164:167], v219, s[8:9] offset:512
	global_load_dwordx4 v[76:79], v219, s[8:9] offset:528
	global_load_dwordx4 v[72:75], v221, s[100:101] offset:512
	global_load_dwordx4 v[112:115], v221, s[100:101] offset:528
	s_waitcnt vmcnt(37)
	v_pk_add_f32 v[132:133], v[132:133], v[104:105]
	v_pk_add_f32 v[134:135], v[134:135], v[106:107]
	v_pk_add_f32 v[108:109], v[108:109], v[246:247]
	v_pk_add_f32 v[110:111], v[110:111], v[248:249]
	v_pk_fma_f32 v[68:69], v[68:69], v[44:45], v[132:133]
	v_pk_fma_f32 v[70:71], v[70:71], v[46:47], v[134:135]
	v_pk_fma_f32 v[64:65], v[64:65], v[40:41], v[108:109]
	v_pk_fma_f32 v[66:67], v[66:67], v[42:43], v[110:111]
	global_store_dwordx4 v219, v[68:71], s[10:11] offset:512
	global_store_dwordx4 v219, v[64:67], s[10:11] offset:528
	v_fmac_f32_e32 v198, v68, v68
	v_fmac_f32_e32 v198, v69, v69
	v_fmac_f32_e32 v198, v70, v70
	v_fmac_f32_e32 v198, v71, v71
	v_fmac_f32_e32 v198, v64, v64
	v_fmac_f32_e32 v198, v65, v65
	v_fmac_f32_e32 v198, v66, v66
	v_fmac_f32_e32 v198, v67, v67
	v_pk_mul_f32 v[132:133], v[152:153], v[68:69]
	v_pk_mul_f32 v[134:135], v[154:155], v[70:71]
	v_pk_mul_f32 v[108:109], v[156:157], v[64:65]
	v_pk_mul_f32 v[110:111], v[158:159], v[66:67]
	v_cvt_pk_bf16_f32 v132, v132, v133
	v_cvt_pk_bf16_f32 v133, v134, v135
	v_cvt_pk_bf16_f32 v134, v108, v109
	v_cvt_pk_bf16_f32 v135, v110, v111
	global_store_dwordx4 v220, v[132:135], s[98:99] offset:256
	v_mov_b32_e32 v240, v198
	s_nop 1
	v_permlane16_swap_b32_e32 v198, v240
	v_add_f32_e32 v240, v198, v240
	v_mov_b32_e32 v241, v240
	s_nop 1
	v_permlane32_swap_b32_e32 v240, v241
	v_add_f32_e32 v240, v240, v241
	v_mov_b32_e32 v233, v240
	s_waitcnt vmcnt(33)
	s_add_u32 s10, s10, 0x10000
	s_addc_u32 s11, s11, 0
	s_add_u32 s98, s98, 0x8000
	s_addc_u32 s99, s99, 0
	s_add_u32 s66, s66, 0x400
	s_addc_u32 s67, s67, 0
	v_pk_add_f32 v[242:243], v[242:243], v[180:181]
	v_pk_add_f32 v[244:245], v[244:245], v[182:183]
	v_pk_add_f32 v[172:173], v[172:173], v[100:101]
	v_pk_add_f32 v[174:175], v[174:175], v[102:103]
	v_pk_fma_f32 v[52:53], v[52:53], v[60:61], v[242:243]
	v_pk_fma_f32 v[54:55], v[54:55], v[62:63], v[244:245]
	v_pk_fma_f32 v[48:49], v[48:49], v[56:57], v[172:173]
	v_pk_fma_f32 v[50:51], v[50:51], v[58:59], v[174:175]
	global_store_dwordx4 v219, v[52:55], s[10:11] offset:0
	global_store_dwordx4 v219, v[48:51], s[10:11] offset:16
	v_mul_f32_e32 v198, v52, v52
	v_fmac_f32_e32 v198, v53, v53
	v_fmac_f32_e32 v198, v54, v54
	v_fmac_f32_e32 v198, v55, v55
	v_fmac_f32_e32 v198, v48, v48
	v_fmac_f32_e32 v198, v49, v49
	v_fmac_f32_e32 v198, v50, v50
	v_fmac_f32_e32 v198, v51, v51
	v_pk_mul_f32 v[242:243], v[144:145], v[52:53]
	v_pk_mul_f32 v[244:245], v[146:147], v[54:55]
	v_pk_mul_f32 v[172:173], v[148:149], v[48:49]
	v_pk_mul_f32 v[174:175], v[150:151], v[50:51]
	v_cvt_pk_bf16_f32 v242, v242, v243
	v_cvt_pk_bf16_f32 v243, v244, v245
	v_cvt_pk_bf16_f32 v244, v172, v173
	v_cvt_pk_bf16_f32 v245, v174, v175
	global_store_dwordx4 v220, v[242:245], s[98:99] offset:0
	s_waitcnt vmcnt(29)
	v_pk_add_f32 v[96:97], v[96:97], v[124:125]
	v_pk_add_f32 v[98:99], v[98:99], v[126:127]
	v_pk_add_f32 v[128:129], v[128:129], v[120:121]
	v_pk_add_f32 v[130:131], v[130:131], v[122:123]
	v_pk_fma_f32 v[36:37], v[36:37], v[44:45], v[96:97]
	v_pk_fma_f32 v[38:39], v[38:39], v[46:47], v[98:99]
	v_pk_fma_f32 v[32:33], v[32:33], v[40:41], v[128:129]
	v_pk_fma_f32 v[34:35], v[34:35], v[42:43], v[130:131]
	global_store_dwordx4 v219, v[36:39], s[10:11] offset:512
	global_store_dwordx4 v219, v[32:35], s[10:11] offset:528
	v_fmac_f32_e32 v198, v36, v36
	v_fmac_f32_e32 v198, v37, v37
	v_fmac_f32_e32 v198, v38, v38
	v_fmac_f32_e32 v198, v39, v39
	v_fmac_f32_e32 v198, v32, v32
	v_fmac_f32_e32 v198, v33, v33
	v_fmac_f32_e32 v198, v34, v34
	v_fmac_f32_e32 v198, v35, v35
	v_pk_mul_f32 v[96:97], v[152:153], v[36:37]
	v_pk_mul_f32 v[98:99], v[154:155], v[38:39]
	v_pk_mul_f32 v[128:129], v[156:157], v[32:33]
	v_pk_mul_f32 v[130:131], v[158:159], v[34:35]
	v_cvt_pk_bf16_f32 v96, v96, v97
	v_cvt_pk_bf16_f32 v97, v98, v99
	v_cvt_pk_bf16_f32 v98, v128, v129
	v_cvt_pk_bf16_f32 v99, v130, v131
	global_store_dwordx4 v220, v[96:99], s[98:99] offset:256
	v_mov_b32_e32 v240, v198
	s_nop 1
	v_permlane16_swap_b32_e32 v198, v240
	v_add_f32_e32 v240, v198, v240
	v_mov_b32_e32 v241, v240
	s_nop 1
	v_permlane32_swap_b32_e32 v240, v241
	v_add_f32_e32 v240, v240, v241
	v_cmp_eq_u32_e64 s[6:7], 1, v236
	s_nop 1
	v_cndmask_b32_e64 v233, v233, v240, s[6:7]
	s_waitcnt vmcnt(28)
	s_add_u32 s10, s10, 0x10000
	s_addc_u32 s11, s11, 0
	s_add_u32 s98, s98, 0x8000
	s_addc_u32 s99, s99, 0
	s_add_u32 s66, s66, 0x400
	s_addc_u32 s67, s67, 0
	v_pk_add_f32 v[168:169], v[168:169], v[88:89]
	v_pk_add_f32 v[170:171], v[170:171], v[90:91]
	v_pk_add_f32 v[92:93], v[92:93], v[224:225]
	v_pk_add_f32 v[94:95], v[94:95], v[226:227]
	v_pk_fma_f32 v[28:29], v[28:29], v[60:61], v[168:169]
	v_pk_fma_f32 v[30:31], v[30:31], v[62:63], v[170:171]
	v_pk_fma_f32 v[24:25], v[24:25], v[56:57], v[92:93]
	v_pk_fma_f32 v[26:27], v[26:27], v[58:59], v[94:95]
	global_store_dwordx4 v219, v[28:31], s[10:11] offset:0
	global_store_dwordx4 v219, v[24:27], s[10:11] offset:16
	v_mul_f32_e32 v198, v28, v28
	v_fmac_f32_e32 v198, v29, v29
	v_fmac_f32_e32 v198, v30, v30
	v_fmac_f32_e32 v198, v31, v31
	v_fmac_f32_e32 v198, v24, v24
	v_fmac_f32_e32 v198, v25, v25
	v_fmac_f32_e32 v198, v26, v26
	v_fmac_f32_e32 v198, v27, v27
	v_pk_mul_f32 v[168:169], v[144:145], v[28:29]
	v_pk_mul_f32 v[170:171], v[146:147], v[30:31]
	v_pk_mul_f32 v[92:93], v[148:149], v[24:25]
	v_pk_mul_f32 v[94:95], v[150:151], v[26:27]
	v_cvt_pk_bf16_f32 v168, v168, v169
	v_cvt_pk_bf16_f32 v169, v170, v171
	v_cvt_pk_bf16_f32 v170, v92, v93
	v_cvt_pk_bf16_f32 v171, v94, v95
	global_store_dwordx4 v220, v[168:171], s[98:99] offset:0
	s_waitcnt vmcnt(23)
	v_pk_add_f32 v[136:137], v[136:137], v[116:117]
	v_pk_add_f32 v[138:139], v[138:139], v[118:119]
	v_pk_add_f32 v[176:177], v[176:177], v[84:85]
	v_pk_add_f32 v[178:179], v[178:179], v[86:87]
	v_pk_fma_f32 v[20:21], v[20:21], v[44:45], v[136:137]
	v_pk_fma_f32 v[22:23], v[22:23], v[46:47], v[138:139]
	v_pk_fma_f32 v[16:17], v[16:17], v[40:41], v[176:177]
	v_pk_fma_f32 v[18:19], v[18:19], v[42:43], v[178:179]
	global_store_dwordx4 v219, v[20:23], s[10:11] offset:512
	global_store_dwordx4 v219, v[16:19], s[10:11] offset:528
	v_fmac_f32_e32 v198, v20, v20
	v_fmac_f32_e32 v198, v21, v21
	v_fmac_f32_e32 v198, v22, v22
	v_fmac_f32_e32 v198, v23, v23
	v_fmac_f32_e32 v198, v16, v16
	v_fmac_f32_e32 v198, v17, v17
	v_fmac_f32_e32 v198, v18, v18
	v_fmac_f32_e32 v198, v19, v19
	v_pk_mul_f32 v[136:137], v[152:153], v[20:21]
	v_pk_mul_f32 v[138:139], v[154:155], v[22:23]
	v_pk_mul_f32 v[176:177], v[156:157], v[16:17]
	v_pk_mul_f32 v[178:179], v[158:159], v[18:19]
	v_cvt_pk_bf16_f32 v136, v136, v137
	v_cvt_pk_bf16_f32 v137, v138, v139
	v_cvt_pk_bf16_f32 v138, v176, v177
	v_cvt_pk_bf16_f32 v139, v178, v179
	global_store_dwordx4 v220, v[136:139], s[98:99] offset:256
	v_mov_b32_e32 v240, v198
	s_nop 1
	v_permlane16_swap_b32_e32 v198, v240
	v_add_f32_e32 v240, v198, v240
	v_mov_b32_e32 v241, v240
	s_nop 1
	v_permlane32_swap_b32_e32 v240, v241
	v_add_f32_e32 v240, v240, v241
	v_cmp_eq_u32_e64 s[6:7], 2, v236
	s_nop 1
	v_cndmask_b32_e64 v233, v233, v240, s[6:7]
	s_waitcnt vmcnt(19)
	s_add_u32 s10, s10, 0x10000
	s_addc_u32 s11, s11, 0
	s_add_u32 s98, s98, 0x8000
	s_addc_u32 s99, s99, 0
	s_add_u32 s66, s66, 0x400
	s_addc_u32 s67, s67, 0
	v_pk_add_f32 v[80:81], v[80:81], v[228:229]
	v_pk_add_f32 v[82:83], v[82:83], v[230:231]
	v_pk_add_f32 v[140:141], v[140:141], v[160:161]
	v_pk_add_f32 v[142:143], v[142:143], v[162:163]
	v_pk_fma_f32 v[12:13], v[12:13], v[60:61], v[80:81]
	v_pk_fma_f32 v[14:15], v[14:15], v[62:63], v[82:83]
	v_pk_fma_f32 v[8:9], v[8:9], v[56:57], v[140:141]
	v_pk_fma_f32 v[10:11], v[10:11], v[58:59], v[142:143]
	global_store_dwordx4 v219, v[12:15], s[10:11] offset:0
	global_store_dwordx4 v219, v[8:11], s[10:11] offset:16
	v_mul_f32_e32 v198, v12, v12
	v_fmac_f32_e32 v198, v13, v13
	v_fmac_f32_e32 v198, v14, v14
	v_fmac_f32_e32 v198, v15, v15
	v_fmac_f32_e32 v198, v8, v8
	v_fmac_f32_e32 v198, v9, v9
	v_fmac_f32_e32 v198, v10, v10
	v_fmac_f32_e32 v198, v11, v11
	v_pk_mul_f32 v[80:81], v[144:145], v[12:13]
	v_pk_mul_f32 v[82:83], v[146:147], v[14:15]
	v_pk_mul_f32 v[140:141], v[148:149], v[8:9]
	v_pk_mul_f32 v[142:143], v[150:151], v[10:11]
	v_cvt_pk_bf16_f32 v80, v80, v81
	v_cvt_pk_bf16_f32 v81, v82, v83
	v_cvt_pk_bf16_f32 v82, v140, v141
	v_cvt_pk_bf16_f32 v83, v142, v143
	global_store_dwordx4 v220, v[80:83], s[98:99] offset:0
	s_waitcnt vmcnt(18)
	v_pk_add_f32 v[164:165], v[164:165], v[72:73]
	v_pk_add_f32 v[166:167], v[166:167], v[74:75]
	v_pk_add_f32 v[76:77], v[76:77], v[112:113]
	v_pk_add_f32 v[78:79], v[78:79], v[114:115]
	v_pk_fma_f32 v[4:5], v[4:5], v[44:45], v[164:165]
	v_pk_fma_f32 v[6:7], v[6:7], v[46:47], v[166:167]
	v_pk_fma_f32 v[0:1], v[0:1], v[40:41], v[76:77]
	v_pk_fma_f32 v[2:3], v[2:3], v[42:43], v[78:79]
	global_store_dwordx4 v219, v[4:7], s[10:11] offset:512
	global_store_dwordx4 v219, v[0:3], s[10:11] offset:528
	v_fmac_f32_e32 v198, v4, v4
	v_fmac_f32_e32 v198, v5, v5
	v_fmac_f32_e32 v198, v6, v6
	v_fmac_f32_e32 v198, v7, v7
	v_fmac_f32_e32 v198, v0, v0
	v_fmac_f32_e32 v198, v1, v1
	v_fmac_f32_e32 v198, v2, v2
	v_fmac_f32_e32 v198, v3, v3
	v_pk_mul_f32 v[164:165], v[152:153], v[4:5]
	v_pk_mul_f32 v[166:167], v[154:155], v[6:7]
	v_pk_mul_f32 v[76:77], v[156:157], v[0:1]
	v_pk_mul_f32 v[78:79], v[158:159], v[2:3]
	v_cvt_pk_bf16_f32 v164, v164, v165
	v_cvt_pk_bf16_f32 v165, v166, v167
	v_cvt_pk_bf16_f32 v166, v76, v77
	v_cvt_pk_bf16_f32 v167, v78, v79
	global_store_dwordx4 v220, v[164:167], s[98:99] offset:256
	v_mov_b32_e32 v240, v198
	s_nop 1
	v_permlane16_swap_b32_e32 v198, v240
	v_add_f32_e32 v240, v198, v240
	v_mov_b32_e32 v241, v240
	s_nop 1
	v_permlane32_swap_b32_e32 v240, v241
	v_add_f32_e32 v240, v240, v241
	v_cmp_eq_u32_e64 s[6:7], 3, v236
	s_nop 1
	v_cndmask_b32_e64 v233, v233, v240, s[6:7]
	global_store_dword v222, v233, s[66:67] offset:-3072
	s_branch .Lepo_done
.Lepo_per:
	s_lshl_b32 s8, s66, 4
	s_lshl_b32 s9, s75, 2
	s_add_i32 s8, s8, s9
	s_lshl_b32 s9, s24, 6
	s_add_i32 s8, s8, s9
	s_add_i32 s8, s8, 0xea9a000
	s_add_u32 s66, s58, s8
	s_addc_u32 s67, s59, 0
	s_sub_i32 s8, s6, 32
	s_ashr_i32 s8, s8, 3
	s_add_i32 s8, s8, 1
	s_mul_i32 s8, s8, 0x6000
	s_add_i32 s8, s8, 0xe802000
	s_add_u32 s8, s58, s8
	s_addc_u32 s9, s59, 0
	global_load_dwordx4 v[60:63], v218, s[8:9] offset:0
	global_load_dwordx4 v[56:59], v218, s[8:9] offset:16
	global_load_dwordx4 v[44:47], v218, s[8:9] offset:512
	global_load_dwordx4 v[40:43], v218, s[8:9] offset:528
	s_add_u32 s8, s8, 0x2000
	s_addc_u32 s9, s9, 0
	global_load_dwordx4 v[144:147], v218, s[8:9] offset:0
	global_load_dwordx4 v[148:151], v218, s[8:9] offset:16
	global_load_dwordx4 v[152:155], v218, s[8:9] offset:512
	global_load_dwordx4 v[156:159], v218, s[8:9] offset:528
	global_load_dwordx4 v[160:163], v218, s[18:19] offset:0
	global_load_dwordx4 v[164:167], v218, s[18:19] offset:16
	global_load_dwordx4 v[168:171], v218, s[18:19] offset:512
	global_load_dwordx4 v[172:175], v218, s[18:19] offset:528
	s_sub_i32 s8, s24, 0x2000
	s_lshl_b32 s8, s8, 12
	s_add_u32 s8, s14, s8
	s_addc_u32 s9, s15, 0
	s_lshl_b32 s100, s6, 2
	s_lshr_b32 s101, s76, 6
	s_add_i32 s100, s100, s101
	s_and_b32 s100, s100, 31
	s_lshl_b32 s100, s100, 11
	s_add_i32 s100, s100, 0xe8ea000
	s_add_u32 s100, s58, s100
	s_addc_u32 s101, s59, 0
	v_mov_b32_e32 v221, v218
	global_load_dwordx4 v[176:179], v219, s[8:9] offset:0
	global_load_dwordx4 v[180:183], v219, s[8:9] offset:16
	global_load_dwordx4 v[224:227], v221, s[100:101] offset:0
	global_load_dwordx4 v[228:231], v221, s[100:101] offset:16
	s_waitcnt vmcnt(4)
	v_pk_add_f32 v[144:145], v[144:145], 1.0 op_sel_hi:[1,0]
	v_pk_add_f32 v[146:147], v[146:147], 1.0 op_sel_hi:[1,0]
	v_pk_add_f32 v[148:149], v[148:149], 1.0 op_sel_hi:[1,0]
	v_pk_add_f32 v[150:151], v[150:151], 1.0 op_sel_hi:[1,0]
	v_pk_add_f32 v[152:153], v[152:153], 1.0 op_sel_hi:[1,0]
	v_pk_add_f32 v[154:155], v[154:155], 1.0 op_sel_hi:[1,0]
	v_pk_add_f32 v[156:157], v[156:157], 1.0 op_sel_hi:[1,0]
	v_pk_add_f32 v[158:159], v[158:159], 1.0 op_sel_hi:[1,0]
	v_pk_mul_f32 v[144:145], v[160:161], v[144:145]
	v_pk_mul_f32 v[146:147], v[162:163], v[146:147]
	v_pk_mul_f32 v[148:149], v[164:165], v[148:149]
	v_pk_mul_f32 v[150:151], v[166:167], v[150:151]
	v_pk_mul_f32 v[152:153], v[168:169], v[152:153]
	v_pk_mul_f32 v[154:155], v[170:171], v[154:155]
	v_pk_mul_f32 v[156:157], v[172:173], v[156:157]
	v_pk_mul_f32 v[158:159], v[174:175], v[158:159]
	global_load_dwordx4 v[242:245], v219, s[8:9] offset:512
	global_load_dwordx4 v[246:249], v219, s[8:9] offset:528
	global_load_dwordx4 v[160:163], v221, s[100:101] offset:512
	global_load_dwordx4 v[164:167], v221, s[100:101] offset:528
	s_waitcnt vmcnt(4)
	v_pk_add_f32 v[176:177], v[176:177], v[224:225]
	v_pk_add_f32 v[178:179], v[178:179], v[226:227]
	v_pk_add_f32 v[180:181], v[180:181], v[228:229]
	v_pk_add_f32 v[182:183], v[182:183], v[230:231]
	v_pk_fma_f32 v[140:141], v[140:141], v[60:61], v[176:177]
	v_pk_fma_f32 v[142:143], v[142:143], v[62:63], v[178:179]
	v_pk_fma_f32 v[136:137], v[136:137], v[56:57], v[180:181]
	v_pk_fma_f32 v[138:139], v[138:139], v[58:59], v[182:183]
	global_store_dwordx4 v219, v[140:143], s[10:11] offset:0
	global_store_dwordx4 v219, v[136:139], s[10:11] offset:16
	v_mul_f32_e32 v198, v140, v140
	v_fmac_f32_e32 v198, v141, v141
	v_fmac_f32_e32 v198, v142, v142
	v_fmac_f32_e32 v198, v143, v143
	v_fmac_f32_e32 v198, v136, v136
	v_fmac_f32_e32 v198, v137, v137
	v_fmac_f32_e32 v198, v138, v138
	v_fmac_f32_e32 v198, v139, v139
	v_pk_mul_f32 v[176:177], v[144:145], v[140:141]
	v_pk_mul_f32 v[178:179], v[146:147], v[142:143]
	v_pk_mul_f32 v[180:181], v[148:149], v[136:137]
	v_pk_mul_f32 v[182:183], v[150:151], v[138:139]
	v_cvt_pk_bf16_f32 v176, v176, v177
	v_cvt_pk_bf16_f32 v177, v178, v179
	v_cvt_pk_bf16_f32 v178, v180, v181
	v_cvt_pk_bf16_f32 v179, v182, v183
	global_store_dwordx4 v220, v[176:179], s[98:99] offset:0
	s_add_u32 s8, s8, 0x10000
	s_addc_u32 s9, s9, 0
	global_load_dwordx4 v[168:171], v219, s[8:9] offset:0
	global_load_dwordx4 v[172:175], v219, s[8:9] offset:16
	global_load_dwordx4 v[180:183], v221, s[100:101] offset:0
	global_load_dwordx4 v[224:227], v221, s[100:101] offset:16
	global_load_dwordx4 v[228:231], v219, s[8:9] offset:512
	global_load_dwordx4 v[140:143], v219, s[8:9] offset:528
	global_load_dwordx4 v[136:139], v221, s[100:101] offset:512
	global_load_dwordx4 v[176:179], v221, s[100:101] offset:528
	s_waitcnt vmcnt(11)
	v_pk_add_f32 v[242:243], v[242:243], v[160:161]
	v_pk_add_f32 v[244:245], v[244:245], v[162:163]
	v_pk_add_f32 v[246:247], v[246:247], v[164:165]
	v_pk_add_f32 v[248:249], v[248:249], v[166:167]
	v_pk_fma_f32 v[132:133], v[132:133], v[44:45], v[242:243]
	v_pk_fma_f32 v[134:135], v[134:135], v[46:47], v[244:245]
	v_pk_fma_f32 v[128:129], v[128:129], v[40:41], v[246:247]
	v_pk_fma_f32 v[130:131], v[130:131], v[42:43], v[248:249]
	global_store_dwordx4 v219, v[132:135], s[10:11] offset:512
	global_store_dwordx4 v219, v[128:131], s[10:11] offset:528
	v_fmac_f32_e32 v198, v132, v132
	v_fmac_f32_e32 v198, v133, v133
	v_fmac_f32_e32 v198, v134, v134
	v_fmac_f32_e32 v198, v135, v135
	v_fmac_f32_e32 v198, v128, v128
	v_fmac_f32_e32 v198, v129, v129
	v_fmac_f32_e32 v198, v130, v130
	v_fmac_f32_e32 v198, v131, v131
	v_pk_mul_f32 v[242:243], v[152:153], v[132:133]
	v_pk_mul_f32 v[244:245], v[154:155], v[134:135]
	v_pk_mul_f32 v[246:247], v[156:157], v[128:129]
	v_pk_mul_f32 v[248:249], v[158:159], v[130:131]
	v_cvt_pk_bf16_f32 v242, v242, v243
	v_cvt_pk_bf16_f32 v243, v244, v245
	v_cvt_pk_bf16_f32 v244, v246, v247
	v_cvt_pk_bf16_f32 v245, v248, v249
	global_store_dwordx4 v220, v[242:245], s[98:99] offset:256
	v_mov_b32_e32 v240, v198
	s_nop 1
	v_permlane16_swap_b32_e32 v198, v240
	v_add_f32_e32 v240, v198, v240
	v_mov_b32_e32 v241, v240
	s_nop 1
	v_permlane32_swap_b32_e32 v240, v241
	v_add_f32_e32 v240, v240, v241
	v_mov_b32_e32 v233, v240
	s_add_u32 s8, s8, 0x10000
	s_addc_u32 s9, s9, 0
	global_load_dwordx4 v[246:249], v219, s[8:9] offset:0
	global_load_dwordx4 v[160:163], v219, s[8:9] offset:16
	global_load_dwordx4 v[164:167], v221, s[100:101] offset:0
	global_load_dwordx4 v[132:135], v221, s[100:101] offset:16
	s_waitcnt vmcnt(11)
	s_add_u32 s10, s10, 0x10000
	s_addc_u32 s11, s11, 0
	s_add_u32 s98, s98, 0x8000
	s_addc_u32 s99, s99, 0
	s_add_u32 s66, s66, 0x400
	s_addc_u32 s67, s67, 0
	v_pk_add_f32 v[168:169], v[168:169], v[180:181]
	v_pk_add_f32 v[170:171], v[170:171], v[182:183]
	v_pk_add_f32 v[172:173], v[172:173], v[224:225]
	v_pk_add_f32 v[174:175], v[174:175], v[226:227]
	v_pk_fma_f32 v[124:125], v[124:125], v[60:61], v[168:169]
	v_pk_fma_f32 v[126:127], v[126:127], v[62:63], v[170:171]
	v_pk_fma_f32 v[120:121], v[120:121], v[56:57], v[172:173]
	v_pk_fma_f32 v[122:123], v[122:123], v[58:59], v[174:175]
	global_store_dwordx4 v219, v[124:127], s[10:11] offset:0
	global_store_dwordx4 v219, v[120:123], s[10:11] offset:16
	v_mul_f32_e32 v198, v124, v124
	v_fmac_f32_e32 v198, v125, v125
	v_fmac_f32_e32 v198, v126, v126
	v_fmac_f32_e32 v198, v127, v127
	v_fmac_f32_e32 v198, v120, v120
	v_fmac_f32_e32 v198, v121, v121
	v_fmac_f32_e32 v198, v122, v122
	v_fmac_f32_e32 v198, v123, v123
	v_pk_mul_f32 v[168:169], v[144:145], v[124:125]
	v_pk_mul_f32 v[170:171], v[146:147], v[126:127]
	v_pk_mul_f32 v[172:173], v[148:149], v[120:121]
	v_pk_mul_f32 v[174:175], v[150:151], v[122:123]
	v_cvt_pk_bf16_f32 v168, v168, v169
	v_cvt_pk_bf16_f32 v169, v170, v171
	v_cvt_pk_bf16_f32 v170, v172, v173
	v_cvt_pk_bf16_f32 v171, v174, v175
	global_store_dwordx4 v220, v[168:171], s[98:99] offset:0
	global_load_dwordx4 v[128:131], v219, s[8:9] offset:512
	global_load_dwordx4 v[242:245], v219, s[8:9] offset:528
	global_load_dwordx4 v[172:175], v221, s[100:101] offset:512
	global_load_dwordx4 v[180:183], v221, s[100:101] offset:528
	s_add_u32 s8, s8, 0x10000
	s_addc_u32 s9, s9, 0
	global_load_dwordx4 v[224:227], v219, s[8:9] offset:0
	global_load_dwordx4 v[124:127], v219, s[8:9] offset:16
	global_load_dwordx4 v[120:123], v221, s[100:101] offset:0
	global_load_dwordx4 v[168:171], v221, s[100:101] offset:16
	s_waitcnt vmcnt(18)
	v_pk_add_f32 v[228:229], v[228:229], v[136:137]
	v_pk_add_f32 v[230:231], v[230:231], v[138:139]
	v_pk_add_f32 v[140:141], v[140:141], v[176:177]
	v_pk_add_f32 v[142:143], v[142:143], v[178:179]
	v_pk_fma_f32 v[116:117], v[116:117], v[44:45], v[228:229]
	v_pk_fma_f32 v[118:119], v[118:119], v[46:47], v[230:231]
	v_pk_fma_f32 v[112:113], v[112:113], v[40:41], v[140:141]
	v_pk_fma_f32 v[114:115], v[114:115], v[42:43], v[142:143]
	global_store_dwordx4 v219, v[116:119], s[10:11] offset:512
	global_store_dwordx4 v219, v[112:115], s[10:11] offset:528
	v_fmac_f32_e32 v198, v116, v116
	v_fmac_f32_e32 v198, v117, v117
	v_fmac_f32_e32 v198, v118, v118
	v_fmac_f32_e32 v198, v119, v119
	v_fmac_f32_e32 v198, v112, v112
	v_fmac_f32_e32 v198, v113, v113
	v_fmac_f32_e32 v198, v114, v114
	v_fmac_f32_e32 v198, v115, v115
	v_pk_mul_f32 v[228:229], v[152:153], v[116:117]
	v_pk_mul_f32 v[230:231], v[154:155], v[118:119]
	v_pk_mul_f32 v[140:141], v[156:157], v[112:113]
	v_pk_mul_f32 v[142:143], v[158:159], v[114:115]
	v_cvt_pk_bf16_f32 v228, v228, v229
	v_cvt_pk_bf16_f32 v229, v230, v231
	v_cvt_pk_bf16_f32 v230, v140, v141
	v_cvt_pk_bf16_f32 v231, v142, v143
	global_store_dwordx4 v220, v[228:231], s[98:99] offset:256
	v_mov_b32_e32 v240, v198
	s_nop 1
	v_permlane16_swap_b32_e32 v198, v240
	v_add_f32_e32 v240, v198, v240
	v_mov_b32_e32 v241, v240
	s_nop 1
	v_permlane32_swap_b32_e32 v240, v241
	v_add_f32_e32 v240, v240, v241
	v_cmp_eq_u32_e64 s[6:7], 1, v236
	s_nop 1
	v_cndmask_b32_e64 v233, v233, v240, s[6:7]
	global_load_dwordx4 v[140:143], v219, s[8:9] offset:512
	global_load_dwordx4 v[136:139], v219, s[8:9] offset:528
	global_load_dwordx4 v[176:179], v221, s[100:101] offset:512
	global_load_dwordx4 v[116:119], v221, s[100:101] offset:528
	s_waitcnt vmcnt(18)
	s_add_u32 s10, s10, 0x10000
	s_addc_u32 s11, s11, 0
	s_add_u32 s98, s98, 0x8000
	s_addc_u32 s99, s99, 0
	s_add_u32 s66, s66, 0x400
	s_addc_u32 s67, s67, 0
	v_pk_add_f32 v[246:247], v[246:247], v[164:165]
	v_pk_add_f32 v[248:249], v[248:249], v[166:167]
	v_pk_add_f32 v[160:161], v[160:161], v[132:133]
	v_pk_add_f32 v[162:163], v[162:163], v[134:135]
	v_pk_fma_f32 v[108:109], v[108:109], v[60:61], v[246:247]
	v_pk_fma_f32 v[110:111], v[110:111], v[62:63], v[248:249]
	v_pk_fma_f32 v[104:105], v[104:105], v[56:57], v[160:161]
	v_pk_fma_f32 v[106:107], v[106:107], v[58:59], v[162:163]
	global_store_dwordx4 v219, v[108:111], s[10:11] offset:0
	global_store_dwordx4 v219, v[104:107], s[10:11] offset:16
	v_mul_f32_e32 v198, v108, v108
	v_fmac_f32_e32 v198, v109, v109
	v_fmac_f32_e32 v198, v110, v110
	v_fmac_f32_e32 v198, v111, v111
	v_fmac_f32_e32 v198, v104, v104
	v_fmac_f32_e32 v198, v105, v105
	v_fmac_f32_e32 v198, v106, v106
	v_fmac_f32_e32 v198, v107, v107
	v_pk_mul_f32 v[246:247], v[144:145], v[108:109]
	v_pk_mul_f32 v[248:249], v[146:147], v[110:111]
	v_pk_mul_f32 v[160:161], v[148:149], v[104:105]
	v_pk_mul_f32 v[162:163], v[150:151], v[106:107]
	v_cvt_pk_bf16_f32 v246, v246, v247
	v_cvt_pk_bf16_f32 v247, v248, v249
	v_cvt_pk_bf16_f32 v248, v160, v161
	v_cvt_pk_bf16_f32 v249, v162, v163
	global_store_dwordx4 v220, v[246:249], s[98:99] offset:0
	s_add_u32 s8, s8, 0x50000
	s_addc_u32 s9, s9, 0
	s_add_u32 s100, s100, 0x1000
	s_addc_u32 s101, s101, 0
	global_load_dwordx4 v[112:115], v219, s[8:9] offset:0
	global_load_dwordx4 v[228:231], v219, s[8:9] offset:16
	global_load_dwordx4 v[160:163], v221, s[100:101] offset:0
	global_load_dwordx4 v[164:167], v221, s[100:101] offset:16
	global_load_dwordx4 v[132:135], v219, s[8:9] offset:512
	global_load_dwordx4 v[108:111], v219, s[8:9] offset:528
	global_load_dwordx4 v[104:107], v221, s[100:101] offset:512
	global_load_dwordx4 v[246:249], v221, s[100:101] offset:528
	s_waitcnt vmcnt(22)
	v_pk_add_f32 v[128:129], v[128:129], v[172:173]
	v_pk_add_f32 v[130:131], v[130:131], v[174:175]
	v_pk_add_f32 v[242:243], v[242:243], v[180:181]
	v_pk_add_f32 v[244:245], v[244:245], v[182:183]
	v_pk_fma_f32 v[100:101], v[100:101], v[44:45], v[128:129]
	v_pk_fma_f32 v[102:103], v[102:103], v[46:47], v[130:131]
	v_pk_fma_f32 v[96:97], v[96:97], v[40:41], v[242:243]
	v_pk_fma_f32 v[98:99], v[98:99], v[42:43], v[244:245]
	global_store_dwordx4 v219, v[100:103], s[10:11] offset:512
	global_store_dwordx4 v219, v[96:99], s[10:11] offset:528
	v_fmac_f32_e32 v198, v100, v100
	v_fmac_f32_e32 v198, v101, v101
	v_fmac_f32_e32 v198, v102, v102
	v_fmac_f32_e32 v198, v103, v103
	v_fmac_f32_e32 v198, v96, v96
	v_fmac_f32_e32 v198, v97, v97
	v_fmac_f32_e32 v198, v98, v98
	v_fmac_f32_e32 v198, v99, v99
	v_pk_mul_f32 v[128:129], v[152:153], v[100:101]
	v_pk_mul_f32 v[130:131], v[154:155], v[102:103]
	v_pk_mul_f32 v[242:243], v[156:157], v[96:97]
	v_pk_mul_f32 v[244:245], v[158:159], v[98:99]
	v_cvt_pk_bf16_f32 v128, v128, v129
	v_cvt_pk_bf16_f32 v129, v130, v131
	v_cvt_pk_bf16_f32 v130, v242, v243
	v_cvt_pk_bf16_f32 v131, v244, v245
	global_store_dwordx4 v220, v[128:131], s[98:99] offset:256
	v_mov_b32_e32 v240, v198
	s_nop 1
	v_permlane16_swap_b32_e32 v198, v240
	v_add_f32_e32 v240, v198, v240
	v_mov_b32_e32 v241, v240
	s_nop 1
	v_permlane32_swap_b32_e32 v240, v241
	v_add_f32_e32 v240, v240, v241
	v_cmp_eq_u32_e64 s[6:7], 2, v236
	s_nop 1
	v_cndmask_b32_e64 v233, v233, v240, s[6:7]
	s_add_u32 s8, s8, 0x10000
	s_addc_u32 s9, s9, 0
	global_load_dwordx4 v[242:245], v219, s[8:9] offset:0
	global_load_dwordx4 v[172:175], v219, s[8:9] offset:16
	global_load_dwordx4 v[180:183], v221, s[100:101] offset:0
	global_load_dwordx4 v[100:103], v221, s[100:101] offset:16
	s_waitcnt vmcnt(25)
	s_add_u32 s10, s10, 0x10000
	s_addc_u32 s11, s11, 0
	s_add_u32 s98, s98, 0x8000
	s_addc_u32 s99, s99, 0
	s_add_u32 s66, s66, 0x400
	s_addc_u32 s67, s67, 0
	v_pk_add_f32 v[224:225], v[224:225], v[120:121]
	v_pk_add_f32 v[226:227], v[226:227], v[122:123]
	v_pk_add_f32 v[124:125], v[124:125], v[168:169]
	v_pk_add_f32 v[126:127], v[126:127], v[170:171]
	v_pk_fma_f32 v[92:93], v[92:93], v[60:61], v[224:225]
	v_pk_fma_f32 v[94:95], v[94:95], v[62:63], v[226:227]
	v_pk_fma_f32 v[88:89], v[88:89], v[56:57], v[124:125]
	v_pk_fma_f32 v[90:91], v[90:91], v[58:59], v[126:127]
	global_store_dwordx4 v219, v[92:95], s[10:11] offset:0
	global_store_dwordx4 v219, v[88:91], s[10:11] offset:16
	v_mul_f32_e32 v198, v92, v92
	v_fmac_f32_e32 v198, v93, v93
	v_fmac_f32_e32 v198, v94, v94
	v_fmac_f32_e32 v198, v95, v95
	v_fmac_f32_e32 v198, v88, v88
	v_fmac_f32_e32 v198, v89, v89
	v_fmac_f32_e32 v198, v90, v90
	v_fmac_f32_e32 v198, v91, v91
	v_pk_mul_f32 v[224:225], v[144:145], v[92:93]
	v_pk_mul_f32 v[226:227], v[146:147], v[94:95]
	v_pk_mul_f32 v[124:125], v[148:149], v[88:89]
	v_pk_mul_f32 v[126:127], v[150:151], v[90:91]
	v_cvt_pk_bf16_f32 v224, v224, v225
	v_cvt_pk_bf16_f32 v225, v226, v227
	v_cvt_pk_bf16_f32 v226, v124, v125
	v_cvt_pk_bf16_f32 v227, v126, v127
	global_store_dwordx4 v220, v[224:227], s[98:99] offset:0
	global_load_dwordx4 v[96:99], v219, s[8:9] offset:512
	global_load_dwordx4 v[128:131], v219, s[8:9] offset:528
	global_load_dwordx4 v[124:127], v221, s[100:101] offset:512
	global_load_dwordx4 v[120:123], v221, s[100:101] offset:528
	s_add_u32 s8, s8, 0x10000
	s_addc_u32 s9, s9, 0
	global_load_dwordx4 v[168:171], v219, s[8:9] offset:0
	global_load_dwordx4 v[92:95], v219, s[8:9] offset:16
	global_load_dwordx4 v[88:91], v221, s[100:101] offset:0
	global_load_dwordx4 v[224:227], v221, s[100:101] offset:16
	s_waitcnt vmcnt(29)
	v_pk_add_f32 v[140:141], v[140:141], v[176:177]
	v_pk_add_f32 v[142:143], v[142:143], v[178:179]
	v_pk_add_f32 v[136:137], v[136:137], v[116:117]
	v_pk_add_f32 v[138:139], v[138:139], v[118:119]
	v_pk_fma_f32 v[84:85], v[84:85], v[44:45], v[140:141]
	v_pk_fma_f32 v[86:87], v[86:87], v[46:47], v[142:143]
	v_pk_fma_f32 v[80:81], v[80:81], v[40:41], v[136:137]
	v_pk_fma_f32 v[82:83], v[82:83], v[42:43], v[138:139]
	global_store_dwordx4 v219, v[84:87], s[10:11] offset:512
	global_store_dwordx4 v219, v[80:83], s[10:11] offset:528
	v_fmac_f32_e32 v198, v84, v84
	v_fmac_f32_e32 v198, v85, v85
	v_fmac_f32_e32 v198, v86, v86
	v_fmac_f32_e32 v198, v87, v87
	v_fmac_f32_e32 v198, v80, v80
	v_fmac_f32_e32 v198, v81, v81
	v_fmac_f32_e32 v198, v82, v82
	v_fmac_f32_e32 v198, v83, v83
	v_pk_mul_f32 v[140:141], v[152:153], v[84:85]
	v_pk_mul_f32 v[142:143], v[154:155], v[86:87]
	v_pk_mul_f32 v[136:137], v[156:157], v[80:81]
	v_pk_mul_f32 v[138:139], v[158:159], v[82:83]
	v_cvt_pk_bf16_f32 v140, v140, v141
	v_cvt_pk_bf16_f32 v141, v142, v143
	v_cvt_pk_bf16_f32 v142, v136, v137
	v_cvt_pk_bf16_f32 v143, v138, v139
	global_store_dwordx4 v220, v[140:143], s[98:99] offset:256
	v_mov_b32_e32 v240, v198
	s_nop 1
	v_permlane16_swap_b32_e32 v198, v240
	v_add_f32_e32 v240, v198, v240
	v_mov_b32_e32 v241, v240
	s_nop 1
	v_permlane32_swap_b32_e32 v240, v241
	v_add_f32_e32 v240, v240, v241
	v_cmp_eq_u32_e64 s[6:7], 3, v236
	s_nop 1
	v_cndmask_b32_e64 v233, v233, v240, s[6:7]
	global_store_dword v222, v233, s[66:67] offset:-3072
	global_load_dwordx4 v[136:139], v219, s[8:9] offset:512
	global_load_dwordx4 v[176:179], v219, s[8:9] offset:528
	global_load_dwordx4 v[116:119], v221, s[100:101] offset:512
	global_load_dwordx4 v[84:87], v221, s[100:101] offset:528
	s_waitcnt vmcnt(30)
	s_add_u32 s10, s10, 0x50000
	s_addc_u32 s11, s11, 0
	s_add_u32 s98, s98, 0x28000
	s_addc_u32 s99, s99, 0
	s_add_u32 s66, s66, 0x1400
	s_addc_u32 s67, s67, 0
	v_pk_add_f32 v[112:113], v[112:113], v[160:161]
	v_pk_add_f32 v[114:115], v[114:115], v[162:163]
	v_pk_add_f32 v[228:229], v[228:229], v[164:165]
	v_pk_add_f32 v[230:231], v[230:231], v[166:167]
	v_pk_fma_f32 v[76:77], v[76:77], v[60:61], v[112:113]
	v_pk_fma_f32 v[78:79], v[78:79], v[62:63], v[114:115]
	v_pk_fma_f32 v[72:73], v[72:73], v[56:57], v[228:229]
	v_pk_fma_f32 v[74:75], v[74:75], v[58:59], v[230:231]
	global_store_dwordx4 v219, v[76:79], s[10:11] offset:0
	global_store_dwordx4 v219, v[72:75], s[10:11] offset:16
	v_mul_f32_e32 v198, v76, v76
	v_fmac_f32_e32 v198, v77, v77
	v_fmac_f32_e32 v198, v78, v78
	v_fmac_f32_e32 v198, v79, v79
	v_fmac_f32_e32 v198, v72, v72
	v_fmac_f32_e32 v198, v73, v73
	v_fmac_f32_e32 v198, v74, v74
	v_fmac_f32_e32 v198, v75, v75
	v_pk_mul_f32 v[112:113], v[144:145], v[76:77]
	v_pk_mul_f32 v[114:115], v[146:147], v[78:79]
	v_pk_mul_f32 v[228:229], v[148:149], v[72:73]
	v_pk_mul_f32 v[230:231], v[150:151], v[74:75]
	v_cvt_pk_bf16_f32 v112, v112, v113
	v_cvt_pk_bf16_f32 v113, v114, v115
	v_cvt_pk_bf16_f32 v114, v228, v229
	v_cvt_pk_bf16_f32 v115, v230, v231
	global_store_dwordx4 v220, v[112:115], s[98:99] offset:0
	s_add_u32 s8, s8, 0x10000
	s_addc_u32 s9, s9, 0
	global_load_dwordx4 v[80:83], v219, s[8:9] offset:0
	global_load_dwordx4 v[140:143], v219, s[8:9] offset:16
	global_load_dwordx4 v[228:231], v221, s[100:101] offset:0
	global_load_dwordx4 v[160:163], v221, s[100:101] offset:16
	global_load_dwordx4 v[164:167], v219, s[8:9] offset:512
	global_load_dwordx4 v[76:79], v219, s[8:9] offset:528
	global_load_dwordx4 v[72:75], v221, s[100:101] offset:512
	global_load_dwordx4 v[112:115], v221, s[100:101] offset:528
	s_waitcnt vmcnt(37)
	v_pk_add_f32 v[132:133], v[132:133], v[104:105]
	v_pk_add_f32 v[134:135], v[134:135], v[106:107]
	v_pk_add_f32 v[108:109], v[108:109], v[246:247]
	v_pk_add_f32 v[110:111], v[110:111], v[248:249]
	v_pk_fma_f32 v[68:69], v[68:69], v[44:45], v[132:133]
	v_pk_fma_f32 v[70:71], v[70:71], v[46:47], v[134:135]
	v_pk_fma_f32 v[64:65], v[64:65], v[40:41], v[108:109]
	v_pk_fma_f32 v[66:67], v[66:67], v[42:43], v[110:111]
	global_store_dwordx4 v219, v[68:71], s[10:11] offset:512
	global_store_dwordx4 v219, v[64:67], s[10:11] offset:528
	v_fmac_f32_e32 v198, v68, v68
	v_fmac_f32_e32 v198, v69, v69
	v_fmac_f32_e32 v198, v70, v70
	v_fmac_f32_e32 v198, v71, v71
	v_fmac_f32_e32 v198, v64, v64
	v_fmac_f32_e32 v198, v65, v65
	v_fmac_f32_e32 v198, v66, v66
	v_fmac_f32_e32 v198, v67, v67
	v_pk_mul_f32 v[132:133], v[152:153], v[68:69]
	v_pk_mul_f32 v[134:135], v[154:155], v[70:71]
	v_pk_mul_f32 v[108:109], v[156:157], v[64:65]
	v_pk_mul_f32 v[110:111], v[158:159], v[66:67]
	v_cvt_pk_bf16_f32 v132, v132, v133
	v_cvt_pk_bf16_f32 v133, v134, v135
	v_cvt_pk_bf16_f32 v134, v108, v109
	v_cvt_pk_bf16_f32 v135, v110, v111
	global_store_dwordx4 v220, v[132:135], s[98:99] offset:256
	v_mov_b32_e32 v240, v198
	s_nop 1
	v_permlane16_swap_b32_e32 v198, v240
	v_add_f32_e32 v240, v198, v240
	v_mov_b32_e32 v241, v240
	s_nop 1
	v_permlane32_swap_b32_e32 v240, v241
	v_add_f32_e32 v240, v240, v241
	v_mov_b32_e32 v233, v240
	s_waitcnt vmcnt(33)
	s_add_u32 s10, s10, 0x10000
	s_addc_u32 s11, s11, 0
	s_add_u32 s98, s98, 0x8000
	s_addc_u32 s99, s99, 0
	s_add_u32 s66, s66, 0x400
	s_addc_u32 s67, s67, 0
	v_pk_add_f32 v[242:243], v[242:243], v[180:181]
	v_pk_add_f32 v[244:245], v[244:245], v[182:183]
	v_pk_add_f32 v[172:173], v[172:173], v[100:101]
	v_pk_add_f32 v[174:175], v[174:175], v[102:103]
	v_pk_fma_f32 v[52:53], v[52:53], v[60:61], v[242:243]
	v_pk_fma_f32 v[54:55], v[54:55], v[62:63], v[244:245]
	v_pk_fma_f32 v[48:49], v[48:49], v[56:57], v[172:173]
	v_pk_fma_f32 v[50:51], v[50:51], v[58:59], v[174:175]
	global_store_dwordx4 v219, v[52:55], s[10:11] offset:0
	global_store_dwordx4 v219, v[48:51], s[10:11] offset:16
	v_mul_f32_e32 v198, v52, v52
	v_fmac_f32_e32 v198, v53, v53
	v_fmac_f32_e32 v198, v54, v54
	v_fmac_f32_e32 v198, v55, v55
	v_fmac_f32_e32 v198, v48, v48
	v_fmac_f32_e32 v198, v49, v49
	v_fmac_f32_e32 v198, v50, v50
	v_fmac_f32_e32 v198, v51, v51
	v_pk_mul_f32 v[242:243], v[144:145], v[52:53]
	v_pk_mul_f32 v[244:245], v[146:147], v[54:55]
	v_pk_mul_f32 v[172:173], v[148:149], v[48:49]
	v_pk_mul_f32 v[174:175], v[150:151], v[50:51]
	v_cvt_pk_bf16_f32 v242, v242, v243
	v_cvt_pk_bf16_f32 v243, v244, v245
	v_cvt_pk_bf16_f32 v244, v172, v173
	v_cvt_pk_bf16_f32 v245, v174, v175
	global_store_dwordx4 v220, v[242:245], s[98:99] offset:0
	s_waitcnt vmcnt(29)
	v_pk_add_f32 v[96:97], v[96:97], v[124:125]
	v_pk_add_f32 v[98:99], v[98:99], v[126:127]
	v_pk_add_f32 v[128:129], v[128:129], v[120:121]
	v_pk_add_f32 v[130:131], v[130:131], v[122:123]
	v_pk_fma_f32 v[36:37], v[36:37], v[44:45], v[96:97]
	v_pk_fma_f32 v[38:39], v[38:39], v[46:47], v[98:99]
	v_pk_fma_f32 v[32:33], v[32:33], v[40:41], v[128:129]
	v_pk_fma_f32 v[34:35], v[34:35], v[42:43], v[130:131]
	global_store_dwordx4 v219, v[36:39], s[10:11] offset:512
	global_store_dwordx4 v219, v[32:35], s[10:11] offset:528
	v_fmac_f32_e32 v198, v36, v36
	v_fmac_f32_e32 v198, v37, v37
	v_fmac_f32_e32 v198, v38, v38
	v_fmac_f32_e32 v198, v39, v39
	v_fmac_f32_e32 v198, v32, v32
	v_fmac_f32_e32 v198, v33, v33
	v_fmac_f32_e32 v198, v34, v34
	v_fmac_f32_e32 v198, v35, v35
	v_pk_mul_f32 v[96:97], v[152:153], v[36:37]
	v_pk_mul_f32 v[98:99], v[154:155], v[38:39]
	v_pk_mul_f32 v[128:129], v[156:157], v[32:33]
	v_pk_mul_f32 v[130:131], v[158:159], v[34:35]
	v_cvt_pk_bf16_f32 v96, v96, v97
	v_cvt_pk_bf16_f32 v97, v98, v99
	v_cvt_pk_bf16_f32 v98, v128, v129
	v_cvt_pk_bf16_f32 v99, v130, v131
	global_store_dwordx4 v220, v[96:99], s[98:99] offset:256
	v_mov_b32_e32 v240, v198
	s_nop 1
	v_permlane16_swap_b32_e32 v198, v240
	v_add_f32_e32 v240, v198, v240
	v_mov_b32_e32 v241, v240
	s_nop 1
	v_permlane32_swap_b32_e32 v240, v241
	v_add_f32_e32 v240, v240, v241
	v_cmp_eq_u32_e64 s[6:7], 1, v236
	s_nop 1
	v_cndmask_b32_e64 v233, v233, v240, s[6:7]
	s_waitcnt vmcnt(28)
	s_add_u32 s10, s10, 0x10000
	s_addc_u32 s11, s11, 0
	s_add_u32 s98, s98, 0x8000
	s_addc_u32 s99, s99, 0
	s_add_u32 s66, s66, 0x400
	s_addc_u32 s67, s67, 0
	v_pk_add_f32 v[168:169], v[168:169], v[88:89]
	v_pk_add_f32 v[170:171], v[170:171], v[90:91]
	v_pk_add_f32 v[92:93], v[92:93], v[224:225]
	v_pk_add_f32 v[94:95], v[94:95], v[226:227]
	v_pk_fma_f32 v[28:29], v[28:29], v[60:61], v[168:169]
	v_pk_fma_f32 v[30:31], v[30:31], v[62:63], v[170:171]
	v_pk_fma_f32 v[24:25], v[24:25], v[56:57], v[92:93]
	v_pk_fma_f32 v[26:27], v[26:27], v[58:59], v[94:95]
	global_store_dwordx4 v219, v[28:31], s[10:11] offset:0
	global_store_dwordx4 v219, v[24:27], s[10:11] offset:16
	v_mul_f32_e32 v198, v28, v28
	v_fmac_f32_e32 v198, v29, v29
	v_fmac_f32_e32 v198, v30, v30
	v_fmac_f32_e32 v198, v31, v31
	v_fmac_f32_e32 v198, v24, v24
	v_fmac_f32_e32 v198, v25, v25
	v_fmac_f32_e32 v198, v26, v26
	v_fmac_f32_e32 v198, v27, v27
	v_pk_mul_f32 v[168:169], v[144:145], v[28:29]
	v_pk_mul_f32 v[170:171], v[146:147], v[30:31]
	v_pk_mul_f32 v[92:93], v[148:149], v[24:25]
	v_pk_mul_f32 v[94:95], v[150:151], v[26:27]
	v_cvt_pk_bf16_f32 v168, v168, v169
	v_cvt_pk_bf16_f32 v169, v170, v171
	v_cvt_pk_bf16_f32 v170, v92, v93
	v_cvt_pk_bf16_f32 v171, v94, v95
	global_store_dwordx4 v220, v[168:171], s[98:99] offset:0
	s_waitcnt vmcnt(23)
	v_pk_add_f32 v[136:137], v[136:137], v[116:117]
	v_pk_add_f32 v[138:139], v[138:139], v[118:119]
	v_pk_add_f32 v[176:177], v[176:177], v[84:85]
	v_pk_add_f32 v[178:179], v[178:179], v[86:87]
	v_pk_fma_f32 v[20:21], v[20:21], v[44:45], v[136:137]
	v_pk_fma_f32 v[22:23], v[22:23], v[46:47], v[138:139]
	v_pk_fma_f32 v[16:17], v[16:17], v[40:41], v[176:177]
	v_pk_fma_f32 v[18:19], v[18:19], v[42:43], v[178:179]
	global_store_dwordx4 v219, v[20:23], s[10:11] offset:512
	global_store_dwordx4 v219, v[16:19], s[10:11] offset:528
	v_fmac_f32_e32 v198, v20, v20
	v_fmac_f32_e32 v198, v21, v21
	v_fmac_f32_e32 v198, v22, v22
	v_fmac_f32_e32 v198, v23, v23
	v_fmac_f32_e32 v198, v16, v16
	v_fmac_f32_e32 v198, v17, v17
	v_fmac_f32_e32 v198, v18, v18
	v_fmac_f32_e32 v198, v19, v19
	v_pk_mul_f32 v[136:137], v[152:153], v[20:21]
	v_pk_mul_f32 v[138:139], v[154:155], v[22:23]
	v_pk_mul_f32 v[176:177], v[156:157], v[16:17]
	v_pk_mul_f32 v[178:179], v[158:159], v[18:19]
	v_cvt_pk_bf16_f32 v136, v136, v137
	v_cvt_pk_bf16_f32 v137, v138, v139
	v_cvt_pk_bf16_f32 v138, v176, v177
	v_cvt_pk_bf16_f32 v139, v178, v179
	global_store_dwordx4 v220, v[136:139], s[98:99] offset:256
	v_mov_b32_e32 v240, v198
	s_nop 1
	v_permlane16_swap_b32_e32 v198, v240
	v_add_f32_e32 v240, v198, v240
	v_mov_b32_e32 v241, v240
	s_nop 1
	v_permlane32_swap_b32_e32 v240, v241
	v_add_f32_e32 v240, v240, v241
	v_cmp_eq_u32_e64 s[6:7], 2, v236
	s_nop 1
	v_cndmask_b32_e64 v233, v233, v240, s[6:7]
	s_waitcnt vmcnt(19)
	s_add_u32 s10, s10, 0x10000
	s_addc_u32 s11, s11, 0
	s_add_u32 s98, s98, 0x8000
	s_addc_u32 s99, s99, 0
	s_add_u32 s66, s66, 0x400
	s_addc_u32 s67, s67, 0
	v_pk_add_f32 v[80:81], v[80:81], v[228:229]
	v_pk_add_f32 v[82:83], v[82:83], v[230:231]
	v_pk_add_f32 v[140:141], v[140:141], v[160:161]
	v_pk_add_f32 v[142:143], v[142:143], v[162:163]
	v_pk_fma_f32 v[12:13], v[12:13], v[60:61], v[80:81]
	v_pk_fma_f32 v[14:15], v[14:15], v[62:63], v[82:83]
	v_pk_fma_f32 v[8:9], v[8:9], v[56:57], v[140:141]
	v_pk_fma_f32 v[10:11], v[10:11], v[58:59], v[142:143]
	global_store_dwordx4 v219, v[12:15], s[10:11] offset:0
	global_store_dwordx4 v219, v[8:11], s[10:11] offset:16
	v_mul_f32_e32 v198, v12, v12
	v_fmac_f32_e32 v198, v13, v13
	v_fmac_f32_e32 v198, v14, v14
	v_fmac_f32_e32 v198, v15, v15
	v_fmac_f32_e32 v198, v8, v8
	v_fmac_f32_e32 v198, v9, v9
	v_fmac_f32_e32 v198, v10, v10
	v_fmac_f32_e32 v198, v11, v11
	v_pk_mul_f32 v[80:81], v[144:145], v[12:13]
	v_pk_mul_f32 v[82:83], v[146:147], v[14:15]
	v_pk_mul_f32 v[140:141], v[148:149], v[8:9]
	v_pk_mul_f32 v[142:143], v[150:151], v[10:11]
	v_cvt_pk_bf16_f32 v80, v80, v81
	v_cvt_pk_bf16_f32 v81, v82, v83
	v_cvt_pk_bf16_f32 v82, v140, v141
	v_cvt_pk_bf16_f32 v83, v142, v143
	global_store_dwordx4 v220, v[80:83], s[98:99] offset:0
	s_waitcnt vmcnt(18)
	v_pk_add_f32 v[164:165], v[164:165], v[72:73]
	v_pk_add_f32 v[166:167], v[166:167], v[74:75]
	v_pk_add_f32 v[76:77], v[76:77], v[112:113]
	v_pk_add_f32 v[78:79], v[78:79], v[114:115]
	v_pk_fma_f32 v[4:5], v[4:5], v[44:45], v[164:165]
	v_pk_fma_f32 v[6:7], v[6:7], v[46:47], v[166:167]
	v_pk_fma_f32 v[0:1], v[0:1], v[40:41], v[76:77]
	v_pk_fma_f32 v[2:3], v[2:3], v[42:43], v[78:79]
	global_store_dwordx4 v219, v[4:7], s[10:11] offset:512
	global_store_dwordx4 v219, v[0:3], s[10:11] offset:528
	v_fmac_f32_e32 v198, v4, v4
	v_fmac_f32_e32 v198, v5, v5
	v_fmac_f32_e32 v198, v6, v6
	v_fmac_f32_e32 v198, v7, v7
	v_fmac_f32_e32 v198, v0, v0
	v_fmac_f32_e32 v198, v1, v1
	v_fmac_f32_e32 v198, v2, v2
	v_fmac_f32_e32 v198, v3, v3
	v_pk_mul_f32 v[164:165], v[152:153], v[4:5]
	v_pk_mul_f32 v[166:167], v[154:155], v[6:7]
	v_pk_mul_f32 v[76:77], v[156:157], v[0:1]
	v_pk_mul_f32 v[78:79], v[158:159], v[2:3]
	v_cvt_pk_bf16_f32 v164, v164, v165
	v_cvt_pk_bf16_f32 v165, v166, v167
	v_cvt_pk_bf16_f32 v166, v76, v77
	v_cvt_pk_bf16_f32 v167, v78, v79
	global_store_dwordx4 v220, v[164:167], s[98:99] offset:256
	v_mov_b32_e32 v240, v198
	s_nop 1
	v_permlane16_swap_b32_e32 v198, v240
	v_add_f32_e32 v240, v198, v240
	v_mov_b32_e32 v241, v240
	s_nop 1
	v_permlane32_swap_b32_e32 v240, v241
	v_add_f32_e32 v240, v240, v241
	v_cmp_eq_u32_e64 s[6:7], 3, v236
	s_nop 1
	v_cndmask_b32_e64 v233, v233, v240, s[6:7]
	global_store_dword v222, v233, s[66:67] offset:-3072
	s_branch .Lepo_done
.Lepo_half:
	s_cmp_lt_i32 s6, 32
	s_cbranch_scc1 .Lepo_ctx_lo
	s_cmp_lt_i32 s66, 2
	s_cbranch_scc1 .Lepo_per_lo
.Lepo_pec_lo:
	s_lshl_b32 s8, s66, 4
	s_lshl_b32 s9, s75, 2
	s_add_i32 s8, s8, s9
	s_lshl_b32 s9, s24, 6
	s_add_i32 s8, s8, s9
	s_add_i32 s8, s8, 0xea9a000
	s_add_u32 s66, s58, s8
	s_addc_u32 s67, s59, 0
	s_sub_i32 s8, s6, 32
	s_ashr_i32 s8, s8, 3
	s_add_i32 s8, s8, 1
	s_mul_i32 s8, s8, 0x6000
	s_add_i32 s8, s8, 0xe802000
	s_add_u32 s8, s58, s8
	s_addc_u32 s9, s59, 0
	global_load_dwordx4 v[60:63], v218, s[8:9] offset:0
	global_load_dwordx4 v[56:59], v218, s[8:9] offset:16
	global_load_dwordx4 v[44:47], v218, s[8:9] offset:512
	global_load_dwordx4 v[40:43], v218, s[8:9] offset:528
	s_add_u32 s8, s8, 0x2000
	s_addc_u32 s9, s9, 0
	global_load_dwordx4 v[144:147], v218, s[8:9] offset:0
	global_load_dwordx4 v[148:151], v218, s[8:9] offset:16
	global_load_dwordx4 v[152:155], v218, s[8:9] offset:512
	global_load_dwordx4 v[156:159], v218, s[8:9] offset:528
	global_load_dwordx4 v[160:163], v218, s[18:19] offset:0
	global_load_dwordx4 v[164:167], v218, s[18:19] offset:16
	global_load_dwordx4 v[168:171], v218, s[18:19] offset:512
	global_load_dwordx4 v[172:175], v218, s[18:19] offset:528
	s_sub_i32 s8, s24, 0x2000
	s_lshl_b32 s8, s8, 12
	s_add_u32 s8, s14, s8
	s_addc_u32 s9, s15, 0
	s_add_u32 s100, s58, 0xe8fa000
	s_addc_u32 s101, s59, 0
	v_lshlrev_b32_e32 v221, 11, v235
	v_add_u32_e32 v221, v221, v218
	v_add_u32_e32 v221, 0xfffff800, v221
	global_load_dwordx4 v[176:179], v219, s[8:9] offset:0
	global_load_dwordx4 v[180:183], v219, s[8:9] offset:16
	global_load_dwordx4 v[224:227], v221, s[100:101] offset:0
	global_load_dwordx4 v[228:231], v221, s[100:101] offset:16
	s_waitcnt vmcnt(4)
	v_pk_add_f32 v[144:145], v[144:145], 1.0 op_sel_hi:[1,0]
	v_pk_add_f32 v[146:147], v[146:147], 1.0 op_sel_hi:[1,0]
	v_pk_add_f32 v[148:149], v[148:149], 1.0 op_sel_hi:[1,0]
	v_pk_add_f32 v[150:151], v[150:151], 1.0 op_sel_hi:[1,0]
	v_pk_add_f32 v[152:153], v[152:153], 1.0 op_sel_hi:[1,0]
	v_pk_add_f32 v[154:155], v[154:155], 1.0 op_sel_hi:[1,0]
	v_pk_add_f32 v[156:157], v[156:157], 1.0 op_sel_hi:[1,0]
	v_pk_add_f32 v[158:159], v[158:159], 1.0 op_sel_hi:[1,0]
	v_pk_mul_f32 v[144:145], v[160:161], v[144:145]
	v_pk_mul_f32 v[146:147], v[162:163], v[146:147]
	v_pk_mul_f32 v[148:149], v[164:165], v[148:149]
	v_pk_mul_f32 v[150:151], v[166:167], v[150:151]
	v_pk_mul_f32 v[152:153], v[168:169], v[152:153]
	v_pk_mul_f32 v[154:155], v[170:171], v[154:155]
	v_pk_mul_f32 v[156:157], v[172:173], v[156:157]
	v_pk_mul_f32 v[158:159], v[174:175], v[158:159]
	global_load_dwordx4 v[242:245], v219, s[8:9] offset:512
	global_load_dwordx4 v[246:249], v219, s[8:9] offset:528
	global_load_dwordx4 v[160:163], v221, s[100:101] offset:512
	global_load_dwordx4 v[164:167], v221, s[100:101] offset:528
	s_waitcnt vmcnt(4)
	v_pk_add_f32 v[176:177], v[176:177], v[224:225]
	v_pk_add_f32 v[178:179], v[178:179], v[226:227]
	v_pk_add_f32 v[180:181], v[180:181], v[228:229]
	v_pk_add_f32 v[182:183], v[182:183], v[230:231]
	v_pk_fma_f32 v[140:141], v[140:141], v[60:61], v[176:177]
	v_pk_fma_f32 v[142:143], v[142:143], v[62:63], v[178:179]
	v_pk_fma_f32 v[136:137], v[136:137], v[56:57], v[180:181]
	v_pk_fma_f32 v[138:139], v[138:139], v[58:59], v[182:183]
	global_store_dwordx4 v219, v[140:143], s[10:11] offset:0
	global_store_dwordx4 v219, v[136:139], s[10:11] offset:16
	v_mul_f32_e32 v198, v140, v140
	v_fmac_f32_e32 v198, v141, v141
	v_fmac_f32_e32 v198, v142, v142
	v_fmac_f32_e32 v198, v143, v143
	v_fmac_f32_e32 v198, v136, v136
	v_fmac_f32_e32 v198, v137, v137
	v_fmac_f32_e32 v198, v138, v138
	v_fmac_f32_e32 v198, v139, v139
	v_pk_mul_f32 v[176:177], v[144:145], v[140:141]
	v_pk_mul_f32 v[178:179], v[146:147], v[142:143]
	v_pk_mul_f32 v[180:181], v[148:149], v[136:137]
	v_pk_mul_f32 v[182:183], v[150:151], v[138:139]
	v_cvt_pk_bf16_f32 v176, v176, v177
	v_cvt_pk_bf16_f32 v177, v178, v179
	v_cvt_pk_bf16_f32 v178, v180, v181
	v_cvt_pk_bf16_f32 v179, v182, v183
	global_store_dwordx4 v220, v[176:179], s[98:99] offset:0
	s_add_u32 s8, s8, 0x10000
	s_addc_u32 s9, s9, 0
	s_add_u32 s100, s100, 0x8000
	s_addc_u32 s101, s101, 0
	global_load_dwordx4 v[168:171], v219, s[8:9] offset:0
	global_load_dwordx4 v[172:175], v219, s[8:9] offset:16
	global_load_dwordx4 v[180:183], v221, s[100:101] offset:0
	global_load_dwordx4 v[224:227], v221, s[100:101] offset:16
	global_load_dwordx4 v[228:231], v219, s[8:9] offset:512
	global_load_dwordx4 v[140:143], v219, s[8:9] offset:528
	global_load_dwordx4 v[136:139], v221, s[100:101] offset:512
	global_load_dwordx4 v[176:179], v221, s[100:101] offset:528
	s_waitcnt vmcnt(11)
	v_pk_add_f32 v[242:243], v[242:243], v[160:161]
	v_pk_add_f32 v[244:245], v[244:245], v[162:163]
	v_pk_add_f32 v[246:247], v[246:247], v[164:165]
	v_pk_add_f32 v[248:249], v[248:249], v[166:167]
	v_pk_fma_f32 v[132:133], v[132:133], v[44:45], v[242:243]
	v_pk_fma_f32 v[134:135], v[134:135], v[46:47], v[244:245]
	v_pk_fma_f32 v[128:129], v[128:129], v[40:41], v[246:247]
	v_pk_fma_f32 v[130:131], v[130:131], v[42:43], v[248:249]
	global_store_dwordx4 v219, v[132:135], s[10:11] offset:512
	global_store_dwordx4 v219, v[128:131], s[10:11] offset:528
	v_fmac_f32_e32 v198, v132, v132
	v_fmac_f32_e32 v198, v133, v133
	v_fmac_f32_e32 v198, v134, v134
	v_fmac_f32_e32 v198, v135, v135
	v_fmac_f32_e32 v198, v128, v128
	v_fmac_f32_e32 v198, v129, v129
	v_fmac_f32_e32 v198, v130, v130
	v_fmac_f32_e32 v198, v131, v131
	v_pk_mul_f32 v[242:243], v[152:153], v[132:133]
	v_pk_mul_f32 v[244:245], v[154:155], v[134:135]
	v_pk_mul_f32 v[246:247], v[156:157], v[128:129]
	v_pk_mul_f32 v[248:249], v[158:159], v[130:131]
	v_cvt_pk_bf16_f32 v242, v242, v243
	v_cvt_pk_bf16_f32 v243, v244, v245
	v_cvt_pk_bf16_f32 v244, v246, v247
	v_cvt_pk_bf16_f32 v245, v248, v249
	global_store_dwordx4 v220, v[242:245], s[98:99] offset:256
	v_mov_b32_e32 v240, v198
	s_nop 1
	v_permlane16_swap_b32_e32 v198, v240
	v_add_f32_e32 v240, v198, v240
	v_mov_b32_e32 v241, v240
	s_nop 1
	v_permlane32_swap_b32_e32 v240, v241
	v_add_f32_e32 v240, v240, v241
	v_mov_b32_e32 v233, v240
	s_add_u32 s8, s8, 0x10000
	s_addc_u32 s9, s9, 0
	s_add_u32 s100, s100, 0x8000
	s_addc_u32 s101, s101, 0
	global_load_dwordx4 v[246:249], v219, s[8:9] offset:0
	global_load_dwordx4 v[160:163], v219, s[8:9] offset:16
	global_load_dwordx4 v[164:167], v221, s[100:101] offset:0
	global_load_dwordx4 v[132:135], v221, s[100:101] offset:16
	s_waitcnt vmcnt(11)
	s_add_u32 s10, s10, 0x10000
	s_addc_u32 s11, s11, 0
	s_add_u32 s98, s98, 0x8000
	s_addc_u32 s99, s99, 0
	s_add_u32 s66, s66, 0x400
	s_addc_u32 s67, s67, 0
	v_pk_add_f32 v[168:169], v[168:169], v[180:181]
	v_pk_add_f32 v[170:171], v[170:171], v[182:183]
	v_pk_add_f32 v[172:173], v[172:173], v[224:225]
	v_pk_add_f32 v[174:175], v[174:175], v[226:227]
	v_pk_fma_f32 v[124:125], v[124:125], v[60:61], v[168:169]
	v_pk_fma_f32 v[126:127], v[126:127], v[62:63], v[170:171]
	v_pk_fma_f32 v[120:121], v[120:121], v[56:57], v[172:173]
	v_pk_fma_f32 v[122:123], v[122:123], v[58:59], v[174:175]
	global_store_dwordx4 v219, v[124:127], s[10:11] offset:0
	global_store_dwordx4 v219, v[120:123], s[10:11] offset:16
	v_mul_f32_e32 v198, v124, v124
	v_fmac_f32_e32 v198, v125, v125
	v_fmac_f32_e32 v198, v126, v126
	v_fmac_f32_e32 v198, v127, v127
	v_fmac_f32_e32 v198, v120, v120
	v_fmac_f32_e32 v198, v121, v121
	v_fmac_f32_e32 v198, v122, v122
	v_fmac_f32_e32 v198, v123, v123
	v_pk_mul_f32 v[168:169], v[144:145], v[124:125]
	v_pk_mul_f32 v[170:171], v[146:147], v[126:127]
	v_pk_mul_f32 v[172:173], v[148:149], v[120:121]
	v_pk_mul_f32 v[174:175], v[150:151], v[122:123]
	v_cvt_pk_bf16_f32 v168, v168, v169
	v_cvt_pk_bf16_f32 v169, v170, v171
	v_cvt_pk_bf16_f32 v170, v172, v173
	v_cvt_pk_bf16_f32 v171, v174, v175
	global_store_dwordx4 v220, v[168:171], s[98:99] offset:0
	global_load_dwordx4 v[128:131], v219, s[8:9] offset:512
	global_load_dwordx4 v[242:245], v219, s[8:9] offset:528
	global_load_dwordx4 v[172:175], v221, s[100:101] offset:512
	global_load_dwordx4 v[180:183], v221, s[100:101] offset:528
	s_add_u32 s8, s8, 0x10000
	s_addc_u32 s9, s9, 0
	s_add_u32 s100, s100, 0x8000
	s_addc_u32 s101, s101, 0
	global_load_dwordx4 v[224:227], v219, s[8:9] offset:0
	global_load_dwordx4 v[124:127], v219, s[8:9] offset:16
	global_load_dwordx4 v[120:123], v221, s[100:101] offset:0
	global_load_dwordx4 v[168:171], v221, s[100:101] offset:16
	s_waitcnt vmcnt(18)
	v_pk_add_f32 v[228:229], v[228:229], v[136:137]
	v_pk_add_f32 v[230:231], v[230:231], v[138:139]
	v_pk_add_f32 v[140:141], v[140:141], v[176:177]
	v_pk_add_f32 v[142:143], v[142:143], v[178:179]
	v_pk_fma_f32 v[116:117], v[116:117], v[44:45], v[228:229]
	v_pk_fma_f32 v[118:119], v[118:119], v[46:47], v[230:231]
	v_pk_fma_f32 v[112:113], v[112:113], v[40:41], v[140:141]
	v_pk_fma_f32 v[114:115], v[114:115], v[42:43], v[142:143]
	global_store_dwordx4 v219, v[116:119], s[10:11] offset:512
	global_store_dwordx4 v219, v[112:115], s[10:11] offset:528
	v_fmac_f32_e32 v198, v116, v116
	v_fmac_f32_e32 v198, v117, v117
	v_fmac_f32_e32 v198, v118, v118
	v_fmac_f32_e32 v198, v119, v119
	v_fmac_f32_e32 v198, v112, v112
	v_fmac_f32_e32 v198, v113, v113
	v_fmac_f32_e32 v198, v114, v114
	v_fmac_f32_e32 v198, v115, v115
	v_pk_mul_f32 v[228:229], v[152:153], v[116:117]
	v_pk_mul_f32 v[230:231], v[154:155], v[118:119]
	v_pk_mul_f32 v[140:141], v[156:157], v[112:113]
	v_pk_mul_f32 v[142:143], v[158:159], v[114:115]
	v_cvt_pk_bf16_f32 v228, v228, v229
	v_cvt_pk_bf16_f32 v229, v230, v231
	v_cvt_pk_bf16_f32 v230, v140, v141
	v_cvt_pk_bf16_f32 v231, v142, v143
	global_store_dwordx4 v220, v[228:231], s[98:99] offset:256
	v_mov_b32_e32 v240, v198
	s_nop 1
	v_permlane16_swap_b32_e32 v198, v240
	v_add_f32_e32 v240, v198, v240
	v_mov_b32_e32 v241, v240
	s_nop 1
	v_permlane32_swap_b32_e32 v240, v241
	v_add_f32_e32 v240, v240, v241
	v_cmp_eq_u32_e64 s[6:7], 1, v236
	s_nop 1
	v_cndmask_b32_e64 v233, v233, v240, s[6:7]
	global_load_dwordx4 v[140:143], v219, s[8:9] offset:512
	global_load_dwordx4 v[136:139], v219, s[8:9] offset:528
	global_load_dwordx4 v[176:179], v221, s[100:101] offset:512
	global_load_dwordx4 v[116:119], v221, s[100:101] offset:528
	s_waitcnt vmcnt(18)
	s_add_u32 s10, s10, 0x10000
	s_addc_u32 s11, s11, 0
	s_add_u32 s98, s98, 0x8000
	s_addc_u32 s99, s99, 0
	s_add_u32 s66, s66, 0x400
	s_addc_u32 s67, s67, 0
	v_pk_add_f32 v[246:247], v[246:247], v[164:165]
	v_pk_add_f32 v[248:249], v[248:249], v[166:167]
	v_pk_add_f32 v[160:161], v[160:161], v[132:133]
	v_pk_add_f32 v[162:163], v[162:163], v[134:135]
	v_pk_fma_f32 v[108:109], v[108:109], v[60:61], v[246:247]
	v_pk_fma_f32 v[110:111], v[110:111], v[62:63], v[248:249]
	v_pk_fma_f32 v[104:105], v[104:105], v[56:57], v[160:161]
	v_pk_fma_f32 v[106:107], v[106:107], v[58:59], v[162:163]
	global_store_dwordx4 v219, v[108:111], s[10:11] offset:0
	global_store_dwordx4 v219, v[104:107], s[10:11] offset:16
	v_mul_f32_e32 v198, v108, v108
	v_fmac_f32_e32 v198, v109, v109
	v_fmac_f32_e32 v198, v110, v110
	v_fmac_f32_e32 v198, v111, v111
	v_fmac_f32_e32 v198, v104, v104
	v_fmac_f32_e32 v198, v105, v105
	v_fmac_f32_e32 v198, v106, v106
	v_fmac_f32_e32 v198, v107, v107
	v_pk_mul_f32 v[246:247], v[144:145], v[108:109]
	v_pk_mul_f32 v[248:249], v[146:147], v[110:111]
	v_pk_mul_f32 v[160:161], v[148:149], v[104:105]
	v_pk_mul_f32 v[162:163], v[150:151], v[106:107]
	v_cvt_pk_bf16_f32 v246, v246, v247
	v_cvt_pk_bf16_f32 v247, v248, v249
	v_cvt_pk_bf16_f32 v248, v160, v161
	v_cvt_pk_bf16_f32 v249, v162, v163
	global_store_dwordx4 v220, v[246:249], s[98:99] offset:0
	s_waitcnt vmcnt(14)
	v_pk_add_f32 v[128:129], v[128:129], v[172:173]
	v_pk_add_f32 v[130:131], v[130:131], v[174:175]
	v_pk_add_f32 v[242:243], v[242:243], v[180:181]
	v_pk_add_f32 v[244:245], v[244:245], v[182:183]
	v_pk_fma_f32 v[100:101], v[100:101], v[44:45], v[128:129]
	v_pk_fma_f32 v[102:103], v[102:103], v[46:47], v[130:131]
	v_pk_fma_f32 v[96:97], v[96:97], v[40:41], v[242:243]
	v_pk_fma_f32 v[98:99], v[98:99], v[42:43], v[244:245]
	global_store_dwordx4 v219, v[100:103], s[10:11] offset:512
	global_store_dwordx4 v219, v[96:99], s[10:11] offset:528
	v_fmac_f32_e32 v198, v100, v100
	v_fmac_f32_e32 v198, v101, v101
	v_fmac_f32_e32 v198, v102, v102
	v_fmac_f32_e32 v198, v103, v103
	v_fmac_f32_e32 v198, v96, v96
	v_fmac_f32_e32 v198, v97, v97
	v_fmac_f32_e32 v198, v98, v98
	v_fmac_f32_e32 v198, v99, v99
	v_pk_mul_f32 v[128:129], v[152:153], v[100:101]
	v_pk_mul_f32 v[130:131], v[154:155], v[102:103]
	v_pk_mul_f32 v[242:243], v[156:157], v[96:97]
	v_pk_mul_f32 v[244:245], v[158:159], v[98:99]
	v_cvt_pk_bf16_f32 v128, v128, v129
	v_cvt_pk_bf16_f32 v129, v130, v131
	v_cvt_pk_bf16_f32 v130, v242, v243
	v_cvt_pk_bf16_f32 v131, v244, v245
	global_store_dwordx4 v220, v[128:131], s[98:99] offset:256
	v_mov_b32_e32 v240, v198
	s_nop 1
	v_permlane16_swap_b32_e32 v198, v240
	v_add_f32_e32 v240, v198, v240
	v_mov_b32_e32 v241, v240
	s_nop 1
	v_permlane32_swap_b32_e32 v240, v241
	v_add_f32_e32 v240, v240, v241
	v_cmp_eq_u32_e64 s[6:7], 2, v236
	s_nop 1
	v_cndmask_b32_e64 v233, v233, v240, s[6:7]
	s_waitcnt vmcnt(13)
	s_add_u32 s10, s10, 0x10000
	s_addc_u32 s11, s11, 0
	s_add_u32 s98, s98, 0x8000
	s_addc_u32 s99, s99, 0
	s_add_u32 s66, s66, 0x400
	s_addc_u32 s67, s67, 0
	v_pk_add_f32 v[224:225], v[224:225], v[120:121]
	v_pk_add_f32 v[226:227], v[226:227], v[122:123]
	v_pk_add_f32 v[124:125], v[124:125], v[168:169]
	v_pk_add_f32 v[126:127], v[126:127], v[170:171]
	v_pk_fma_f32 v[92:93], v[92:93], v[60:61], v[224:225]
	v_pk_fma_f32 v[94:95], v[94:95], v[62:63], v[226:227]
	v_pk_fma_f32 v[88:89], v[88:89], v[56:57], v[124:125]
	v_pk_fma_f32 v[90:91], v[90:91], v[58:59], v[126:127]
	global_store_dwordx4 v219, v[92:95], s[10:11] offset:0
	global_store_dwordx4 v219, v[88:91], s[10:11] offset:16
	v_mul_f32_e32 v198, v92, v92
	v_fmac_f32_e32 v198, v93, v93
	v_fmac_f32_e32 v198, v94, v94
	v_fmac_f32_e32 v198, v95, v95
	v_fmac_f32_e32 v198, v88, v88
	v_fmac_f32_e32 v198, v89, v89
	v_fmac_f32_e32 v198, v90, v90
	v_fmac_f32_e32 v198, v91, v91
	v_pk_mul_f32 v[224:225], v[144:145], v[92:93]
	v_pk_mul_f32 v[226:227], v[146:147], v[94:95]
	v_pk_mul_f32 v[124:125], v[148:149], v[88:89]
	v_pk_mul_f32 v[126:127], v[150:151], v[90:91]
	v_cvt_pk_bf16_f32 v224, v224, v225
	v_cvt_pk_bf16_f32 v225, v226, v227
	v_cvt_pk_bf16_f32 v226, v124, v125
	v_cvt_pk_bf16_f32 v227, v126, v127
	global_store_dwordx4 v220, v[224:227], s[98:99] offset:0
	s_waitcnt vmcnt(9)
	v_pk_add_f32 v[140:141], v[140:141], v[176:177]
	v_pk_add_f32 v[142:143], v[142:143], v[178:179]
	v_pk_add_f32 v[136:137], v[136:137], v[116:117]
	v_pk_add_f32 v[138:139], v[138:139], v[118:119]
	v_pk_fma_f32 v[84:85], v[84:85], v[44:45], v[140:141]
	v_pk_fma_f32 v[86:87], v[86:87], v[46:47], v[142:143]
	v_pk_fma_f32 v[80:81], v[80:81], v[40:41], v[136:137]
	v_pk_fma_f32 v[82:83], v[82:83], v[42:43], v[138:139]
	global_store_dwordx4 v219, v[84:87], s[10:11] offset:512
	global_store_dwordx4 v219, v[80:83], s[10:11] offset:528
	v_fmac_f32_e32 v198, v84, v84
	v_fmac_f32_e32 v198, v85, v85
	v_fmac_f32_e32 v198, v86, v86
	v_fmac_f32_e32 v198, v87, v87
	v_fmac_f32_e32 v198, v80, v80
	v_fmac_f32_e32 v198, v81, v81
	v_fmac_f32_e32 v198, v82, v82
	v_fmac_f32_e32 v198, v83, v83
	v_pk_mul_f32 v[140:141], v[152:153], v[84:85]
	v_pk_mul_f32 v[142:143], v[154:155], v[86:87]
	v_pk_mul_f32 v[136:137], v[156:157], v[80:81]
	v_pk_mul_f32 v[138:139], v[158:159], v[82:83]
	v_cvt_pk_bf16_f32 v140, v140, v141
	v_cvt_pk_bf16_f32 v141, v142, v143
	v_cvt_pk_bf16_f32 v142, v136, v137
	v_cvt_pk_bf16_f32 v143, v138, v139
	global_store_dwordx4 v220, v[140:143], s[98:99] offset:256
	v_mov_b32_e32 v240, v198
	s_nop 1
	v_permlane16_swap_b32_e32 v198, v240
	v_add_f32_e32 v240, v198, v240
	v_mov_b32_e32 v241, v240
	s_nop 1
	v_permlane32_swap_b32_e32 v240, v241
	v_add_f32_e32 v240, v240, v241
	v_cmp_eq_u32_e64 s[6:7], 3, v236
	s_nop 1
	v_cndmask_b32_e64 v233, v233, v240, s[6:7]
	global_store_dword v222, v233, s[66:67] offset:-3072
	s_branch .Lepo_done
.Lepo_per_lo:
	s_lshl_b32 s8, s66, 4
	s_lshl_b32 s9, s75, 2
	s_add_i32 s8, s8, s9
	s_lshl_b32 s9, s24, 6
	s_add_i32 s8, s8, s9
	s_add_i32 s8, s8, 0xea9a000
	s_add_u32 s66, s58, s8
	s_addc_u32 s67, s59, 0
	s_sub_i32 s8, s6, 32
	s_ashr_i32 s8, s8, 3
	s_add_i32 s8, s8, 1
	s_mul_i32 s8, s8, 0x6000
	s_add_i32 s8, s8, 0xe802000
	s_add_u32 s8, s58, s8
	s_addc_u32 s9, s59, 0
	global_load_dwordx4 v[60:63], v218, s[8:9] offset:0
	global_load_dwordx4 v[56:59], v218, s[8:9] offset:16
	global_load_dwordx4 v[44:47], v218, s[8:9] offset:512
	global_load_dwordx4 v[40:43], v218, s[8:9] offset:528
	s_add_u32 s8, s8, 0x2000
	s_addc_u32 s9, s9, 0
	global_load_dwordx4 v[144:147], v218, s[8:9] offset:0
	global_load_dwordx4 v[148:151], v218, s[8:9] offset:16
	global_load_dwordx4 v[152:155], v218, s[8:9] offset:512
	global_load_dwordx4 v[156:159], v218, s[8:9] offset:528
	global_load_dwordx4 v[160:163], v218, s[18:19] offset:0
	global_load_dwordx4 v[164:167], v218, s[18:19] offset:16
	global_load_dwordx4 v[168:171], v218, s[18:19] offset:512
	global_load_dwordx4 v[172:175], v218, s[18:19] offset:528
	s_sub_i32 s8, s24, 0x2000
	s_lshl_b32 s8, s8, 12
	s_add_u32 s8, s14, s8
	s_addc_u32 s9, s15, 0
	s_lshl_b32 s100, s6, 2
	s_lshr_b32 s101, s76, 6
	s_add_i32 s100, s100, s101
	s_and_b32 s101, s2, 1
	s_lshl_b32 s101, s101, 1
	s_add_i32 s100, s100, s101
	s_and_b32 s100, s100, 31
	s_lshl_b32 s100, s100, 11
	s_add_i32 s100, s100, 0xe8ea000
	s_add_u32 s100, s58, s100
	s_addc_u32 s101, s59, 0
	v_mov_b32_e32 v221, v218
	global_load_dwordx4 v[176:179], v219, s[8:9] offset:0
	global_load_dwordx4 v[180:183], v219, s[8:9] offset:16
	global_load_dwordx4 v[224:227], v221, s[100:101] offset:0
	global_load_dwordx4 v[228:231], v221, s[100:101] offset:16
	s_waitcnt vmcnt(4)
	v_pk_add_f32 v[144:145], v[144:145], 1.0 op_sel_hi:[1,0]
	v_pk_add_f32 v[146:147], v[146:147], 1.0 op_sel_hi:[1,0]
	v_pk_add_f32 v[148:149], v[148:149], 1.0 op_sel_hi:[1,0]
	v_pk_add_f32 v[150:151], v[150:151], 1.0 op_sel_hi:[1,0]
	v_pk_add_f32 v[152:153], v[152:153], 1.0 op_sel_hi:[1,0]
	v_pk_add_f32 v[154:155], v[154:155], 1.0 op_sel_hi:[1,0]
	v_pk_add_f32 v[156:157], v[156:157], 1.0 op_sel_hi:[1,0]
	v_pk_add_f32 v[158:159], v[158:159], 1.0 op_sel_hi:[1,0]
	v_pk_mul_f32 v[144:145], v[160:161], v[144:145]
	v_pk_mul_f32 v[146:147], v[162:163], v[146:147]
	v_pk_mul_f32 v[148:149], v[164:165], v[148:149]
	v_pk_mul_f32 v[150:151], v[166:167], v[150:151]
	v_pk_mul_f32 v[152:153], v[168:169], v[152:153]
	v_pk_mul_f32 v[154:155], v[170:171], v[154:155]
	v_pk_mul_f32 v[156:157], v[172:173], v[156:157]
	v_pk_mul_f32 v[158:159], v[174:175], v[158:159]
	global_load_dwordx4 v[242:245], v219, s[8:9] offset:512
	global_load_dwordx4 v[246:249], v219, s[8:9] offset:528
	global_load_dwordx4 v[160:163], v221, s[100:101] offset:512
	global_load_dwordx4 v[164:167], v221, s[100:101] offset:528
	s_waitcnt vmcnt(4)
	v_pk_add_f32 v[176:177], v[176:177], v[224:225]
	v_pk_add_f32 v[178:179], v[178:179], v[226:227]
	v_pk_add_f32 v[180:181], v[180:181], v[228:229]
	v_pk_add_f32 v[182:183], v[182:183], v[230:231]
	v_pk_fma_f32 v[140:141], v[140:141], v[60:61], v[176:177]
	v_pk_fma_f32 v[142:143], v[142:143], v[62:63], v[178:179]
	v_pk_fma_f32 v[136:137], v[136:137], v[56:57], v[180:181]
	v_pk_fma_f32 v[138:139], v[138:139], v[58:59], v[182:183]
	global_store_dwordx4 v219, v[140:143], s[10:11] offset:0
	global_store_dwordx4 v219, v[136:139], s[10:11] offset:16
	v_mul_f32_e32 v198, v140, v140
	v_fmac_f32_e32 v198, v141, v141
	v_fmac_f32_e32 v198, v142, v142
	v_fmac_f32_e32 v198, v143, v143
	v_fmac_f32_e32 v198, v136, v136
	v_fmac_f32_e32 v198, v137, v137
	v_fmac_f32_e32 v198, v138, v138
	v_fmac_f32_e32 v198, v139, v139
	v_pk_mul_f32 v[176:177], v[144:145], v[140:141]
	v_pk_mul_f32 v[178:179], v[146:147], v[142:143]
	v_pk_mul_f32 v[180:181], v[148:149], v[136:137]
	v_pk_mul_f32 v[182:183], v[150:151], v[138:139]
	v_cvt_pk_bf16_f32 v176, v176, v177
	v_cvt_pk_bf16_f32 v177, v178, v179
	v_cvt_pk_bf16_f32 v178, v180, v181
	v_cvt_pk_bf16_f32 v179, v182, v183
	global_store_dwordx4 v220, v[176:179], s[98:99] offset:0
	s_add_u32 s8, s8, 0x10000
	s_addc_u32 s9, s9, 0
	global_load_dwordx4 v[168:171], v219, s[8:9] offset:0
	global_load_dwordx4 v[172:175], v219, s[8:9] offset:16
	global_load_dwordx4 v[180:183], v221, s[100:101] offset:0
	global_load_dwordx4 v[224:227], v221, s[100:101] offset:16
	global_load_dwordx4 v[228:231], v219, s[8:9] offset:512
	global_load_dwordx4 v[140:143], v219, s[8:9] offset:528
	global_load_dwordx4 v[136:139], v221, s[100:101] offset:512
	global_load_dwordx4 v[176:179], v221, s[100:101] offset:528
	s_waitcnt vmcnt(11)
	v_pk_add_f32 v[242:243], v[242:243], v[160:161]
	v_pk_add_f32 v[244:245], v[244:245], v[162:163]
	v_pk_add_f32 v[246:247], v[246:247], v[164:165]
	v_pk_add_f32 v[248:249], v[248:249], v[166:167]
	v_pk_fma_f32 v[132:133], v[132:133], v[44:45], v[242:243]
	v_pk_fma_f32 v[134:135], v[134:135], v[46:47], v[244:245]
	v_pk_fma_f32 v[128:129], v[128:129], v[40:41], v[246:247]
	v_pk_fma_f32 v[130:131], v[130:131], v[42:43], v[248:249]
	global_store_dwordx4 v219, v[132:135], s[10:11] offset:512
	global_store_dwordx4 v219, v[128:131], s[10:11] offset:528
	v_fmac_f32_e32 v198, v132, v132
	v_fmac_f32_e32 v198, v133, v133
	v_fmac_f32_e32 v198, v134, v134
	v_fmac_f32_e32 v198, v135, v135
	v_fmac_f32_e32 v198, v128, v128
	v_fmac_f32_e32 v198, v129, v129
	v_fmac_f32_e32 v198, v130, v130
	v_fmac_f32_e32 v198, v131, v131
	v_pk_mul_f32 v[242:243], v[152:153], v[132:133]
	v_pk_mul_f32 v[244:245], v[154:155], v[134:135]
	v_pk_mul_f32 v[246:247], v[156:157], v[128:129]
	v_pk_mul_f32 v[248:249], v[158:159], v[130:131]
	v_cvt_pk_bf16_f32 v242, v242, v243
	v_cvt_pk_bf16_f32 v243, v244, v245
	v_cvt_pk_bf16_f32 v244, v246, v247
	v_cvt_pk_bf16_f32 v245, v248, v249
	global_store_dwordx4 v220, v[242:245], s[98:99] offset:256
	v_mov_b32_e32 v240, v198
	s_nop 1
	v_permlane16_swap_b32_e32 v198, v240
	v_add_f32_e32 v240, v198, v240
	v_mov_b32_e32 v241, v240
	s_nop 1
	v_permlane32_swap_b32_e32 v240, v241
	v_add_f32_e32 v240, v240, v241
	v_mov_b32_e32 v233, v240
	s_add_u32 s8, s8, 0x10000
	s_addc_u32 s9, s9, 0
	global_load_dwordx4 v[246:249], v219, s[8:9] offset:0
	global_load_dwordx4 v[160:163], v219, s[8:9] offset:16
	global_load_dwordx4 v[164:167], v221, s[100:101] offset:0
	global_load_dwordx4 v[132:135], v221, s[100:101] offset:16
	s_waitcnt vmcnt(11)
	s_add_u32 s10, s10, 0x10000
	s_addc_u32 s11, s11, 0
	s_add_u32 s98, s98, 0x8000
	s_addc_u32 s99, s99, 0
	s_add_u32 s66, s66, 0x400
	s_addc_u32 s67, s67, 0
	v_pk_add_f32 v[168:169], v[168:169], v[180:181]
	v_pk_add_f32 v[170:171], v[170:171], v[182:183]
	v_pk_add_f32 v[172:173], v[172:173], v[224:225]
	v_pk_add_f32 v[174:175], v[174:175], v[226:227]
	v_pk_fma_f32 v[124:125], v[124:125], v[60:61], v[168:169]
	v_pk_fma_f32 v[126:127], v[126:127], v[62:63], v[170:171]
	v_pk_fma_f32 v[120:121], v[120:121], v[56:57], v[172:173]
	v_pk_fma_f32 v[122:123], v[122:123], v[58:59], v[174:175]
	global_store_dwordx4 v219, v[124:127], s[10:11] offset:0
	global_store_dwordx4 v219, v[120:123], s[10:11] offset:16
	v_mul_f32_e32 v198, v124, v124
	v_fmac_f32_e32 v198, v125, v125
	v_fmac_f32_e32 v198, v126, v126
	v_fmac_f32_e32 v198, v127, v127
	v_fmac_f32_e32 v198, v120, v120
	v_fmac_f32_e32 v198, v121, v121
	v_fmac_f32_e32 v198, v122, v122
	v_fmac_f32_e32 v198, v123, v123
	v_pk_mul_f32 v[168:169], v[144:145], v[124:125]
	v_pk_mul_f32 v[170:171], v[146:147], v[126:127]
	v_pk_mul_f32 v[172:173], v[148:149], v[120:121]
	v_pk_mul_f32 v[174:175], v[150:151], v[122:123]
	v_cvt_pk_bf16_f32 v168, v168, v169
	v_cvt_pk_bf16_f32 v169, v170, v171
	v_cvt_pk_bf16_f32 v170, v172, v173
	v_cvt_pk_bf16_f32 v171, v174, v175
	global_store_dwordx4 v220, v[168:171], s[98:99] offset:0
	global_load_dwordx4 v[128:131], v219, s[8:9] offset:512
	global_load_dwordx4 v[242:245], v219, s[8:9] offset:528
	global_load_dwordx4 v[172:175], v221, s[100:101] offset:512
	global_load_dwordx4 v[180:183], v221, s[100:101] offset:528
	s_add_u32 s8, s8, 0x10000
	s_addc_u32 s9, s9, 0
	global_load_dwordx4 v[224:227], v219, s[8:9] offset:0
	global_load_dwordx4 v[124:127], v219, s[8:9] offset:16
	global_load_dwordx4 v[120:123], v221, s[100:101] offset:0
	global_load_dwordx4 v[168:171], v221, s[100:101] offset:16
	s_waitcnt vmcnt(18)
	v_pk_add_f32 v[228:229], v[228:229], v[136:137]
	v_pk_add_f32 v[230:231], v[230:231], v[138:139]
	v_pk_add_f32 v[140:141], v[140:141], v[176:177]
	v_pk_add_f32 v[142:143], v[142:143], v[178:179]
	v_pk_fma_f32 v[116:117], v[116:117], v[44:45], v[228:229]
	v_pk_fma_f32 v[118:119], v[118:119], v[46:47], v[230:231]
	v_pk_fma_f32 v[112:113], v[112:113], v[40:41], v[140:141]
	v_pk_fma_f32 v[114:115], v[114:115], v[42:43], v[142:143]
	global_store_dwordx4 v219, v[116:119], s[10:11] offset:512
	global_store_dwordx4 v219, v[112:115], s[10:11] offset:528
	v_fmac_f32_e32 v198, v116, v116
	v_fmac_f32_e32 v198, v117, v117
	v_fmac_f32_e32 v198, v118, v118
	v_fmac_f32_e32 v198, v119, v119
	v_fmac_f32_e32 v198, v112, v112
	v_fmac_f32_e32 v198, v113, v113
	v_fmac_f32_e32 v198, v114, v114
	v_fmac_f32_e32 v198, v115, v115
	v_pk_mul_f32 v[228:229], v[152:153], v[116:117]
	v_pk_mul_f32 v[230:231], v[154:155], v[118:119]
	v_pk_mul_f32 v[140:141], v[156:157], v[112:113]
	v_pk_mul_f32 v[142:143], v[158:159], v[114:115]
	v_cvt_pk_bf16_f32 v228, v228, v229
	v_cvt_pk_bf16_f32 v229, v230, v231
	v_cvt_pk_bf16_f32 v230, v140, v141
	v_cvt_pk_bf16_f32 v231, v142, v143
	global_store_dwordx4 v220, v[228:231], s[98:99] offset:256
	v_mov_b32_e32 v240, v198
	s_nop 1
	v_permlane16_swap_b32_e32 v198, v240
	v_add_f32_e32 v240, v198, v240
	v_mov_b32_e32 v241, v240
	s_nop 1
	v_permlane32_swap_b32_e32 v240, v241
	v_add_f32_e32 v240, v240, v241
	v_cmp_eq_u32_e64 s[6:7], 1, v236
	s_nop 1
	v_cndmask_b32_e64 v233, v233, v240, s[6:7]
	global_load_dwordx4 v[140:143], v219, s[8:9] offset:512
	global_load_dwordx4 v[136:139], v219, s[8:9] offset:528
	global_load_dwordx4 v[176:179], v221, s[100:101] offset:512
	global_load_dwordx4 v[116:119], v221, s[100:101] offset:528
	s_waitcnt vmcnt(18)
	s_add_u32 s10, s10, 0x10000
	s_addc_u32 s11, s11, 0
	s_add_u32 s98, s98, 0x8000
	s_addc_u32 s99, s99, 0
	s_add_u32 s66, s66, 0x400
	s_addc_u32 s67, s67, 0
	v_pk_add_f32 v[246:247], v[246:247], v[164:165]
	v_pk_add_f32 v[248:249], v[248:249], v[166:167]
	v_pk_add_f32 v[160:161], v[160:161], v[132:133]
	v_pk_add_f32 v[162:163], v[162:163], v[134:135]
	v_pk_fma_f32 v[108:109], v[108:109], v[60:61], v[246:247]
	v_pk_fma_f32 v[110:111], v[110:111], v[62:63], v[248:249]
	v_pk_fma_f32 v[104:105], v[104:105], v[56:57], v[160:161]
	v_pk_fma_f32 v[106:107], v[106:107], v[58:59], v[162:163]
	global_store_dwordx4 v219, v[108:111], s[10:11] offset:0
	global_store_dwordx4 v219, v[104:107], s[10:11] offset:16
	v_mul_f32_e32 v198, v108, v108
	v_fmac_f32_e32 v198, v109, v109
	v_fmac_f32_e32 v198, v110, v110
	v_fmac_f32_e32 v198, v111, v111
	v_fmac_f32_e32 v198, v104, v104
	v_fmac_f32_e32 v198, v105, v105
	v_fmac_f32_e32 v198, v106, v106
	v_fmac_f32_e32 v198, v107, v107
	v_pk_mul_f32 v[246:247], v[144:145], v[108:109]
	v_pk_mul_f32 v[248:249], v[146:147], v[110:111]
	v_pk_mul_f32 v[160:161], v[148:149], v[104:105]
	v_pk_mul_f32 v[162:163], v[150:151], v[106:107]
	v_cvt_pk_bf16_f32 v246, v246, v247
	v_cvt_pk_bf16_f32 v247, v248, v249
	v_cvt_pk_bf16_f32 v248, v160, v161
	v_cvt_pk_bf16_f32 v249, v162, v163
	global_store_dwordx4 v220, v[246:249], s[98:99] offset:0
	s_waitcnt vmcnt(14)
	v_pk_add_f32 v[128:129], v[128:129], v[172:173]
	v_pk_add_f32 v[130:131], v[130:131], v[174:175]
	v_pk_add_f32 v[242:243], v[242:243], v[180:181]
	v_pk_add_f32 v[244:245], v[244:245], v[182:183]
	v_pk_fma_f32 v[100:101], v[100:101], v[44:45], v[128:129]
	v_pk_fma_f32 v[102:103], v[102:103], v[46:47], v[130:131]
	v_pk_fma_f32 v[96:97], v[96:97], v[40:41], v[242:243]
	v_pk_fma_f32 v[98:99], v[98:99], v[42:43], v[244:245]
	global_store_dwordx4 v219, v[100:103], s[10:11] offset:512
	global_store_dwordx4 v219, v[96:99], s[10:11] offset:528
	v_fmac_f32_e32 v198, v100, v100
	v_fmac_f32_e32 v198, v101, v101
	v_fmac_f32_e32 v198, v102, v102
	v_fmac_f32_e32 v198, v103, v103
	v_fmac_f32_e32 v198, v96, v96
	v_fmac_f32_e32 v198, v97, v97
	v_fmac_f32_e32 v198, v98, v98
	v_fmac_f32_e32 v198, v99, v99
	v_pk_mul_f32 v[128:129], v[152:153], v[100:101]
	v_pk_mul_f32 v[130:131], v[154:155], v[102:103]
	v_pk_mul_f32 v[242:243], v[156:157], v[96:97]
	v_pk_mul_f32 v[244:245], v[158:159], v[98:99]
	v_cvt_pk_bf16_f32 v128, v128, v129
	v_cvt_pk_bf16_f32 v129, v130, v131
	v_cvt_pk_bf16_f32 v130, v242, v243
	v_cvt_pk_bf16_f32 v131, v244, v245
	global_store_dwordx4 v220, v[128:131], s[98:99] offset:256
	v_mov_b32_e32 v240, v198
	s_nop 1
	v_permlane16_swap_b32_e32 v198, v240
	v_add_f32_e32 v240, v198, v240
	v_mov_b32_e32 v241, v240
	s_nop 1
	v_permlane32_swap_b32_e32 v240, v241
	v_add_f32_e32 v240, v240, v241
	v_cmp_eq_u32_e64 s[6:7], 2, v236
	s_nop 1
	v_cndmask_b32_e64 v233, v233, v240, s[6:7]
	s_waitcnt vmcnt(13)
	s_add_u32 s10, s10, 0x10000
	s_addc_u32 s11, s11, 0
	s_add_u32 s98, s98, 0x8000
	s_addc_u32 s99, s99, 0
	s_add_u32 s66, s66, 0x400
	s_addc_u32 s67, s67, 0
	v_pk_add_f32 v[224:225], v[224:225], v[120:121]
	v_pk_add_f32 v[226:227], v[226:227], v[122:123]
	v_pk_add_f32 v[124:125], v[124:125], v[168:169]
	v_pk_add_f32 v[126:127], v[126:127], v[170:171]
	v_pk_fma_f32 v[92:93], v[92:93], v[60:61], v[224:225]
	v_pk_fma_f32 v[94:95], v[94:95], v[62:63], v[226:227]
	v_pk_fma_f32 v[88:89], v[88:89], v[56:57], v[124:125]
	v_pk_fma_f32 v[90:91], v[90:91], v[58:59], v[126:127]
	global_store_dwordx4 v219, v[92:95], s[10:11] offset:0
	global_store_dwordx4 v219, v[88:91], s[10:11] offset:16
	v_mul_f32_e32 v198, v92, v92
	v_fmac_f32_e32 v198, v93, v93
	v_fmac_f32_e32 v198, v94, v94
	v_fmac_f32_e32 v198, v95, v95
	v_fmac_f32_e32 v198, v88, v88
	v_fmac_f32_e32 v198, v89, v89
	v_fmac_f32_e32 v198, v90, v90
	v_fmac_f32_e32 v198, v91, v91
	v_pk_mul_f32 v[224:225], v[144:145], v[92:93]
	v_pk_mul_f32 v[226:227], v[146:147], v[94:95]
	v_pk_mul_f32 v[124:125], v[148:149], v[88:89]
	v_pk_mul_f32 v[126:127], v[150:151], v[90:91]
	v_cvt_pk_bf16_f32 v224, v224, v225
	v_cvt_pk_bf16_f32 v225, v226, v227
	v_cvt_pk_bf16_f32 v226, v124, v125
	v_cvt_pk_bf16_f32 v227, v126, v127
	global_store_dwordx4 v220, v[224:227], s[98:99] offset:0
	s_waitcnt vmcnt(9)
	v_pk_add_f32 v[140:141], v[140:141], v[176:177]
	v_pk_add_f32 v[142:143], v[142:143], v[178:179]
	v_pk_add_f32 v[136:137], v[136:137], v[116:117]
	v_pk_add_f32 v[138:139], v[138:139], v[118:119]
	v_pk_fma_f32 v[84:85], v[84:85], v[44:45], v[140:141]
	v_pk_fma_f32 v[86:87], v[86:87], v[46:47], v[142:143]
	v_pk_fma_f32 v[80:81], v[80:81], v[40:41], v[136:137]
	v_pk_fma_f32 v[82:83], v[82:83], v[42:43], v[138:139]
	global_store_dwordx4 v219, v[84:87], s[10:11] offset:512
	global_store_dwordx4 v219, v[80:83], s[10:11] offset:528
	v_fmac_f32_e32 v198, v84, v84
	v_fmac_f32_e32 v198, v85, v85
	v_fmac_f32_e32 v198, v86, v86
	v_fmac_f32_e32 v198, v87, v87
	v_fmac_f32_e32 v198, v80, v80
	v_fmac_f32_e32 v198, v81, v81
	v_fmac_f32_e32 v198, v82, v82
	v_fmac_f32_e32 v198, v83, v83
	v_pk_mul_f32 v[140:141], v[152:153], v[84:85]
	v_pk_mul_f32 v[142:143], v[154:155], v[86:87]
	v_pk_mul_f32 v[136:137], v[156:157], v[80:81]
	v_pk_mul_f32 v[138:139], v[158:159], v[82:83]
	v_cvt_pk_bf16_f32 v140, v140, v141
	v_cvt_pk_bf16_f32 v141, v142, v143
	v_cvt_pk_bf16_f32 v142, v136, v137
	v_cvt_pk_bf16_f32 v143, v138, v139
	global_store_dwordx4 v220, v[140:143], s[98:99] offset:256
	v_mov_b32_e32 v240, v198
	s_nop 1
	v_permlane16_swap_b32_e32 v198, v240
	v_add_f32_e32 v240, v198, v240
	v_mov_b32_e32 v241, v240
	s_nop 1
	v_permlane32_swap_b32_e32 v240, v241
	v_add_f32_e32 v240, v240, v241
	v_cmp_eq_u32_e64 s[6:7], 3, v236
	s_nop 1
	v_cndmask_b32_e64 v233, v233, v240, s[6:7]
	global_store_dword v222, v233, s[66:67] offset:-3072
	s_branch .Lepo_done
.Lepo_ctx_lo:
	s_lshl_b32 s8, s66, 4
	s_lshl_b32 s9, s75, 2
	s_add_i32 s8, s8, s9
	s_lshl_b32 s9, s24, 6
	s_add_i32 s8, s8, s9
	s_add_i32 s8, s8, 0xea9a000
	s_add_u32 s66, s58, s8
	s_addc_u32 s67, s59, 0
	s_mov_b32 s8, 0xe802000
	s_add_u32 s8, s58, s8
	s_addc_u32 s9, s59, 0
	global_load_dwordx4 v[60:63], v218, s[8:9] offset:0
	global_load_dwordx4 v[56:59], v218, s[8:9] offset:16
	global_load_dwordx4 v[44:47], v218, s[8:9] offset:512
	global_load_dwordx4 v[40:43], v218, s[8:9] offset:528
	s_add_u32 s8, s8, 0x2000
	s_addc_u32 s9, s9, 0
	global_load_dwordx4 v[144:147], v218, s[8:9] offset:0
	global_load_dwordx4 v[148:151], v218, s[8:9] offset:16
	global_load_dwordx4 v[152:155], v218, s[8:9] offset:512
	global_load_dwordx4 v[156:159], v218, s[8:9] offset:528
	global_load_dwordx4 v[160:163], v218, s[18:19] offset:0
	global_load_dwordx4 v[164:167], v218, s[18:19] offset:16
	global_load_dwordx4 v[168:171], v218, s[18:19] offset:512
	global_load_dwordx4 v[172:175], v218, s[18:19] offset:528
	s_lshl_b32 s8, s24, 12
	s_add_u32 s8, s12, s8
	s_addc_u32 s9, s13, 0
	global_load_dwordx4 v[176:179], v219, s[8:9] offset:0
	global_load_dwordx4 v[180:183], v219, s[8:9] offset:16
	global_load_dwordx4 v[224:227], v219, s[8:9] offset:512
	global_load_dwordx4 v[228:231], v219, s[8:9] offset:528
	s_add_u32 s8, s8, 0x10000
	s_addc_u32 s9, s9, 0
	global_load_dwordx4 v[242:245], v219, s[8:9] offset:0
	global_load_dwordx4 v[246:249], v219, s[8:9] offset:16
	s_waitcnt vmcnt(6)
	v_pk_add_f32 v[144:145], v[144:145], 1.0 op_sel_hi:[1,0]
	v_pk_add_f32 v[146:147], v[146:147], 1.0 op_sel_hi:[1,0]
	v_pk_add_f32 v[148:149], v[148:149], 1.0 op_sel_hi:[1,0]
	v_pk_add_f32 v[150:151], v[150:151], 1.0 op_sel_hi:[1,0]
	v_pk_add_f32 v[152:153], v[152:153], 1.0 op_sel_hi:[1,0]
	v_pk_add_f32 v[154:155], v[154:155], 1.0 op_sel_hi:[1,0]
	v_pk_add_f32 v[156:157], v[156:157], 1.0 op_sel_hi:[1,0]
	v_pk_add_f32 v[158:159], v[158:159], 1.0 op_sel_hi:[1,0]
	v_pk_mul_f32 v[144:145], v[160:161], v[144:145]
	v_pk_mul_f32 v[146:147], v[162:163], v[146:147]
	v_pk_mul_f32 v[148:149], v[164:165], v[148:149]
	v_pk_mul_f32 v[150:151], v[166:167], v[150:151]
	v_pk_mul_f32 v[152:153], v[168:169], v[152:153]
	v_pk_mul_f32 v[154:155], v[170:171], v[154:155]
	v_pk_mul_f32 v[156:157], v[172:173], v[156:157]
	v_pk_mul_f32 v[158:159], v[174:175], v[158:159]
	global_load_dwordx4 v[160:163], v219, s[8:9] offset:512
	global_load_dwordx4 v[164:167], v219, s[8:9] offset:528
	s_add_u32 s8, s8, 0x10000
	s_addc_u32 s9, s9, 0
	global_load_dwordx4 v[168:171], v219, s[8:9] offset:0
	global_load_dwordx4 v[172:175], v219, s[8:9] offset:16
	s_waitcnt vmcnt(8)
	v_pk_fma_f32 v[140:141], v[140:141], v[60:61], v[176:177]
	v_pk_fma_f32 v[142:143], v[142:143], v[62:63], v[178:179]
	v_pk_fma_f32 v[136:137], v[136:137], v[56:57], v[180:181]
	v_pk_fma_f32 v[138:139], v[138:139], v[58:59], v[182:183]
	global_store_dwordx4 v219, v[140:143], s[10:11] offset:0
	global_store_dwordx4 v219, v[136:139], s[10:11] offset:16
	v_mul_f32_e32 v198, v140, v140
	v_fmac_f32_e32 v198, v141, v141
	v_fmac_f32_e32 v198, v142, v142
	v_fmac_f32_e32 v198, v143, v143
	v_fmac_f32_e32 v198, v136, v136
	v_fmac_f32_e32 v198, v137, v137
	v_fmac_f32_e32 v198, v138, v138
	v_fmac_f32_e32 v198, v139, v139
	v_pk_mul_f32 v[176:177], v[144:145], v[140:141]
	v_pk_mul_f32 v[178:179], v[146:147], v[142:143]
	v_pk_mul_f32 v[180:181], v[148:149], v[136:137]
	v_pk_mul_f32 v[182:183], v[150:151], v[138:139]
	v_cvt_pk_bf16_f32 v176, v176, v177
	v_cvt_pk_bf16_f32 v177, v178, v179
	v_cvt_pk_bf16_f32 v178, v180, v181
	v_cvt_pk_bf16_f32 v179, v182, v183
	global_store_dwordx4 v220, v[176:179], s[98:99] offset:0
	global_load_dwordx4 v[180:183], v219, s[8:9] offset:512
	global_load_dwordx4 v[140:143], v219, s[8:9] offset:528
	s_add_u32 s8, s8, 0x10000
	s_addc_u32 s9, s9, 0
	global_load_dwordx4 v[136:139], v219, s[8:9] offset:0
	global_load_dwordx4 v[176:179], v219, s[8:9] offset:16
	s_waitcnt vmcnt(13)
	v_pk_fma_f32 v[132:133], v[132:133], v[44:45], v[224:225]
	v_pk_fma_f32 v[134:135], v[134:135], v[46:47], v[226:227]
	v_pk_fma_f32 v[128:129], v[128:129], v[40:41], v[228:229]
	v_pk_fma_f32 v[130:131], v[130:131], v[42:43], v[230:231]
	global_store_dwordx4 v219, v[132:135], s[10:11] offset:512
	global_store_dwordx4 v219, v[128:131], s[10:11] offset:528
	v_fmac_f32_e32 v198, v132, v132
	v_fmac_f32_e32 v198, v133, v133
	v_fmac_f32_e32 v198, v134, v134
	v_fmac_f32_e32 v198, v135, v135
	v_fmac_f32_e32 v198, v128, v128
	v_fmac_f32_e32 v198, v129, v129
	v_fmac_f32_e32 v198, v130, v130
	v_fmac_f32_e32 v198, v131, v131
	v_pk_mul_f32 v[224:225], v[152:153], v[132:133]
	v_pk_mul_f32 v[226:227], v[154:155], v[134:135]
	v_pk_mul_f32 v[228:229], v[156:157], v[128:129]
	v_pk_mul_f32 v[230:231], v[158:159], v[130:131]
	v_cvt_pk_bf16_f32 v224, v224, v225
	v_cvt_pk_bf16_f32 v225, v226, v227
	v_cvt_pk_bf16_f32 v226, v228, v229
	v_cvt_pk_bf16_f32 v227, v230, v231
	global_store_dwordx4 v220, v[224:227], s[98:99] offset:256
	v_mov_b32_e32 v240, v198
	s_nop 1
	v_permlane16_swap_b32_e32 v198, v240
	v_add_f32_e32 v240, v198, v240
	v_mov_b32_e32 v241, v240
	s_nop 1
	v_permlane32_swap_b32_e32 v240, v241
	v_add_f32_e32 v240, v240, v241
	v_mov_b32_e32 v233, v240
	global_load_dwordx4 v[228:231], v219, s[8:9] offset:512
	global_load_dwordx4 v[132:135], v219, s[8:9] offset:528
	s_waitcnt vmcnt(16)
	s_add_u32 s10, s10, 0x10000
	s_addc_u32 s11, s11, 0
	s_add_u32 s98, s98, 0x8000
	s_addc_u32 s99, s99, 0
	s_add_u32 s66, s66, 0x400
	s_addc_u32 s67, s67, 0
	v_pk_fma_f32 v[124:125], v[124:125], v[60:61], v[242:243]
	v_pk_fma_f32 v[126:127], v[126:127], v[62:63], v[244:245]
	v_pk_fma_f32 v[120:121], v[120:121], v[56:57], v[246:247]
	v_pk_fma_f32 v[122:123], v[122:123], v[58:59], v[248:249]
	global_store_dwordx4 v219, v[124:127], s[10:11] offset:0
	global_store_dwordx4 v219, v[120:123], s[10:11] offset:16
	v_mul_f32_e32 v198, v124, v124
	v_fmac_f32_e32 v198, v125, v125
	v_fmac_f32_e32 v198, v126, v126
	v_fmac_f32_e32 v198, v127, v127
	v_fmac_f32_e32 v198, v120, v120
	v_fmac_f32_e32 v198, v121, v121
	v_fmac_f32_e32 v198, v122, v122
	v_fmac_f32_e32 v198, v123, v123
	v_pk_mul_f32 v[242:243], v[144:145], v[124:125]
	v_pk_mul_f32 v[244:245], v[146:147], v[126:127]
	v_pk_mul_f32 v[246:247], v[148:149], v[120:121]
	v_pk_mul_f32 v[248:249], v[150:151], v[122:123]
	v_cvt_pk_bf16_f32 v242, v242, v243
	v_cvt_pk_bf16_f32 v243, v244, v245
	v_cvt_pk_bf16_f32 v244, v246, v247
	v_cvt_pk_bf16_f32 v245, v248, v249
	global_store_dwordx4 v220, v[242:245], s[98:99] offset:0
	s_waitcnt vmcnt(17)
	v_pk_fma_f32 v[116:117], v[116:117], v[44:45], v[160:161]
	v_pk_fma_f32 v[118:119], v[118:119], v[46:47], v[162:163]
	v_pk_fma_f32 v[112:113], v[112:113], v[40:41], v[164:165]
	v_pk_fma_f32 v[114:115], v[114:115], v[42:43], v[166:167]
	global_store_dwordx4 v219, v[116:119], s[10:11] offset:512
	global_store_dwordx4 v219, v[112:115], s[10:11] offset:528
	v_fmac_f32_e32 v198, v116, v116
	v_fmac_f32_e32 v198, v117, v117
	v_fmac_f32_e32 v198, v118, v118
	v_fmac_f32_e32 v198, v119, v119
	v_fmac_f32_e32 v198, v112, v112
	v_fmac_f32_e32 v198, v113, v113
	v_fmac_f32_e32 v198, v114, v114
	v_fmac_f32_e32 v198, v115, v115
	v_pk_mul_f32 v[160:161], v[152:153], v[116:117]
	v_pk_mul_f32 v[162:163], v[154:155], v[118:119]
	v_pk_mul_f32 v[164:165], v[156:157], v[112:113]
	v_pk_mul_f32 v[166:167], v[158:159], v[114:115]
	v_cvt_pk_bf16_f32 v160, v160, v161
	v_cvt_pk_bf16_f32 v161, v162, v163
	v_cvt_pk_bf16_f32 v162, v164, v165
	v_cvt_pk_bf16_f32 v163, v166, v167
	global_store_dwordx4 v220, v[160:163], s[98:99] offset:256
	v_mov_b32_e32 v240, v198
	s_nop 1
	v_permlane16_swap_b32_e32 v198, v240
	v_add_f32_e32 v240, v198, v240
	v_mov_b32_e32 v241, v240
	s_nop 1
	v_permlane32_swap_b32_e32 v240, v241
	v_add_f32_e32 v240, v240, v241
	v_cmp_eq_u32_e64 s[6:7], 1, v236
	s_nop 1
	v_cndmask_b32_e64 v233, v233, v240, s[6:7]
	s_waitcnt vmcnt(18)
	s_add_u32 s10, s10, 0x10000
	s_addc_u32 s11, s11, 0
	s_add_u32 s98, s98, 0x8000
	s_addc_u32 s99, s99, 0
	s_add_u32 s66, s66, 0x400
	s_addc_u32 s67, s67, 0
	v_pk_fma_f32 v[108:109], v[108:109], v[60:61], v[168:169]
	v_pk_fma_f32 v[110:111], v[110:111], v[62:63], v[170:171]
	v_pk_fma_f32 v[104:105], v[104:105], v[56:57], v[172:173]
	v_pk_fma_f32 v[106:107], v[106:107], v[58:59], v[174:175]
	global_store_dwordx4 v219, v[108:111], s[10:11] offset:0
	global_store_dwordx4 v219, v[104:107], s[10:11] offset:16
	v_mul_f32_e32 v198, v108, v108
	v_fmac_f32_e32 v198, v109, v109
	v_fmac_f32_e32 v198, v110, v110
	v_fmac_f32_e32 v198, v111, v111
	v_fmac_f32_e32 v198, v104, v104
	v_fmac_f32_e32 v198, v105, v105
	v_fmac_f32_e32 v198, v106, v106
	v_fmac_f32_e32 v198, v107, v107
	v_pk_mul_f32 v[168:169], v[144:145], v[108:109]
	v_pk_mul_f32 v[170:171], v[146:147], v[110:111]
	v_pk_mul_f32 v[172:173], v[148:149], v[104:105]
	v_pk_mul_f32 v[174:175], v[150:151], v[106:107]
	v_cvt_pk_bf16_f32 v168, v168, v169
	v_cvt_pk_bf16_f32 v169, v170, v171
	v_cvt_pk_bf16_f32 v170, v172, v173
	v_cvt_pk_bf16_f32 v171, v174, v175
	global_store_dwordx4 v220, v[168:171], s[98:99] offset:0
	s_waitcnt vmcnt(16)
	v_pk_fma_f32 v[100:101], v[100:101], v[44:45], v[180:181]
	v_pk_fma_f32 v[102:103], v[102:103], v[46:47], v[182:183]
	v_pk_fma_f32 v[96:97], v[96:97], v[40:41], v[140:141]
	v_pk_fma_f32 v[98:99], v[98:99], v[42:43], v[142:143]
	global_store_dwordx4 v219, v[100:103], s[10:11] offset:512
	global_store_dwordx4 v219, v[96:99], s[10:11] offset:528
	v_fmac_f32_e32 v198, v100, v100
	v_fmac_f32_e32 v198, v101, v101
	v_fmac_f32_e32 v198, v102, v102
	v_fmac_f32_e32 v198, v103, v103
	v_fmac_f32_e32 v198, v96, v96
	v_fmac_f32_e32 v198, v97, v97
	v_fmac_f32_e32 v198, v98, v98
	v_fmac_f32_e32 v198, v99, v99
	v_pk_mul_f32 v[180:181], v[152:153], v[100:101]
	v_pk_mul_f32 v[182:183], v[154:155], v[102:103]
	v_pk_mul_f32 v[140:141], v[156:157], v[96:97]
	v_pk_mul_f32 v[142:143], v[158:159], v[98:99]
	v_cvt_pk_bf16_f32 v180, v180, v181
	v_cvt_pk_bf16_f32 v181, v182, v183
	v_cvt_pk_bf16_f32 v182, v140, v141
	v_cvt_pk_bf16_f32 v183, v142, v143
	global_store_dwordx4 v220, v[180:183], s[98:99] offset:256
	v_mov_b32_e32 v240, v198
	s_nop 1
	v_permlane16_swap_b32_e32 v198, v240
	v_add_f32_e32 v240, v198, v240
	v_mov_b32_e32 v241, v240
	s_nop 1
	v_permlane32_swap_b32_e32 v240, v241
	v_add_f32_e32 v240, v240, v241
	v_cmp_eq_u32_e64 s[6:7], 2, v236
	s_nop 1
	v_cndmask_b32_e64 v233, v233, v240, s[6:7]
	s_waitcnt vmcnt(17)
	s_add_u32 s10, s10, 0x10000
	s_addc_u32 s11, s11, 0
	s_add_u32 s98, s98, 0x8000
	s_addc_u32 s99, s99, 0
	s_add_u32 s66, s66, 0x400
	s_addc_u32 s67, s67, 0
	v_pk_fma_f32 v[92:93], v[92:93], v[60:61], v[136:137]
	v_pk_fma_f32 v[94:95], v[94:95], v[62:63], v[138:139]
	v_pk_fma_f32 v[88:89], v[88:89], v[56:57], v[176:177]
	v_pk_fma_f32 v[90:91], v[90:91], v[58:59], v[178:179]
	global_store_dwordx4 v219, v[92:95], s[10:11] offset:0
	global_store_dwordx4 v219, v[88:91], s[10:11] offset:16
	v_mul_f32_e32 v198, v92, v92
	v_fmac_f32_e32 v198, v93, v93
	v_fmac_f32_e32 v198, v94, v94
	v_fmac_f32_e32 v198, v95, v95
	v_fmac_f32_e32 v198, v88, v88
	v_fmac_f32_e32 v198, v89, v89
	v_fmac_f32_e32 v198, v90, v90
	v_fmac_f32_e32 v198, v91, v91
	v_pk_mul_f32 v[136:137], v[144:145], v[92:93]
	v_pk_mul_f32 v[138:139], v[146:147], v[94:95]
	v_pk_mul_f32 v[176:177], v[148:149], v[88:89]
	v_pk_mul_f32 v[178:179], v[150:151], v[90:91]
	v_cvt_pk_bf16_f32 v136, v136, v137
	v_cvt_pk_bf16_f32 v137, v138, v139
	v_cvt_pk_bf16_f32 v138, v176, v177
	v_cvt_pk_bf16_f32 v139, v178, v179
	global_store_dwordx4 v220, v[136:139], s[98:99] offset:0
	s_waitcnt vmcnt(15)
	v_pk_fma_f32 v[84:85], v[84:85], v[44:45], v[228:229]
	v_pk_fma_f32 v[86:87], v[86:87], v[46:47], v[230:231]
	v_pk_fma_f32 v[80:81], v[80:81], v[40:41], v[132:133]
	v_pk_fma_f32 v[82:83], v[82:83], v[42:43], v[134:135]
	global_store_dwordx4 v219, v[84:87], s[10:11] offset:512
	global_store_dwordx4 v219, v[80:83], s[10:11] offset:528
	v_fmac_f32_e32 v198, v84, v84
	v_fmac_f32_e32 v198, v85, v85
	v_fmac_f32_e32 v198, v86, v86
	v_fmac_f32_e32 v198, v87, v87
	v_fmac_f32_e32 v198, v80, v80
	v_fmac_f32_e32 v198, v81, v81
	v_fmac_f32_e32 v198, v82, v82
	v_fmac_f32_e32 v198, v83, v83
	v_pk_mul_f32 v[228:229], v[152:153], v[84:85]
	v_pk_mul_f32 v[230:231], v[154:155], v[86:87]
	v_pk_mul_f32 v[132:133], v[156:157], v[80:81]
	v_pk_mul_f32 v[134:135], v[158:159], v[82:83]
	v_cvt_pk_bf16_f32 v228, v228, v229
	v_cvt_pk_bf16_f32 v229, v230, v231
	v_cvt_pk_bf16_f32 v230, v132, v133
	v_cvt_pk_bf16_f32 v231, v134, v135
	global_store_dwordx4 v220, v[228:231], s[98:99] offset:256
	v_mov_b32_e32 v240, v198
	s_nop 1
	v_permlane16_swap_b32_e32 v198, v240
	v_add_f32_e32 v240, v198, v240
	v_mov_b32_e32 v241, v240
	s_nop 1
	v_permlane32_swap_b32_e32 v240, v241
	v_add_f32_e32 v240, v240, v241
	v_cmp_eq_u32_e64 s[6:7], 3, v236
	s_nop 1
	v_cndmask_b32_e64 v233, v233, v240, s[6:7]
	global_store_dword v222, v233, s[66:67] offset:-3072
	s_branch .Lepo_done
.Lepo_ctx:
	s_lshl_b32 s8, s66, 4
	s_lshl_b32 s9, s75, 2
	s_add_i32 s8, s8, s9
	s_lshl_b32 s9, s24, 6
	s_add_i32 s8, s8, s9
	s_add_i32 s8, s8, 0xea9a000
	s_add_u32 s66, s58, s8
	s_addc_u32 s67, s59, 0
	s_mov_b32 s8, 0xe802000
	s_add_u32 s8, s58, s8
	s_addc_u32 s9, s59, 0
	global_load_dwordx4 v[60:63], v218, s[8:9] offset:0
	global_load_dwordx4 v[56:59], v218, s[8:9] offset:16
	global_load_dwordx4 v[44:47], v218, s[8:9] offset:512
	global_load_dwordx4 v[40:43], v218, s[8:9] offset:528
	s_add_u32 s8, s8, 0x2000
	s_addc_u32 s9, s9, 0
	global_load_dwordx4 v[144:147], v218, s[8:9] offset:0
	global_load_dwordx4 v[148:151], v218, s[8:9] offset:16
	global_load_dwordx4 v[152:155], v218, s[8:9] offset:512
	global_load_dwordx4 v[156:159], v218, s[8:9] offset:528
	global_load_dwordx4 v[160:163], v218, s[18:19] offset:0
	global_load_dwordx4 v[164:167], v218, s[18:19] offset:16
	global_load_dwordx4 v[168:171], v218, s[18:19] offset:512
	global_load_dwordx4 v[172:175], v218, s[18:19] offset:528
	s_lshl_b32 s8, s24, 12
	s_add_u32 s8, s12, s8
	s_addc_u32 s9, s13, 0
	global_load_dwordx4 v[176:179], v219, s[8:9] offset:0
	global_load_dwordx4 v[180:183], v219, s[8:9] offset:16
	global_load_dwordx4 v[224:227], v219, s[8:9] offset:512
	global_load_dwordx4 v[228:231], v219, s[8:9] offset:528
	s_add_u32 s8, s8, 0x10000
	s_addc_u32 s9, s9, 0
	global_load_dwordx4 v[242:245], v219, s[8:9] offset:0
	global_load_dwordx4 v[246:249], v219, s[8:9] offset:16
	s_waitcnt vmcnt(6)
	v_pk_add_f32 v[144:145], v[144:145], 1.0 op_sel_hi:[1,0]
	v_pk_add_f32 v[146:147], v[146:147], 1.0 op_sel_hi:[1,0]
	v_pk_add_f32 v[148:149], v[148:149], 1.0 op_sel_hi:[1,0]
	v_pk_add_f32 v[150:151], v[150:151], 1.0 op_sel_hi:[1,0]
	v_pk_add_f32 v[152:153], v[152:153], 1.0 op_sel_hi:[1,0]
	v_pk_add_f32 v[154:155], v[154:155], 1.0 op_sel_hi:[1,0]
	v_pk_add_f32 v[156:157], v[156:157], 1.0 op_sel_hi:[1,0]
	v_pk_add_f32 v[158:159], v[158:159], 1.0 op_sel_hi:[1,0]
	v_pk_mul_f32 v[144:145], v[160:161], v[144:145]
	v_pk_mul_f32 v[146:147], v[162:163], v[146:147]
	v_pk_mul_f32 v[148:149], v[164:165], v[148:149]
	v_pk_mul_f32 v[150:151], v[166:167], v[150:151]
	v_pk_mul_f32 v[152:153], v[168:169], v[152:153]
	v_pk_mul_f32 v[154:155], v[170:171], v[154:155]
	v_pk_mul_f32 v[156:157], v[172:173], v[156:157]
	v_pk_mul_f32 v[158:159], v[174:175], v[158:159]
	global_load_dwordx4 v[160:163], v219, s[8:9] offset:512
	global_load_dwordx4 v[164:167], v219, s[8:9] offset:528
	s_add_u32 s8, s8, 0x10000
	s_addc_u32 s9, s9, 0
	global_load_dwordx4 v[168:171], v219, s[8:9] offset:0
	global_load_dwordx4 v[172:175], v219, s[8:9] offset:16
	s_waitcnt vmcnt(8)
	v_pk_fma_f32 v[140:141], v[140:141], v[60:61], v[176:177]
	v_pk_fma_f32 v[142:143], v[142:143], v[62:63], v[178:179]
	v_pk_fma_f32 v[136:137], v[136:137], v[56:57], v[180:181]
	v_pk_fma_f32 v[138:139], v[138:139], v[58:59], v[182:183]
	global_store_dwordx4 v219, v[140:143], s[10:11] offset:0
	global_store_dwordx4 v219, v[136:139], s[10:11] offset:16
	v_mul_f32_e32 v198, v140, v140
	v_fmac_f32_e32 v198, v141, v141
	v_fmac_f32_e32 v198, v142, v142
	v_fmac_f32_e32 v198, v143, v143
	v_fmac_f32_e32 v198, v136, v136
	v_fmac_f32_e32 v198, v137, v137
	v_fmac_f32_e32 v198, v138, v138
	v_fmac_f32_e32 v198, v139, v139
	v_pk_mul_f32 v[176:177], v[144:145], v[140:141]
	v_pk_mul_f32 v[178:179], v[146:147], v[142:143]
	v_pk_mul_f32 v[180:181], v[148:149], v[136:137]
	v_pk_mul_f32 v[182:183], v[150:151], v[138:139]
	v_cvt_pk_bf16_f32 v176, v176, v177
	v_cvt_pk_bf16_f32 v177, v178, v179
	v_cvt_pk_bf16_f32 v178, v180, v181
	v_cvt_pk_bf16_f32 v179, v182, v183
	global_store_dwordx4 v220, v[176:179], s[98:99] offset:0
	global_load_dwordx4 v[180:183], v219, s[8:9] offset:512
	global_load_dwordx4 v[140:143], v219, s[8:9] offset:528
	s_add_u32 s8, s8, 0x10000
	s_addc_u32 s9, s9, 0
	global_load_dwordx4 v[136:139], v219, s[8:9] offset:0
	global_load_dwordx4 v[176:179], v219, s[8:9] offset:16
	s_waitcnt vmcnt(13)
	v_pk_fma_f32 v[132:133], v[132:133], v[44:45], v[224:225]
	v_pk_fma_f32 v[134:135], v[134:135], v[46:47], v[226:227]
	v_pk_fma_f32 v[128:129], v[128:129], v[40:41], v[228:229]
	v_pk_fma_f32 v[130:131], v[130:131], v[42:43], v[230:231]
	global_store_dwordx4 v219, v[132:135], s[10:11] offset:512
	global_store_dwordx4 v219, v[128:131], s[10:11] offset:528
	v_fmac_f32_e32 v198, v132, v132
	v_fmac_f32_e32 v198, v133, v133
	v_fmac_f32_e32 v198, v134, v134
	v_fmac_f32_e32 v198, v135, v135
	v_fmac_f32_e32 v198, v128, v128
	v_fmac_f32_e32 v198, v129, v129
	v_fmac_f32_e32 v198, v130, v130
	v_fmac_f32_e32 v198, v131, v131
	v_pk_mul_f32 v[224:225], v[152:153], v[132:133]
	v_pk_mul_f32 v[226:227], v[154:155], v[134:135]
	v_pk_mul_f32 v[228:229], v[156:157], v[128:129]
	v_pk_mul_f32 v[230:231], v[158:159], v[130:131]
	v_cvt_pk_bf16_f32 v224, v224, v225
	v_cvt_pk_bf16_f32 v225, v226, v227
	v_cvt_pk_bf16_f32 v226, v228, v229
	v_cvt_pk_bf16_f32 v227, v230, v231
	global_store_dwordx4 v220, v[224:227], s[98:99] offset:256
	v_mov_b32_e32 v240, v198
	s_nop 1
	v_permlane16_swap_b32_e32 v198, v240
	v_add_f32_e32 v240, v198, v240
	v_mov_b32_e32 v241, v240
	s_nop 1
	v_permlane32_swap_b32_e32 v240, v241
	v_add_f32_e32 v240, v240, v241
	v_mov_b32_e32 v233, v240
	global_load_dwordx4 v[228:231], v219, s[8:9] offset:512
	global_load_dwordx4 v[132:135], v219, s[8:9] offset:528
	s_add_u32 s8, s8, 0x50000
	s_addc_u32 s9, s9, 0
	global_load_dwordx4 v[128:131], v219, s[8:9] offset:0
	global_load_dwordx4 v[224:227], v219, s[8:9] offset:16
	s_waitcnt vmcnt(18)
	s_add_u32 s10, s10, 0x10000
	s_addc_u32 s11, s11, 0
	s_add_u32 s98, s98, 0x8000
	s_addc_u32 s99, s99, 0
	s_add_u32 s66, s66, 0x400
	s_addc_u32 s67, s67, 0
	v_pk_fma_f32 v[124:125], v[124:125], v[60:61], v[242:243]
	v_pk_fma_f32 v[126:127], v[126:127], v[62:63], v[244:245]
	v_pk_fma_f32 v[120:121], v[120:121], v[56:57], v[246:247]
	v_pk_fma_f32 v[122:123], v[122:123], v[58:59], v[248:249]
	global_store_dwordx4 v219, v[124:127], s[10:11] offset:0
	global_store_dwordx4 v219, v[120:123], s[10:11] offset:16
	v_mul_f32_e32 v198, v124, v124
	v_fmac_f32_e32 v198, v125, v125
	v_fmac_f32_e32 v198, v126, v126
	v_fmac_f32_e32 v198, v127, v127
	v_fmac_f32_e32 v198, v120, v120
	v_fmac_f32_e32 v198, v121, v121
	v_fmac_f32_e32 v198, v122, v122
	v_fmac_f32_e32 v198, v123, v123
	v_pk_mul_f32 v[242:243], v[144:145], v[124:125]
	v_pk_mul_f32 v[244:245], v[146:147], v[126:127]
	v_pk_mul_f32 v[246:247], v[148:149], v[120:121]
	v_pk_mul_f32 v[248:249], v[150:151], v[122:123]
	v_cvt_pk_bf16_f32 v242, v242, v243
	v_cvt_pk_bf16_f32 v243, v244, v245
	v_cvt_pk_bf16_f32 v244, v246, v247
	v_cvt_pk_bf16_f32 v245, v248, v249
	global_store_dwordx4 v220, v[242:245], s[98:99] offset:0
	global_load_dwordx4 v[246:249], v219, s[8:9] offset:512
	global_load_dwordx4 v[124:127], v219, s[8:9] offset:528
	s_add_u32 s8, s8, 0x10000
	s_addc_u32 s9, s9, 0
	global_load_dwordx4 v[120:123], v219, s[8:9] offset:0
	global_load_dwordx4 v[242:245], v219, s[8:9] offset:16
	s_waitcnt vmcnt(23)
	v_pk_fma_f32 v[116:117], v[116:117], v[44:45], v[160:161]
	v_pk_fma_f32 v[118:119], v[118:119], v[46:47], v[162:163]
	v_pk_fma_f32 v[112:113], v[112:113], v[40:41], v[164:165]
	v_pk_fma_f32 v[114:115], v[114:115], v[42:43], v[166:167]
	global_store_dwordx4 v219, v[116:119], s[10:11] offset:512
	global_store_dwordx4 v219, v[112:115], s[10:11] offset:528
	v_fmac_f32_e32 v198, v116, v116
	v_fmac_f32_e32 v198, v117, v117
	v_fmac_f32_e32 v198, v118, v118
	v_fmac_f32_e32 v198, v119, v119
	v_fmac_f32_e32 v198, v112, v112
	v_fmac_f32_e32 v198, v113, v113
	v_fmac_f32_e32 v198, v114, v114
	v_fmac_f32_e32 v198, v115, v115
	v_pk_mul_f32 v[160:161], v[152:153], v[116:117]
	v_pk_mul_f32 v[162:163], v[154:155], v[118:119]
	v_pk_mul_f32 v[164:165], v[156:157], v[112:113]
	v_pk_mul_f32 v[166:167], v[158:159], v[114:115]
	v_cvt_pk_bf16_f32 v160, v160, v161
	v_cvt_pk_bf16_f32 v161, v162, v163
	v_cvt_pk_bf16_f32 v162, v164, v165
	v_cvt_pk_bf16_f32 v163, v166, v167
	global_store_dwordx4 v220, v[160:163], s[98:99] offset:256
	v_mov_b32_e32 v240, v198
	s_nop 1
	v_permlane16_swap_b32_e32 v198, v240
	v_add_f32_e32 v240, v198, v240
	v_mov_b32_e32 v241, v240
	s_nop 1
	v_permlane32_swap_b32_e32 v240, v241
	v_add_f32_e32 v240, v240, v241
	v_cmp_eq_u32_e64 s[6:7], 1, v236
	s_nop 1
	v_cndmask_b32_e64 v233, v233, v240, s[6:7]
	global_load_dwordx4 v[164:167], v219, s[8:9] offset:512
	global_load_dwordx4 v[116:119], v219, s[8:9] offset:528
	s_add_u32 s8, s8, 0x10000
	s_addc_u32 s9, s9, 0
	global_load_dwordx4 v[112:115], v219, s[8:9] offset:0
	global_load_dwordx4 v[160:163], v219, s[8:9] offset:16
	s_waitcnt vmcnt(28)
	s_add_u32 s10, s10, 0x10000
	s_addc_u32 s11, s11, 0
	s_add_u32 s98, s98, 0x8000
	s_addc_u32 s99, s99, 0
	s_add_u32 s66, s66, 0x400
	s_addc_u32 s67, s67, 0
	v_pk_fma_f32 v[108:109], v[108:109], v[60:61], v[168:169]
	v_pk_fma_f32 v[110:111], v[110:111], v[62:63], v[170:171]
	v_pk_fma_f32 v[104:105], v[104:105], v[56:57], v[172:173]
	v_pk_fma_f32 v[106:107], v[106:107], v[58:59], v[174:175]
	global_store_dwordx4 v219, v[108:111], s[10:11] offset:0
	global_store_dwordx4 v219, v[104:107], s[10:11] offset:16
	v_mul_f32_e32 v198, v108, v108
	v_fmac_f32_e32 v198, v109, v109
	v_fmac_f32_e32 v198, v110, v110
	v_fmac_f32_e32 v198, v111, v111
	v_fmac_f32_e32 v198, v104, v104
	v_fmac_f32_e32 v198, v105, v105
	v_fmac_f32_e32 v198, v106, v106
	v_fmac_f32_e32 v198, v107, v107
	v_pk_mul_f32 v[168:169], v[144:145], v[108:109]
	v_pk_mul_f32 v[170:171], v[146:147], v[110:111]
	v_pk_mul_f32 v[172:173], v[148:149], v[104:105]
	v_pk_mul_f32 v[174:175], v[150:151], v[106:107]
	v_cvt_pk_bf16_f32 v168, v168, v169
	v_cvt_pk_bf16_f32 v169, v170, v171
	v_cvt_pk_bf16_f32 v170, v172, v173
	v_cvt_pk_bf16_f32 v171, v174, v175
	global_store_dwordx4 v220, v[168:171], s[98:99] offset:0
	global_load_dwordx4 v[172:175], v219, s[8:9] offset:512
	global_load_dwordx4 v[108:111], v219, s[8:9] offset:528
	s_add_u32 s8, s8, 0x10000
	s_addc_u32 s9, s9, 0
	global_load_dwordx4 v[104:107], v219, s[8:9] offset:0
	global_load_dwordx4 v[168:171], v219, s[8:9] offset:16
	s_waitcnt vmcnt(30)
	v_pk_fma_f32 v[100:101], v[100:101], v[44:45], v[180:181]
	v_pk_fma_f32 v[102:103], v[102:103], v[46:47], v[182:183]
	v_pk_fma_f32 v[96:97], v[96:97], v[40:41], v[140:141]
	v_pk_fma_f32 v[98:99], v[98:99], v[42:43], v[142:143]
	global_store_dwordx4 v219, v[100:103], s[10:11] offset:512
	global_store_dwordx4 v219, v[96:99], s[10:11] offset:528
	v_fmac_f32_e32 v198, v100, v100
	v_fmac_f32_e32 v198, v101, v101
	v_fmac_f32_e32 v198, v102, v102
	v_fmac_f32_e32 v198, v103, v103
	v_fmac_f32_e32 v198, v96, v96
	v_fmac_f32_e32 v198, v97, v97
	v_fmac_f32_e32 v198, v98, v98
	v_fmac_f32_e32 v198, v99, v99
	v_pk_mul_f32 v[180:181], v[152:153], v[100:101]
	v_pk_mul_f32 v[182:183], v[154:155], v[102:103]
	v_pk_mul_f32 v[140:141], v[156:157], v[96:97]
	v_pk_mul_f32 v[142:143], v[158:159], v[98:99]
	v_cvt_pk_bf16_f32 v180, v180, v181
	v_cvt_pk_bf16_f32 v181, v182, v183
	v_cvt_pk_bf16_f32 v182, v140, v141
	v_cvt_pk_bf16_f32 v183, v142, v143
	global_store_dwordx4 v220, v[180:183], s[98:99] offset:256
	v_mov_b32_e32 v240, v198
	s_nop 1
	v_permlane16_swap_b32_e32 v198, v240
	v_add_f32_e32 v240, v198, v240
	v_mov_b32_e32 v241, v240
	s_nop 1
	v_permlane32_swap_b32_e32 v240, v241
	v_add_f32_e32 v240, v240, v241
	v_cmp_eq_u32_e64 s[6:7], 2, v236
	s_nop 1
	v_cndmask_b32_e64 v233, v233, v240, s[6:7]
	global_load_dwordx4 v[140:143], v219, s[8:9] offset:512
	global_load_dwordx4 v[100:103], v219, s[8:9] offset:528
	s_waitcnt vmcnt(33)
	s_add_u32 s10, s10, 0x10000
	s_addc_u32 s11, s11, 0
	s_add_u32 s98, s98, 0x8000
	s_addc_u32 s99, s99, 0
	s_add_u32 s66, s66, 0x400
	s_addc_u32 s67, s67, 0
	v_pk_fma_f32 v[92:93], v[92:93], v[60:61], v[136:137]
	v_pk_fma_f32 v[94:95], v[94:95], v[62:63], v[138:139]
	v_pk_fma_f32 v[88:89], v[88:89], v[56:57], v[176:177]
	v_pk_fma_f32 v[90:91], v[90:91], v[58:59], v[178:179]
	global_store_dwordx4 v219, v[92:95], s[10:11] offset:0
	global_store_dwordx4 v219, v[88:91], s[10:11] offset:16
	v_mul_f32_e32 v198, v92, v92
	v_fmac_f32_e32 v198, v93, v93
	v_fmac_f32_e32 v198, v94, v94
	v_fmac_f32_e32 v198, v95, v95
	v_fmac_f32_e32 v198, v88, v88
	v_fmac_f32_e32 v198, v89, v89
	v_fmac_f32_e32 v198, v90, v90
	v_fmac_f32_e32 v198, v91, v91
	v_pk_mul_f32 v[136:137], v[144:145], v[92:93]
	v_pk_mul_f32 v[138:139], v[146:147], v[94:95]
	v_pk_mul_f32 v[176:177], v[148:149], v[88:89]
	v_pk_mul_f32 v[178:179], v[150:151], v[90:91]
	v_cvt_pk_bf16_f32 v136, v136, v137
	v_cvt_pk_bf16_f32 v137, v138, v139
	v_cvt_pk_bf16_f32 v138, v176, v177
	v_cvt_pk_bf16_f32 v139, v178, v179
	global_store_dwordx4 v220, v[136:139], s[98:99] offset:0
	s_waitcnt vmcnt(31)
	v_pk_fma_f32 v[84:85], v[84:85], v[44:45], v[228:229]
	v_pk_fma_f32 v[86:87], v[86:87], v[46:47], v[230:231]
	v_pk_fma_f32 v[80:81], v[80:81], v[40:41], v[132:133]
	v_pk_fma_f32 v[82:83], v[82:83], v[42:43], v[134:135]
	global_store_dwordx4 v219, v[84:87], s[10:11] offset:512
	global_store_dwordx4 v219, v[80:83], s[10:11] offset:528
	v_fmac_f32_e32 v198, v84, v84
	v_fmac_f32_e32 v198, v85, v85
	v_fmac_f32_e32 v198, v86, v86
	v_fmac_f32_e32 v198, v87, v87
	v_fmac_f32_e32 v198, v80, v80
	v_fmac_f32_e32 v198, v81, v81
	v_fmac_f32_e32 v198, v82, v82
	v_fmac_f32_e32 v198, v83, v83
	v_pk_mul_f32 v[228:229], v[152:153], v[84:85]
	v_pk_mul_f32 v[230:231], v[154:155], v[86:87]
	v_pk_mul_f32 v[132:133], v[156:157], v[80:81]
	v_pk_mul_f32 v[134:135], v[158:159], v[82:83]
	v_cvt_pk_bf16_f32 v228, v228, v229
	v_cvt_pk_bf16_f32 v229, v230, v231
	v_cvt_pk_bf16_f32 v230, v132, v133
	v_cvt_pk_bf16_f32 v231, v134, v135
	global_store_dwordx4 v220, v[228:231], s[98:99] offset:256
	v_mov_b32_e32 v240, v198
	s_nop 1
	v_permlane16_swap_b32_e32 v198, v240
	v_add_f32_e32 v240, v198, v240
	v_mov_b32_e32 v241, v240
	s_nop 1
	v_permlane32_swap_b32_e32 v240, v241
	v_add_f32_e32 v240, v240, v241
	v_cmp_eq_u32_e64 s[6:7], 3, v236
	s_nop 1
	v_cndmask_b32_e64 v233, v233, v240, s[6:7]
	global_store_dword v222, v233, s[66:67] offset:-3072
	s_waitcnt vmcnt(33)
	s_add_u32 s10, s10, 0x50000
	s_addc_u32 s11, s11, 0
	s_add_u32 s98, s98, 0x28000
	s_addc_u32 s99, s99, 0
	s_add_u32 s66, s66, 0x1400
	s_addc_u32 s67, s67, 0
	v_pk_fma_f32 v[76:77], v[76:77], v[60:61], v[128:129]
	v_pk_fma_f32 v[78:79], v[78:79], v[62:63], v[130:131]
	v_pk_fma_f32 v[72:73], v[72:73], v[56:57], v[224:225]
	v_pk_fma_f32 v[74:75], v[74:75], v[58:59], v[226:227]
	global_store_dwordx4 v219, v[76:79], s[10:11] offset:0
	global_store_dwordx4 v219, v[72:75], s[10:11] offset:16
	v_mul_f32_e32 v198, v76, v76
	v_fmac_f32_e32 v198, v77, v77
	v_fmac_f32_e32 v198, v78, v78
	v_fmac_f32_e32 v198, v79, v79
	v_fmac_f32_e32 v198, v72, v72
	v_fmac_f32_e32 v198, v73, v73
	v_fmac_f32_e32 v198, v74, v74
	v_fmac_f32_e32 v198, v75, v75
	v_pk_mul_f32 v[128:129], v[144:145], v[76:77]
	v_pk_mul_f32 v[130:131], v[146:147], v[78:79]
	v_pk_mul_f32 v[224:225], v[148:149], v[72:73]
	v_pk_mul_f32 v[226:227], v[150:151], v[74:75]
	v_cvt_pk_bf16_f32 v128, v128, v129
	v_cvt_pk_bf16_f32 v129, v130, v131
	v_cvt_pk_bf16_f32 v130, v224, v225
	v_cvt_pk_bf16_f32 v131, v226, v227
	global_store_dwordx4 v220, v[128:131], s[98:99] offset:0
	s_waitcnt vmcnt(31)
	v_pk_fma_f32 v[68:69], v[68:69], v[44:45], v[246:247]
	v_pk_fma_f32 v[70:71], v[70:71], v[46:47], v[248:249]
	v_pk_fma_f32 v[64:65], v[64:65], v[40:41], v[124:125]
	v_pk_fma_f32 v[66:67], v[66:67], v[42:43], v[126:127]
	global_store_dwordx4 v219, v[68:71], s[10:11] offset:512
	global_store_dwordx4 v219, v[64:67], s[10:11] offset:528
	v_fmac_f32_e32 v198, v68, v68
	v_fmac_f32_e32 v198, v69, v69
	v_fmac_f32_e32 v198, v70, v70
	v_fmac_f32_e32 v198, v71, v71
	v_fmac_f32_e32 v198, v64, v64
	v_fmac_f32_e32 v198, v65, v65
	v_fmac_f32_e32 v198, v66, v66
	v_fmac_f32_e32 v198, v67, v67
	v_pk_mul_f32 v[246:247], v[152:153], v[68:69]
	v_pk_mul_f32 v[248:249], v[154:155], v[70:71]
	v_pk_mul_f32 v[124:125], v[156:157], v[64:65]
	v_pk_mul_f32 v[126:127], v[158:159], v[66:67]
	v_cvt_pk_bf16_f32 v246, v246, v247
	v_cvt_pk_bf16_f32 v247, v248, v249
	v_cvt_pk_bf16_f32 v248, v124, v125
	v_cvt_pk_bf16_f32 v249, v126, v127
	global_store_dwordx4 v220, v[246:249], s[98:99] offset:256
	v_mov_b32_e32 v240, v198
	s_nop 1
	v_permlane16_swap_b32_e32 v198, v240
	v_add_f32_e32 v240, v198, v240
	v_mov_b32_e32 v241, v240
	s_nop 1
	v_permlane32_swap_b32_e32 v240, v241
	v_add_f32_e32 v240, v240, v241
	v_mov_b32_e32 v233, v240
	s_waitcnt vmcnt(32)
	s_add_u32 s10, s10, 0x10000
	s_addc_u32 s11, s11, 0
	s_add_u32 s98, s98, 0x8000
	s_addc_u32 s99, s99, 0
	s_add_u32 s66, s66, 0x400
	s_addc_u32 s67, s67, 0
	v_pk_fma_f32 v[52:53], v[52:53], v[60:61], v[120:121]
	v_pk_fma_f32 v[54:55], v[54:55], v[62:63], v[122:123]
	v_pk_fma_f32 v[48:49], v[48:49], v[56:57], v[242:243]
	v_pk_fma_f32 v[50:51], v[50:51], v[58:59], v[244:245]
	global_store_dwordx4 v219, v[52:55], s[10:11] offset:0
	global_store_dwordx4 v219, v[48:51], s[10:11] offset:16
	v_mul_f32_e32 v198, v52, v52
	v_fmac_f32_e32 v198, v53, v53
	v_fmac_f32_e32 v198, v54, v54
	v_fmac_f32_e32 v198, v55, v55
	v_fmac_f32_e32 v198, v48, v48
	v_fmac_f32_e32 v198, v49, v49
	v_fmac_f32_e32 v198, v50, v50
	v_fmac_f32_e32 v198, v51, v51
	v_pk_mul_f32 v[120:121], v[144:145], v[52:53]
	v_pk_mul_f32 v[122:123], v[146:147], v[54:55]
	v_pk_mul_f32 v[242:243], v[148:149], v[48:49]
	v_pk_mul_f32 v[244:245], v[150:151], v[50:51]
	v_cvt_pk_bf16_f32 v120, v120, v121
	v_cvt_pk_bf16_f32 v121, v122, v123
	v_cvt_pk_bf16_f32 v122, v242, v243
	v_cvt_pk_bf16_f32 v123, v244, v245
	global_store_dwordx4 v220, v[120:123], s[98:99] offset:0
	s_waitcnt vmcnt(30)
	v_pk_fma_f32 v[36:37], v[36:37], v[44:45], v[164:165]
	v_pk_fma_f32 v[38:39], v[38:39], v[46:47], v[166:167]
	v_pk_fma_f32 v[32:33], v[32:33], v[40:41], v[116:117]
	v_pk_fma_f32 v[34:35], v[34:35], v[42:43], v[118:119]
	global_store_dwordx4 v219, v[36:39], s[10:11] offset:512
	global_store_dwordx4 v219, v[32:35], s[10:11] offset:528
	v_fmac_f32_e32 v198, v36, v36
	v_fmac_f32_e32 v198, v37, v37
	v_fmac_f32_e32 v198, v38, v38
	v_fmac_f32_e32 v198, v39, v39
	v_fmac_f32_e32 v198, v32, v32
	v_fmac_f32_e32 v198, v33, v33
	v_fmac_f32_e32 v198, v34, v34
	v_fmac_f32_e32 v198, v35, v35
	v_pk_mul_f32 v[164:165], v[152:153], v[36:37]
	v_pk_mul_f32 v[166:167], v[154:155], v[38:39]
	v_pk_mul_f32 v[116:117], v[156:157], v[32:33]
	v_pk_mul_f32 v[118:119], v[158:159], v[34:35]
	v_cvt_pk_bf16_f32 v164, v164, v165
	v_cvt_pk_bf16_f32 v165, v166, v167
	v_cvt_pk_bf16_f32 v166, v116, v117
	v_cvt_pk_bf16_f32 v167, v118, v119
	global_store_dwordx4 v220, v[164:167], s[98:99] offset:256
	v_mov_b32_e32 v240, v198
	s_nop 1
	v_permlane16_swap_b32_e32 v198, v240
	v_add_f32_e32 v240, v198, v240
	v_mov_b32_e32 v241, v240
	s_nop 1
	v_permlane32_swap_b32_e32 v240, v241
	v_add_f32_e32 v240, v240, v241
	v_cmp_eq_u32_e64 s[6:7], 1, v236
	s_nop 1
	v_cndmask_b32_e64 v233, v233, v240, s[6:7]
	s_waitcnt vmcnt(31)
	s_add_u32 s10, s10, 0x10000
	s_addc_u32 s11, s11, 0
	s_add_u32 s98, s98, 0x8000
	s_addc_u32 s99, s99, 0
	s_add_u32 s66, s66, 0x400
	s_addc_u32 s67, s67, 0
	v_pk_fma_f32 v[28:29], v[28:29], v[60:61], v[112:113]
	v_pk_fma_f32 v[30:31], v[30:31], v[62:63], v[114:115]
	v_pk_fma_f32 v[24:25], v[24:25], v[56:57], v[160:161]
	v_pk_fma_f32 v[26:27], v[26:27], v[58:59], v[162:163]
	global_store_dwordx4 v219, v[28:31], s[10:11] offset:0
	global_store_dwordx4 v219, v[24:27], s[10:11] offset:16
	v_mul_f32_e32 v198, v28, v28
	v_fmac_f32_e32 v198, v29, v29
	v_fmac_f32_e32 v198, v30, v30
	v_fmac_f32_e32 v198, v31, v31
	v_fmac_f32_e32 v198, v24, v24
	v_fmac_f32_e32 v198, v25, v25
	v_fmac_f32_e32 v198, v26, v26
	v_fmac_f32_e32 v198, v27, v27
	v_pk_mul_f32 v[112:113], v[144:145], v[28:29]
	v_pk_mul_f32 v[114:115], v[146:147], v[30:31]
	v_pk_mul_f32 v[160:161], v[148:149], v[24:25]
	v_pk_mul_f32 v[162:163], v[150:151], v[26:27]
	v_cvt_pk_bf16_f32 v112, v112, v113
	v_cvt_pk_bf16_f32 v113, v114, v115
	v_cvt_pk_bf16_f32 v114, v160, v161
	v_cvt_pk_bf16_f32 v115, v162, v163
	global_store_dwordx4 v220, v[112:115], s[98:99] offset:0
	s_waitcnt vmcnt(29)
	v_pk_fma_f32 v[20:21], v[20:21], v[44:45], v[172:173]
	v_pk_fma_f32 v[22:23], v[22:23], v[46:47], v[174:175]
	v_pk_fma_f32 v[16:17], v[16:17], v[40:41], v[108:109]
	v_pk_fma_f32 v[18:19], v[18:19], v[42:43], v[110:111]
	global_store_dwordx4 v219, v[20:23], s[10:11] offset:512
	global_store_dwordx4 v219, v[16:19], s[10:11] offset:528
	v_fmac_f32_e32 v198, v20, v20
	v_fmac_f32_e32 v198, v21, v21
	v_fmac_f32_e32 v198, v22, v22
	v_fmac_f32_e32 v198, v23, v23
	v_fmac_f32_e32 v198, v16, v16
	v_fmac_f32_e32 v198, v17, v17
	v_fmac_f32_e32 v198, v18, v18
	v_fmac_f32_e32 v198, v19, v19
	v_pk_mul_f32 v[172:173], v[152:153], v[20:21]
	v_pk_mul_f32 v[174:175], v[154:155], v[22:23]
	v_pk_mul_f32 v[108:109], v[156:157], v[16:17]
	v_pk_mul_f32 v[110:111], v[158:159], v[18:19]
	v_cvt_pk_bf16_f32 v172, v172, v173
	v_cvt_pk_bf16_f32 v173, v174, v175
	v_cvt_pk_bf16_f32 v174, v108, v109
	v_cvt_pk_bf16_f32 v175, v110, v111
	global_store_dwordx4 v220, v[172:175], s[98:99] offset:256
	v_mov_b32_e32 v240, v198
	s_nop 1
	v_permlane16_swap_b32_e32 v198, v240
	v_add_f32_e32 v240, v198, v240
	v_mov_b32_e32 v241, v240
	s_nop 1
	v_permlane32_swap_b32_e32 v240, v241
	v_add_f32_e32 v240, v240, v241
	v_cmp_eq_u32_e64 s[6:7], 2, v236
	s_nop 1
	v_cndmask_b32_e64 v233, v233, v240, s[6:7]
	s_waitcnt vmcnt(30)
	s_add_u32 s10, s10, 0x10000
	s_addc_u32 s11, s11, 0
	s_add_u32 s98, s98, 0x8000
	s_addc_u32 s99, s99, 0
	s_add_u32 s66, s66, 0x400
	s_addc_u32 s67, s67, 0
	v_pk_fma_f32 v[12:13], v[12:13], v[60:61], v[104:105]
	v_pk_fma_f32 v[14:15], v[14:15], v[62:63], v[106:107]
	v_pk_fma_f32 v[8:9], v[8:9], v[56:57], v[168:169]
	v_pk_fma_f32 v[10:11], v[10:11], v[58:59], v[170:171]
	global_store_dwordx4 v219, v[12:15], s[10:11] offset:0
	global_store_dwordx4 v219, v[8:11], s[10:11] offset:16
	v_mul_f32_e32 v198, v12, v12
	v_fmac_f32_e32 v198, v13, v13
	v_fmac_f32_e32 v198, v14, v14
	v_fmac_f32_e32 v198, v15, v15
	v_fmac_f32_e32 v198, v8, v8
	v_fmac_f32_e32 v198, v9, v9
	v_fmac_f32_e32 v198, v10, v10
	v_fmac_f32_e32 v198, v11, v11
	v_pk_mul_f32 v[104:105], v[144:145], v[12:13]
	v_pk_mul_f32 v[106:107], v[146:147], v[14:15]
	v_pk_mul_f32 v[168:169], v[148:149], v[8:9]
	v_pk_mul_f32 v[170:171], v[150:151], v[10:11]
	v_cvt_pk_bf16_f32 v104, v104, v105
	v_cvt_pk_bf16_f32 v105, v106, v107
	v_cvt_pk_bf16_f32 v106, v168, v169
	v_cvt_pk_bf16_f32 v107, v170, v171
	global_store_dwordx4 v220, v[104:107], s[98:99] offset:0
	s_waitcnt vmcnt(28)
	v_pk_fma_f32 v[4:5], v[4:5], v[44:45], v[140:141]
	v_pk_fma_f32 v[6:7], v[6:7], v[46:47], v[142:143]
	v_pk_fma_f32 v[0:1], v[0:1], v[40:41], v[100:101]
	v_pk_fma_f32 v[2:3], v[2:3], v[42:43], v[102:103]
	global_store_dwordx4 v219, v[4:7], s[10:11] offset:512
	global_store_dwordx4 v219, v[0:3], s[10:11] offset:528
	v_fmac_f32_e32 v198, v4, v4
	v_fmac_f32_e32 v198, v5, v5
	v_fmac_f32_e32 v198, v6, v6
	v_fmac_f32_e32 v198, v7, v7
	v_fmac_f32_e32 v198, v0, v0
	v_fmac_f32_e32 v198, v1, v1
	v_fmac_f32_e32 v198, v2, v2
	v_fmac_f32_e32 v198, v3, v3
	v_pk_mul_f32 v[140:141], v[152:153], v[4:5]
	v_pk_mul_f32 v[142:143], v[154:155], v[6:7]
	v_pk_mul_f32 v[100:101], v[156:157], v[0:1]
	v_pk_mul_f32 v[102:103], v[158:159], v[2:3]
	v_cvt_pk_bf16_f32 v140, v140, v141
	v_cvt_pk_bf16_f32 v141, v142, v143
	v_cvt_pk_bf16_f32 v142, v100, v101
	v_cvt_pk_bf16_f32 v143, v102, v103
	global_store_dwordx4 v220, v[140:143], s[98:99] offset:256
	v_mov_b32_e32 v240, v198
	s_nop 1
	v_permlane16_swap_b32_e32 v198, v240
	v_add_f32_e32 v240, v198, v240
	v_mov_b32_e32 v241, v240
	s_nop 1
	v_permlane32_swap_b32_e32 v240, v241
	v_add_f32_e32 v240, v240, v241
	v_cmp_eq_u32_e64 s[6:7], 3, v236
	s_nop 1
	v_cndmask_b32_e64 v233, v233, v240, s[6:7]
	global_store_dword v222, v233, s[66:67] offset:-3072
.Lepo_done:
	s_andn2_b64 vcc, exec, s[4:5]
	s_mov_b64 s[4:5], -1
	s_cbranch_vccnz .LBB0_954
	s_andn2_b64 vcc, exec, s[22:23]
	s_cbranch_vccnz .LBB0_953
	s_barrier
	s_branch .LBB0_953

	.amdhsa_kernel _Z4mega6Params
		.amdhsa_group_segment_fixed_size 0
		.amdhsa_private_segment_fixed_size 0
		.amdhsa_kernarg_size 528
		.amdhsa_user_sgpr_count 2
		.amdhsa_user_sgpr_dispatch_ptr 0
		.amdhsa_user_sgpr_queue_ptr 0
		.amdhsa_user_sgpr_kernarg_segment_ptr 1
		.amdhsa_user_sgpr_dispatch_id 0
		.amdhsa_user_sgpr_kernarg_preload_length 0
		.amdhsa_user_sgpr_kernarg_preload_offset 0
		.amdhsa_user_sgpr_private_segment_size 0
		.amdhsa_uses_dynamic_stack 0
		.amdhsa_enable_private_segment 0
		.amdhsa_system_sgpr_workgroup_id_x 1
		.amdhsa_system_sgpr_workgroup_id_y 0
		.amdhsa_system_sgpr_workgroup_id_z 0
		.amdhsa_system_sgpr_workgroup_info 0
		.amdhsa_system_vgpr_workitem_id 2
		.amdhsa_next_free_vgpr 255
		.amdhsa_next_free_sgpr 102
		.amdhsa_accum_offset 256
		.amdhsa_reserve_vcc 1
		.amdhsa_float_round_mode_32 0
		.amdhsa_float_round_mode_16_64 0
		.amdhsa_float_denorm_mode_32 3
		.amdhsa_float_denorm_mode_16_64 3
		.amdhsa_dx10_clamp 1
		.amdhsa_ieee_mode 1
		.amdhsa_fp16_overflow 0
		.amdhsa_tg_split 0
		.amdhsa_exception_fp_ieee_invalid_op 0
		.amdhsa_exception_fp_denorm_src 0
		.amdhsa_exception_fp_ieee_div_zero 0
		.amdhsa_exception_fp_ieee_overflow 0
		.amdhsa_exception_fp_ieee_underflow 0
		.amdhsa_exception_fp_ieee_inexact 0
		.amdhsa_exception_int_div_zero 0
	.end_amdhsa_kernel

amdhsa.kernels:
  - .agpr_count:     0
    .args:
      - .offset:         0
        .size:           272
        .value_kind:     by_value
      - .offset:         272
        .size:           4
        .value_kind:     hidden_block_count_x
      - .offset:         276
        .size:           4
        .value_kind:     hidden_block_count_y
      - .offset:         280
        .size:           4
        .value_kind:     hidden_block_count_z
      - .offset:         284
        .size:           2
        .value_kind:     hidden_group_size_x
      - .offset:         286
        .size:           2
        .value_kind:     hidden_group_size_y
      - .offset:         288
        .size:           2
        .value_kind:     hidden_group_size_z
      - .offset:         290
        .size:           2
        .value_kind:     hidden_remainder_x
      - .offset:         292
        .size:           2
        .value_kind:     hidden_remainder_y
      - .offset:         294
        .size:           2
        .value_kind:     hidden_remainder_z
      - .offset:         312
        .size:           8
        .value_kind:     hidden_global_offset_x
      - .offset:         320
        .size:           8
        .value_kind:     hidden_global_offset_y
      - .offset:         328
        .size:           8
        .value_kind:     hidden_global_offset_z
      - .offset:         336
        .size:           2
        .value_kind:     hidden_grid_dims
      - .offset:         360
        .size:           8
        .value_kind:     hidden_multigrid_sync_arg
      - .offset:         392
        .size:           4
        .value_kind:     hidden_dynamic_lds_size
    .group_segment_fixed_size: 0
    .kernarg_segment_align: 8
    .kernarg_segment_size: 528
    .language:       OpenCL C
    .language_version:
      - 2
      - 0
    .max_flat_workgroup_size: 512
    .name:           _Z4mega6Params
    .private_segment_fixed_size: 0
    .sgpr_count:     108
    .sgpr_spill_count: 8
    .symbol:         _Z4mega6Params.kd
    .uniform_work_group_size: 1
    .uses_dynamic_stack: false
    .vgpr_count:     255
    .vgpr_spill_count: 0
    .wavefront_size: 64
